# cache policy: nt hint removed from the rowops' bf16 abuf stores (next GEMM reads them back)
# speedup vs baseline: 1.0090x; 1.0090x over previous
.LBB0_28:
	s_movk_i32 s0, 0x4000
	v_cmp_gt_i32_e32 vcc, s0, v104
	s_or_b64 s[0:1], s[6:7], vcc
	s_and_saveexec_b64 s[8:9], s[0:1]
	s_cbranch_execz .LBB0_27
	s_movk_i32 s0, 0x4000
	v_cmp_gt_i32_e32 vcc, s0, v104
	v_min_i32_e32 v0, 0x4000, v104
	v_ashrrev_i32_e32 v1, 31, v104
	v_readlane_b32 s0, v253, 42
	v_ashrrev_i32_e32 v172, 13, v0
	v_add_u32_e32 v0, 0xffffc000, v104
	v_cndmask_b32_e32 v105, 0, v1, vcc
	v_mov_b32_e32 v2, s0
	v_mov_b32_e32 v3, s89
	v_readlane_b32 s0, v255, 17
	v_cndmask_b32_e32 v0, v0, v104, vcc
	v_mov_b32_e32 v1, v105
	v_cndmask_b32_e32 v3, v2, v3, vcc
	v_mov_b32_e32 v2, s0
	v_mov_b32_e32 v4, s88
	v_cndmask_b32_e32 v2, v2, v4, vcc
	v_lshlrev_b64 v[0:1], 12, v[0:1]
	v_lshl_add_u64 v[120:121], v[2:3], 0, v[0:1]
	v_add_u32_e32 v0, s10, v172
	v_mul_hi_i32_i24_e32 v33, 0x6000, v0
	v_mul_i32_i24_e32 v32, 0x6000, v0
	v_lshl_add_u64 v[0:1], v[120:121], 0, v[192:193]
	s_movk_i32 s12, 0x1000
	v_add_co_u32_e32 v2, vcc, s12, v0
	s_movk_i32 s13, 0x2000
	s_nop 0
	v_addc_co_u32_e32 v3, vcc, 0, v1, vcc
	v_add_co_u32_e32 v4, vcc, s13, v0
	global_load_dwordx4 v[92:95], v[0:1], off nt
	global_load_dwordx4 v[88:91], v[0:1], off offset:1024 nt
	global_load_dwordx4 v[84:87], v[0:1], off offset:2048 nt
	global_load_dwordx4 v[80:83], v[0:1], off offset:3072 nt
	v_addc_co_u32_e32 v5, vcc, 0, v1, vcc
	v_add_co_u32_e32 v0, vcc, s73, v0
	global_load_dwordx4 v[76:79], v[4:5], off offset:-4096 nt
	global_load_dwordx4 v[72:75], v[2:3], off offset:1024 nt
	global_load_dwordx4 v[68:71], v[2:3], off offset:2048 nt
	global_load_dwordx4 v[64:67], v[2:3], off offset:3072 nt
	global_load_dwordx4 v[28:31], v[4:5], off nt
	global_load_dwordx4 v[24:27], v[4:5], off offset:1024 nt
	global_load_dwordx4 v[20:23], v[4:5], off offset:2048 nt
	global_load_dwordx4 v[16:19], v[4:5], off offset:3072 nt
	v_addc_co_u32_e32 v1, vcc, 0, v1, vcc
	global_load_dwordx4 v[12:15], v[0:1], off nt
	global_load_dwordx4 v[8:11], v[0:1], off offset:1024 nt
	global_load_dwordx4 v[4:7], v[0:1], off offset:2048 nt
	s_nop 0
	global_load_dwordx4 v[0:3], v[0:1], off offset:3072 nt
	v_add_u32_e32 v34, 1, v104
	v_ashrrev_i32_e32 v35, 31, v34
	v_lshlrev_b64 v[116:117], 11, v[34:35]
	v_add_u32_e32 v34, 2, v104
	v_ashrrev_i32_e32 v35, 31, v34
	v_lshlrev_b64 v[114:115], 11, v[34:35]
	v_add_u32_e32 v34, 3, v104
	v_ashrrev_i32_e32 v35, 31, v34
	v_cmp_lt_i32_e32 vcc, v211, v210
	v_lshlrev_b64 v[112:113], 11, v[34:35]
	v_lshl_add_u64 v[32:33], s[90:91], 0, v[32:33]
	v_cndmask_b32_e32 v34, v209, v211, vcc
	v_cmp_lt_i32_e32 vcc, v212, v210
	v_lshlrev_b32_e32 v107, 2, v34
	v_lshl_add_u64 v[36:37], v[32:33], 0, v[192:193]
	v_cndmask_b32_e32 v34, v209, v212, vcc
	v_cmp_lt_i32_e32 vcc, v206, v210
	v_lshlrev_b32_e32 v109, 2, v34
	s_mov_b64 s[0:1], 0x345d000
	v_cndmask_b32_e32 v34, v209, v206, vcc
	v_cmp_lt_i32_e32 vcc, v213, v210
	v_lshlrev_b32_e32 v111, 2, v34
	v_lshl_add_u64 v[62:63], v[36:37], 0, s[0:1]
	v_cndmask_b32_e32 v34, v209, v213, vcc
	v_cmp_lt_i32_e32 vcc, v216, v210
	v_lshlrev_b32_e32 v169, 2, v34
	s_mov_b32 s0, 0x345d000
	v_cndmask_b32_e32 v34, v209, v216, vcc
	v_cmp_lt_i32_e32 vcc, v217, v210
	v_lshlrev_b32_e32 v170, 2, v34
	v_lshlrev_b64 v[118:119], 11, v[104:105]
	v_cndmask_b32_e32 v34, v209, v217, vcc
	v_add_co_u32_e32 v36, vcc, s0, v36
	v_lshl_add_u64 v[60:61], v[96:97], 0, v[118:119]
	s_nop 0
	v_addc_co_u32_e32 v37, vcc, 0, v37, vcc
	v_lshlrev_b32_e32 v171, 2, v34
	global_load_dwordx4 v[32:35], v[98:99], off
	v_lshl_add_u64 v[140:141], v[96:97], 0, v[116:117]
	global_load_dwordx4 v[36:39], v[36:37], off
	s_nop 0
	global_load_dwordx4 v[40:43], v[98:99], off offset:1024
	global_load_dwordx4 v[44:47], v[62:63], off offset:1024
	global_load_dwordx4 v[48:51], v[98:99], off offset:2048
	global_load_dwordx4 v[52:55], v[62:63], off offset:2048
	s_mov_b32 s0, 0x358637bd
	s_mov_b32 s16, 0x3a800000
	s_mov_b32 s14, 0x800000
	v_lshl_add_u64 v[134:135], v[96:97], 0, v[114:115]
	v_lshl_add_u64 v[124:125], v[96:97], 0, v[112:113]
	s_waitcnt vmcnt(21)
	v_mov_b32_e32 v138, v92
	s_waitcnt vmcnt(17)
	v_mov_b32_e32 v136, v76
	s_waitcnt vmcnt(16)
	v_mov_b32_e32 v142, v72
	v_mov_b32_e32 v143, v74
	v_mov_b32_e32 v74, v73
	v_mov_b32_e32 v137, v78
	s_waitcnt vmcnt(12)
	v_mov_b32_e32 v72, v24
	v_mov_b32_e32 v73, v26
	v_mov_b32_e32 v26, v25
	v_mov_b32_e32 v24, v68
	v_mov_b32_e32 v25, v70
	v_mov_b32_e32 v70, v69
	s_waitcnt vmcnt(7)
	v_mov_b32_e32 v68, v4
	v_mov_b32_e32 v69, v6
	v_mov_b32_e32 v6, v5
	global_load_dwordx4 v[56:59], v[98:99], off offset:3072
	global_load_dwordx2 v[4:5], v[60:61], off offset:1536 nt
	global_load_dwordx2 v[180:181], v[60:61], off offset:1024 nt
	global_load_dwordx2 v[182:183], v[60:61], off offset:512 nt
	global_load_dwordx2 v[184:185], v[60:61], off nt
	global_load_dwordx2 v[186:187], v[140:141], off offset:1536 nt
	global_load_dwordx2 v[188:189], v[140:141], off offset:1024 nt
	global_load_dwordx2 v[190:191], v[140:141], off offset:512 nt
	global_load_dwordx2 v[224:225], v[140:141], off nt
	global_load_dwordx2 v[232:233], v[134:135], off offset:1536 nt
	global_load_dwordx2 v[234:235], v[134:135], off offset:1024 nt
	global_load_dwordx2 v[236:237], v[134:135], off offset:512 nt
	global_load_dwordx2 v[238:239], v[134:135], off nt
	global_load_dwordx2 v[240:241], v[124:125], off offset:1536 nt
	global_load_dwordx2 v[242:243], v[124:125], off offset:1024 nt
	global_load_dwordx2 v[248:249], v[124:125], off offset:512 nt
	global_load_dwordx2 v[250:251], v[124:125], off nt
	v_mov_b32_e32 v78, v77
	v_mov_b32_e32 v144, v84
	v_mov_b32_e32 v145, v86
	v_mov_b32_e32 v86, v85
	v_mov_b32_e32 v84, v20
	v_mov_b32_e32 v85, v22
	v_mov_b32_e32 v22, v21
	v_mov_b32_e32 v139, v94
	v_mov_b32_e32 v94, v93
	s_waitcnt vmcnt(22)
	v_mov_b32_e32 v130, v32
	v_mov_b32_e32 v131, v34
	s_waitcnt vmcnt(21)
	v_mov_b32_e32 v122, v36
	s_waitcnt vmcnt(19)
	v_mov_b32_e32 v76, v44
	v_mov_b32_e32 v77, v46
	v_mov_b32_e32 v46, v45
	v_mov_b32_e32 v44, v8
	v_mov_b32_e32 v45, v10
	v_mov_b32_e32 v10, v9
	s_waitcnt vmcnt(17)
	v_mov_b32_e32 v8, v52
	v_mov_b32_e32 v9, v54
	v_mov_b32_e32 v54, v53
	v_mov_b32_e32 v123, v38
	v_mov_b32_e32 v38, v37
	v_mov_b32_e32 v36, v28
	v_mov_b32_e32 v37, v30
	v_mov_b32_e32 v30, v29
	v_mov_b32_e32 v28, v12
	v_mov_b32_e32 v29, v14
	v_mov_b32_e32 v14, v13
	v_mov_b32_e32 v12, v88
	v_mov_b32_e32 v13, v90
	v_mov_b32_e32 v90, v89
	v_mov_b32_e32 v34, v33
	v_mov_b32_e32 v32, v80
	v_mov_b32_e32 v33, v82
	v_mov_b32_e32 v82, v81
	s_waitcnt vmcnt(15)
	v_and_b32_e32 v21, 0xffff0000, v5
	v_and_b32_e32 v20, 0xffff0000, v4
	v_lshlrev_b32_e32 v52, 16, v4
	v_lshlrev_b32_e32 v53, 16, v5
	v_mov_b32_e32 v93, v52
	v_mov_b32_e32 v127, v53
	v_mov_b32_e32 v89, v21
	s_waitcnt vmcnt(14)
	v_mov_b32_e32 v4, v180
	v_mov_b32_e32 v5, v181
	v_and_b32_e32 v146, 0xffff0000, v4
	v_and_b32_e32 v147, 0xffff0000, v5
	v_lshlrev_b32_e32 v148, 16, v4
	v_lshlrev_b32_e32 v149, 16, v5
	v_mov_b32_e32 v4, v146
	v_mov_b32_e32 v5, v20
	v_pk_mul_f32 v[4:5], v[4:5], v[4:5]
	v_mov_b32_e32 v92, v148
	v_mov_b32_e32 v126, v149
	v_pk_fma_f32 v[4:5], v[92:93], v[92:93], v[4:5]
	v_mov_b32_e32 v88, v147
	v_pk_fma_f32 v[4:5], v[126:127], v[126:127], v[4:5]
	s_nop 0
	v_pk_fma_f32 v[88:89], v[88:89], v[88:89], v[4:5]
	s_waitcnt vmcnt(13)
	v_mov_b32_e32 v4, v182
	v_mov_b32_e32 v5, v183
	v_and_b32_e32 v151, 0xffff0000, v5
	v_and_b32_e32 v150, 0xffff0000, v4
	v_lshlrev_b32_e32 v152, 16, v4
	v_lshlrev_b32_e32 v153, 16, v5
	v_mov_b32_e32 v127, v152
	v_mov_b32_e32 v129, v153
	v_mov_b32_e32 v61, v151
	s_waitcnt vmcnt(12)
	v_mov_b32_e32 v4, v184
	v_mov_b32_e32 v5, v185
	v_and_b32_e32 v92, 0xffff0000, v4
	v_and_b32_e32 v93, 0xffff0000, v5
	v_lshlrev_b32_e32 v154, 16, v4
	v_lshlrev_b32_e32 v155, 16, v5
	v_mov_b32_e32 v4, v92
	v_mov_b32_e32 v5, v150
	v_pk_mul_f32 v[4:5], v[4:5], v[4:5]
	v_mov_b32_e32 v126, v154
	v_mov_b32_e32 v128, v155
	v_pk_fma_f32 v[4:5], v[126:127], v[126:127], v[4:5]
	v_mov_b32_e32 v60, v93
	v_pk_fma_f32 v[4:5], v[128:129], v[128:129], v[4:5]
	v_mov_b32_e32 v128, v40
	v_mov_b32_e32 v129, v42
	v_mov_b32_e32 v42, v41
	v_pk_fma_f32 v[156:157], v[60:61], v[60:61], v[4:5]
	global_load_dwordx4 v[60:63], v[62:63], off offset:3072
	v_mov_b32_e32 v126, v48
	v_mov_b32_e32 v127, v50
	v_mov_b32_e32 v50, v49
	v_mov_b32_e32 v4, v56
	v_mov_b32_e32 v5, v58
	v_mov_b32_e32 v58, v57
	s_waitcnt vmcnt(12)
	v_mov_b32_e32 v40, v186
	v_mov_b32_e32 v41, v187
	v_and_b32_e32 v159, 0xffff0000, v41
	v_and_b32_e32 v158, 0xffff0000, v40
	v_lshlrev_b32_e32 v160, 16, v40
	v_lshlrev_b32_e32 v161, 16, v41
	s_waitcnt vmcnt(0)
	v_mov_b32_e32 v132, v60
	v_mov_b32_e32 v133, v62
	v_mov_b32_e32 v62, v61
	v_mov_b32_e32 v61, v160
	v_mov_b32_e32 v81, v161
	v_mov_b32_e32 v57, v159
	s_waitcnt vmcnt(0)
	v_mov_b32_e32 v40, v188
	v_mov_b32_e32 v41, v189
	v_and_b32_e32 v48, 0xffff0000, v40
	v_and_b32_e32 v49, 0xffff0000, v41
	v_lshlrev_b32_e32 v162, 16, v40
	v_lshlrev_b32_e32 v163, 16, v41
	v_mov_b32_e32 v40, v48
	v_mov_b32_e32 v41, v158
	v_pk_mul_f32 v[40:41], v[40:41], v[40:41]
	v_mov_b32_e32 v60, v162
	v_mov_b32_e32 v80, v163
	v_pk_fma_f32 v[40:41], v[60:61], v[60:61], v[40:41]
	v_mov_b32_e32 v56, v49
	v_pk_fma_f32 v[40:41], v[80:81], v[80:81], v[40:41]
	s_nop 0
	v_pk_fma_f32 v[40:41], v[56:57], v[56:57], v[40:41]
	s_waitcnt vmcnt(0)
	v_mov_b32_e32 v56, v190
	v_mov_b32_e32 v57, v191
	v_and_b32_e32 v165, 0xffff0000, v57
	v_and_b32_e32 v164, 0xffff0000, v56
	v_lshlrev_b32_e32 v166, 16, v56
	v_lshlrev_b32_e32 v167, 16, v57
	v_mov_b32_e32 v81, v166
	v_mov_b32_e32 v141, v167
	v_mov_b32_e32 v61, v165
	s_waitcnt vmcnt(0)
	v_mov_b32_e32 v56, v224
	v_mov_b32_e32 v57, v225
	v_and_b32_e32 v174, 0xffff0000, v56
	v_and_b32_e32 v175, 0xffff0000, v57
	v_lshlrev_b32_e32 v176, 16, v56
	v_lshlrev_b32_e32 v177, 16, v57
	v_mov_b32_e32 v56, v174
	v_mov_b32_e32 v57, v164
	v_pk_mul_f32 v[56:57], v[56:57], v[56:57]
	v_mov_b32_e32 v80, v176
	v_mov_b32_e32 v140, v177
	v_pk_fma_f32 v[56:57], v[80:81], v[80:81], v[56:57]
	v_mov_b32_e32 v60, v175
	v_pk_fma_f32 v[56:57], v[140:141], v[140:141], v[56:57]
	v_mov_b64_e32 v[140:141], s[0:1]
	v_pk_fma_f32 v[56:57], v[60:61], v[60:61], v[56:57]
	v_mov_b32_e32 v61, v156
	v_mov_b32_e32 v60, v56
	v_mov_b32_e32 v156, v57
	v_pk_add_f32 v[56:57], v[60:61], v[156:157]
	v_mov_b32_e32 v60, v40
	v_mov_b32_e32 v61, v88
	v_pk_add_f32 v[56:57], v[56:57], v[60:61]
	v_mov_b32_e32 v88, v41
	v_pk_add_f32 v[40:41], v[56:57], v[88:89]
	s_nop 0
	s_nop 1
	v_add_f32_dpp v41, v41, v41 quad_perm:[1,0,3,2] row_mask:0xf bank_mask:0xf
	v_add_f32_dpp v40, v40, v40 quad_perm:[1,0,3,2] row_mask:0xf bank_mask:0xf
	s_nop 0
	v_add_f32_dpp v41, v41, v41 quad_perm:[2,3,0,1] row_mask:0xf bank_mask:0xf
	v_add_f32_dpp v40, v40, v40 quad_perm:[2,3,0,1] row_mask:0xf bank_mask:0xf
	s_nop 0
	v_add_f32_dpp v41, v41, v41 row_half_mirror row_mask:0xf bank_mask:0xf
	v_add_f32_dpp v40, v40, v40 row_half_mirror row_mask:0xf bank_mask:0xf
	s_nop 0
	v_add_f32_dpp v41, v41, v41 row_mirror row_mask:0xf bank_mask:0xf
	v_add_f32_dpp v40, v40, v40 row_mirror row_mask:0xf bank_mask:0xf
	s_nop 0
	v_mov_b32_e32 v57, v41
	v_mov_b32_e32 v56, v40
	s_nop 0
	v_permlane16_swap_b32_e32 v41, v57
	v_permlane16_swap_b32_e32 v40, v56
	s_nop 0
	v_add_f32_e32 v41, v41, v57
	v_add_f32_e32 v40, v40, v56
	s_nop 0
	v_mov_b32_e32 v57, v41
	v_mov_b32_e32 v56, v40
	s_nop 0
	v_permlane32_swap_b32_e32 v41, v57
	v_permlane32_swap_b32_e32 v40, v56
	s_nop 0
	v_add_f32_e32 v41, v41, v57
	v_add_f32_e32 v40, v40, v56
	s_nop 0
	s_nop 0
	v_pk_fma_f32 v[156:157], v[40:41], s[16:17], v[140:141] op_sel_hi:[1,0,0]
	s_nop 0
	v_mul_f32_e32 v40, 0x4b800000, v157
	v_cmp_gt_f32_e64 s[0:1], s14, v157
	v_cmp_gt_f32_e32 vcc, s14, v156
	s_nop 0
	v_cndmask_b32_e64 v40, v157, v40, s[0:1]
	v_rsq_f32_e32 v40, v40
	s_nop 0
	v_mul_f32_e32 v41, 0x45800000, v40
	v_cndmask_b32_e64 v178, v40, v41, s[0:1]
	v_pk_mul_f32 v[40:41], v[178:179], v[154:155] op_sel_hi:[0,1]
	v_pk_mul_f32 v[40:41], v[40:41], v[130:131]
	v_pk_mul_f32 v[56:57], v[178:179], v[92:93] op_sel_hi:[0,1]
	v_pk_fma_f32 v[92:93], v[40:41], v[122:123], v[138:139]
	v_pk_mul_f32 v[40:41], v[178:179], v[152:153] op_sel_hi:[0,1]
	v_pk_mul_f32 v[56:57], v[56:57], v[34:35]
	v_pk_mul_f32 v[40:41], v[40:41], v[128:129]
	v_pk_fma_f32 v[88:89], v[56:57], v[38:39], v[94:95]
	v_pk_mul_f32 v[56:57], v[178:179], v[150:151] op_sel_hi:[0,1]
	v_pk_fma_f32 v[80:81], v[40:41], v[76:77], v[12:13]
	v_pk_mul_f32 v[12:13], v[178:179], v[148:149] op_sel_hi:[0,1]
	v_pk_mul_f32 v[56:57], v[56:57], v[42:43]
	v_pk_mul_f32 v[12:13], v[12:13], v[126:127]
	v_pk_fma_f32 v[60:61], v[56:57], v[46:47], v[90:91]
	v_pk_fma_f32 v[56:57], v[12:13], v[8:9], v[144:145]
	v_pk_mul_f32 v[12:13], v[178:179], v[52:53] op_sel_hi:[0,1]
	v_pk_mul_f32 v[20:21], v[178:179], v[20:21] op_sel_hi:[0,1]
	v_pk_mul_f32 v[12:13], v[12:13], v[4:5]
	v_pk_mul_f32 v[20:21], v[20:21], v[58:59]
	v_pk_fma_f32 v[32:33], v[12:13], v[132:133], v[32:33]
	v_pk_fma_f32 v[12:13], v[20:21], v[62:63], v[82:83]
	v_mul_f32_e32 v20, 0x4b800000, v156
	v_cndmask_b32_e32 v20, v156, v20, vcc
	v_rsq_f32_e32 v20, v20
	v_pk_mul_f32 v[40:41], v[178:179], v[146:147] op_sel_hi:[0,1]
	v_pk_mul_f32 v[40:41], v[40:41], v[50:51]
	v_mul_f32_e32 v21, 0x45800000, v20
	v_cndmask_b32_e32 v20, v20, v21, vcc
	v_pk_mul_f32 v[48:49], v[20:21], v[48:49] op_sel_hi:[0,1]
	v_pk_mul_f32 v[48:49], v[48:49], v[50:51]
	v_pk_mul_f32 v[82:83], v[20:21], v[174:175] op_sel_hi:[0,1]
	v_pk_fma_f32 v[48:49], v[48:49], v[54:55], v[70:71]
	v_mov_b32_e32 v70, v64
	v_mov_b32_e32 v71, v66
	v_mov_b32_e32 v66, v65
	v_pk_mul_f32 v[82:83], v[82:83], v[34:35]
	v_pk_mul_f32 v[52:53], v[20:21], v[176:177] op_sel_hi:[0,1]
	v_pk_fma_f32 v[82:83], v[82:83], v[38:39], v[78:79]
	v_pk_mul_f32 v[78:79], v[20:21], v[164:165] op_sel_hi:[0,1]
	v_pk_mul_f32 v[90:91], v[78:79], v[42:43]
	v_pk_mul_f32 v[52:53], v[52:53], v[130:131]
	v_pk_fma_f32 v[74:75], v[90:91], v[46:47], v[74:75]
	v_pk_fma_f32 v[40:41], v[40:41], v[54:55], v[86:87]
	v_pk_fma_f32 v[86:87], v[52:53], v[122:123], v[136:137]
	v_pk_mul_f32 v[52:53], v[20:21], v[166:167] op_sel_hi:[0,1]
	v_pk_mul_f32 v[52:53], v[52:53], v[128:129]
	s_waitcnt vmcnt(0)
	v_mov_b32_e32 v64, v232
	v_mov_b32_e32 v65, v233
	v_and_b32_e32 v91, 0xffff0000, v65
	v_and_b32_e32 v90, 0xffff0000, v64
	v_lshlrev_b32_e32 v94, 16, v64
	v_lshlrev_b32_e32 v95, 16, v65
	v_pk_fma_f32 v[78:79], v[52:53], v[76:77], v[142:143]
	v_pk_mul_f32 v[52:53], v[20:21], v[162:163] op_sel_hi:[0,1]
	v_pk_mul_f32 v[52:53], v[52:53], v[126:127]
	v_mov_b32_e32 v143, v95
	v_pk_fma_f32 v[52:53], v[52:53], v[8:9], v[24:25]
	v_pk_mul_f32 v[24:25], v[20:21], v[160:161] op_sel_hi:[0,1]
	v_pk_mul_f32 v[24:25], v[24:25], v[4:5]
	v_pk_mul_f32 v[20:21], v[20:21], v[158:159] op_sel_hi:[0,1]
	v_pk_fma_f32 v[24:25], v[24:25], v[132:133], v[70:71]
	v_mov_b32_e32 v71, v94
	v_pk_mul_f32 v[20:21], v[20:21], v[58:59]
	s_waitcnt vmcnt(0)
	v_mov_b32_e32 v64, v234
	v_mov_b32_e32 v65, v235
	v_and_b32_e32 v136, 0xffff0000, v64
	v_and_b32_e32 v137, 0xffff0000, v65
	v_lshlrev_b32_e32 v138, 16, v64
	v_lshlrev_b32_e32 v139, 16, v65
	v_mov_b32_e32 v64, v136
	v_mov_b32_e32 v65, v90
	v_pk_mul_f32 v[64:65], v[64:65], v[64:65]
	v_mov_b32_e32 v70, v138
	v_pk_fma_f32 v[64:65], v[70:71], v[70:71], v[64:65]
	v_mov_b32_e32 v142, v139
	v_pk_fma_f32 v[20:21], v[20:21], v[62:63], v[66:67]
	v_mov_b32_e32 v66, v137
	v_mov_b32_e32 v67, v91
	v_pk_fma_f32 v[64:65], v[142:143], v[142:143], v[64:65]
	s_waitcnt vmcnt(0)
	v_mov_b32_e32 v70, v236
	v_mov_b32_e32 v71, v237
	v_lshlrev_b32_e32 v142, 16, v70
	v_pk_fma_f32 v[66:67], v[66:67], v[66:67], v[64:65]
	v_and_b32_e32 v64, 0xffff0000, v70
	s_waitcnt vmcnt(0)
	v_mov_b32_e32 v134, v238
	v_mov_b32_e32 v135, v239
	v_and_b32_e32 v70, 0xffff0000, v134
	v_and_b32_e32 v65, 0xffff0000, v71
	v_lshlrev_b32_e32 v143, 16, v71
	v_and_b32_e32 v71, 0xffff0000, v135
	v_lshlrev_b32_e32 v144, 16, v134
	v_lshlrev_b32_e32 v145, 16, v135
	v_mov_b32_e32 v134, v70
	v_mov_b32_e32 v135, v64
	v_pk_mul_f32 v[134:135], v[134:135], v[134:135]
	v_mov_b32_e32 v148, v144
	v_mov_b32_e32 v149, v142
	v_mov_b32_e32 v150, v145
	v_mov_b32_e32 v151, v143
	v_pk_fma_f32 v[134:135], v[148:149], v[148:149], v[134:135]
	v_mov_b32_e32 v146, v71
	v_mov_b32_e32 v147, v65
	v_pk_fma_f32 v[134:135], v[150:151], v[150:151], v[134:135]
	s_nop 0
	v_pk_fma_f32 v[154:155], v[146:147], v[146:147], v[134:135]
	v_mov_b32_e32 v134, v16
	v_mov_b32_e32 v135, v18
	v_mov_b32_e32 v18, v17
	s_waitcnt vmcnt(0)
	v_mov_b32_e32 v16, v240
	v_mov_b32_e32 v17, v241
	v_and_b32_e32 v147, 0xffff0000, v17
	v_and_b32_e32 v146, 0xffff0000, v16
	v_lshlrev_b32_e32 v148, 16, v16
	v_lshlrev_b32_e32 v149, 16, v17
	v_mov_b32_e32 v159, v148
	v_mov_b32_e32 v161, v149
	v_mov_b32_e32 v157, v147
	s_waitcnt vmcnt(0)
	v_mov_b32_e32 v16, v242
	v_mov_b32_e32 v17, v243
	v_and_b32_e32 v150, 0xffff0000, v16
	v_and_b32_e32 v151, 0xffff0000, v17
	v_lshlrev_b32_e32 v152, 16, v16
	v_lshlrev_b32_e32 v153, 16, v17
	v_mov_b32_e32 v16, v150
	v_mov_b32_e32 v17, v146
	v_pk_mul_f32 v[16:17], v[16:17], v[16:17]
	v_mov_b32_e32 v158, v152
	v_pk_fma_f32 v[16:17], v[158:159], v[158:159], v[16:17]
	v_mov_b32_e32 v160, v153
	v_mov_b32_e32 v156, v151
	v_pk_fma_f32 v[16:17], v[160:161], v[160:161], v[16:17]
	s_waitcnt vmcnt(0)
	v_mov_b32_e32 v158, v248
	v_mov_b32_e32 v159, v249
	v_mov_b32_e32 v124, v250
	v_mov_b32_e32 v125, v251
	v_and_b32_e32 v160, 0xffff0000, v124
	v_pk_fma_f32 v[16:17], v[156:157], v[156:157], v[16:17]
	v_and_b32_e32 v156, 0xffff0000, v158
	v_lshlrev_b32_e32 v158, 16, v158
	v_lshlrev_b32_e32 v124, 16, v124
	v_mov_b32_e32 v162, v160
	v_mov_b32_e32 v163, v156
	v_and_b32_e32 v157, 0xffff0000, v159
	v_lshlrev_b32_e32 v159, 16, v159
	v_and_b32_e32 v161, 0xffff0000, v125
	v_lshlrev_b32_e32 v125, 16, v125
	v_pk_mul_f32 v[162:163], v[162:163], v[162:163]
	v_mov_b32_e32 v166, v124
	v_mov_b32_e32 v167, v158
	v_mov_b32_e32 v174, v125
	v_mov_b32_e32 v175, v159
	v_pk_fma_f32 v[162:163], v[166:167], v[166:167], v[162:163]
	v_mov_b32_e32 v164, v161
	v_mov_b32_e32 v165, v157
	v_pk_fma_f32 v[162:163], v[174:175], v[174:175], v[162:163]
	s_nop 0
	v_pk_fma_f32 v[162:163], v[164:165], v[164:165], v[162:163]
	v_mov_b32_e32 v165, v154
	v_mov_b32_e32 v164, v162
	v_mov_b32_e32 v154, v163
	v_pk_add_f32 v[154:155], v[164:165], v[154:155]
	v_mov_b32_e32 v162, v16
	v_mov_b32_e32 v163, v66
	v_pk_add_f32 v[154:155], v[154:155], v[162:163]
	v_mov_b32_e32 v66, v17
	v_pk_add_f32 v[16:17], v[154:155], v[66:67]
	s_nop 0
	s_nop 1
	v_add_f32_dpp v17, v17, v17 quad_perm:[1,0,3,2] row_mask:0xf bank_mask:0xf
	v_add_f32_dpp v16, v16, v16 quad_perm:[1,0,3,2] row_mask:0xf bank_mask:0xf
	s_nop 0
	v_add_f32_dpp v17, v17, v17 quad_perm:[2,3,0,1] row_mask:0xf bank_mask:0xf
	v_add_f32_dpp v16, v16, v16 quad_perm:[2,3,0,1] row_mask:0xf bank_mask:0xf
	s_nop 0
	v_add_f32_dpp v17, v17, v17 row_half_mirror row_mask:0xf bank_mask:0xf
	v_add_f32_dpp v16, v16, v16 row_half_mirror row_mask:0xf bank_mask:0xf
	s_nop 0
	v_add_f32_dpp v17, v17, v17 row_mirror row_mask:0xf bank_mask:0xf
	v_add_f32_dpp v16, v16, v16 row_mirror row_mask:0xf bank_mask:0xf
	s_nop 0
	v_mov_b32_e32 v67, v17
	v_mov_b32_e32 v66, v16
	s_nop 0
	v_permlane16_swap_b32_e32 v17, v67
	v_permlane16_swap_b32_e32 v16, v66
	s_nop 0
	v_add_f32_e32 v17, v17, v67
	v_add_f32_e32 v16, v16, v66
	s_nop 0
	v_mov_b32_e32 v67, v17
	v_mov_b32_e32 v66, v16
	s_nop 0
	v_permlane32_swap_b32_e32 v17, v67
	v_permlane32_swap_b32_e32 v16, v66
	s_nop 0
	v_add_f32_e32 v17, v17, v67
	v_add_f32_e32 v16, v16, v66
	s_nop 0
	s_nop 0
	v_pk_fma_f32 v[140:141], v[16:17], s[16:17], v[140:141] op_sel_hi:[1,0,0]
	s_nop 0
	v_mul_f32_e32 v16, 0x4b800000, v141
	v_cmp_gt_f32_e64 s[0:1], s14, v141
	v_cmp_gt_f32_e32 vcc, s14, v140
	s_nop 0
	v_cndmask_b32_e64 v16, v141, v16, s[0:1]
	v_rsq_f32_e32 v16, v16
	s_nop 0
	v_mul_f32_e32 v17, 0x45800000, v16
	v_cndmask_b32_e64 v16, v16, v17, s[0:1]
	v_pk_mul_f32 v[66:67], v[16:17], v[144:145] op_sel_hi:[0,1]
	v_pk_mul_f32 v[70:71], v[16:17], v[70:71] op_sel_hi:[0,1]
	v_pk_mul_f32 v[66:67], v[130:131], v[66:67]
	v_pk_mul_f32 v[144:145], v[34:35], v[70:71]
	v_pk_fma_f32 v[70:71], v[122:123], v[66:67], v[36:37]
	v_pk_fma_f32 v[66:67], v[144:145], v[38:39], v[30:31]
	v_pk_mul_f32 v[30:31], v[16:17], v[142:143] op_sel_hi:[0,1]
	v_pk_mul_f32 v[36:37], v[16:17], v[64:65] op_sel_hi:[0,1]
	v_pk_mul_f32 v[30:31], v[30:31], v[128:129]
	v_pk_mul_f32 v[36:37], v[36:37], v[42:43]
	v_pk_fma_f32 v[64:65], v[30:31], v[76:77], v[72:73]
	v_pk_fma_f32 v[36:37], v[36:37], v[46:47], v[26:27]
	v_pk_mul_f32 v[26:27], v[16:17], v[138:139] op_sel_hi:[0,1]
	v_pk_mul_f32 v[30:31], v[16:17], v[136:137] op_sel_hi:[0,1]
	v_pk_mul_f32 v[26:27], v[26:27], v[126:127]
	v_pk_mul_f32 v[72:73], v[30:31], v[50:51]
	v_pk_fma_f32 v[30:31], v[26:27], v[8:9], v[84:85]
	v_pk_fma_f32 v[26:27], v[72:73], v[54:55], v[22:23]
	v_pk_mul_f32 v[22:23], v[16:17], v[94:95] op_sel_hi:[0,1]
	v_pk_mul_f32 v[16:17], v[16:17], v[90:91] op_sel_hi:[0,1]
	v_pk_mul_f32 v[16:17], v[16:17], v[58:59]
	v_pk_mul_f32 v[22:23], v[22:23], v[4:5]
	v_pk_fma_f32 v[16:17], v[16:17], v[62:63], v[18:19]
	v_mul_f32_e32 v18, 0x4b800000, v140
	v_cndmask_b32_e32 v18, v140, v18, vcc
	v_rsq_f32_e32 v18, v18
	v_pk_fma_f32 v[22:23], v[22:23], v[132:133], v[134:135]
	v_mul_f32_e32 v19, 0x45800000, v18
	v_cndmask_b32_e32 v18, v18, v19, vcc
	v_pk_mul_f32 v[72:73], v[18:19], v[124:125] op_sel_hi:[0,1]
	v_pk_mul_f32 v[84:85], v[18:19], v[160:161] op_sel_hi:[0,1]
	v_pk_mul_f32 v[72:73], v[130:131], v[72:73]
	v_pk_mul_f32 v[34:35], v[34:35], v[84:85]
	v_pk_fma_f32 v[84:85], v[122:123], v[72:73], v[28:29]
	v_pk_fma_f32 v[72:73], v[38:39], v[34:35], v[14:15]
	v_pk_mul_f32 v[14:15], v[18:19], v[158:159] op_sel_hi:[0,1]
	v_pk_mul_f32 v[28:29], v[18:19], v[156:157] op_sel_hi:[0,1]
	v_pk_mul_f32 v[14:15], v[128:129], v[14:15]
	v_pk_mul_f32 v[28:29], v[42:43], v[28:29]
	v_pk_fma_f32 v[42:43], v[14:15], v[76:77], v[44:45]
	v_pk_fma_f32 v[38:39], v[28:29], v[46:47], v[10:11]
	v_pk_mul_f32 v[10:11], v[18:19], v[152:153] op_sel_hi:[0,1]
	v_pk_mul_f32 v[14:15], v[18:19], v[150:151] op_sel_hi:[0,1]
	v_pk_mul_f32 v[10:11], v[10:11], v[126:127]
	v_pk_mul_f32 v[14:15], v[14:15], v[50:51]
	v_pk_fma_f32 v[34:35], v[10:11], v[8:9], v[68:69]
	v_pk_fma_f32 v[28:29], v[14:15], v[54:55], v[6:7]
	v_pk_mul_f32 v[6:7], v[18:19], v[148:149] op_sel_hi:[0,1]
	v_mov_b32_e32 v8, v0
	v_mov_b32_e32 v9, v2
	v_mov_b32_e32 v2, v1
	v_lshlrev_b64 v[0:1], 12, v[104:105]
	v_pk_mul_f32 v[4:5], v[6:7], v[4:5]
	v_pk_mul_f32 v[6:7], v[18:19], v[146:147] op_sel_hi:[0,1]
	v_lshl_add_u64 v[0:1], s[88:89], 0, v[0:1]
	v_pk_mul_f32 v[6:7], v[6:7], v[58:59]
	v_cndmask_b32_e64 v1, v121, v1, s[2:3]
	v_cndmask_b32_e64 v0, v120, v0, s[2:3]
	v_pk_fma_f32 v[14:15], v[4:5], v[132:133], v[8:9]
	v_pk_fma_f32 v[18:19], v[6:7], v[62:63], v[2:3]
	v_lshl_add_u64 v[4:5], v[0:1], 0, v[192:193]
	v_mov_b32_e32 v0, v92
	v_mov_b32_e32 v1, v88
	v_mov_b32_e32 v2, v93
	v_mov_b32_e32 v3, v89
	global_store_dwordx4 v[4:5], v[0:3], off nt
	v_add_co_u32_e32 v6, vcc, s12, v4
	s_nop 0
	v_mov_b32_e32 v0, v80
	v_mov_b32_e32 v1, v60
	v_mov_b32_e32 v2, v81
	v_mov_b32_e32 v3, v61
	global_store_dwordx4 v[4:5], v[0:3], off offset:1024 nt
	v_addc_co_u32_e32 v7, vcc, 0, v5, vcc
	s_nop 0
	v_mov_b32_e32 v0, v56
	v_mov_b32_e32 v1, v40
	v_mov_b32_e32 v2, v57
	v_mov_b32_e32 v3, v41
	global_store_dwordx4 v[4:5], v[0:3], off offset:2048 nt
	v_add_co_u32_e32 v8, vcc, s13, v4
	s_nop 0
	v_mov_b32_e32 v0, v32
	v_mov_b32_e32 v1, v12
	v_mov_b32_e32 v2, v33
	v_mov_b32_e32 v3, v13
	global_store_dwordx4 v[4:5], v[0:3], off offset:3072 nt
	v_addc_co_u32_e32 v9, vcc, 0, v5, vcc
	s_nop 0
	v_mov_b32_e32 v0, v86
	v_mov_b32_e32 v1, v82
	v_mov_b32_e32 v2, v87
	v_mov_b32_e32 v3, v83
	global_store_dwordx4 v[8:9], v[0:3], off offset:-4096 nt
	v_add_co_u32_e32 v4, vcc, s73, v4
	s_nop 0
	v_mov_b32_e32 v0, v78
	v_mov_b32_e32 v1, v74
	v_mov_b32_e32 v2, v79
	v_mov_b32_e32 v3, v75
	global_store_dwordx4 v[6:7], v[0:3], off offset:1024 nt
	v_addc_co_u32_e32 v5, vcc, 0, v5, vcc
	s_nop 0
	v_mov_b32_e32 v0, v52
	v_mov_b32_e32 v1, v48
	v_mov_b32_e32 v2, v53
	v_mov_b32_e32 v3, v49
	global_store_dwordx4 v[6:7], v[0:3], off offset:2048 nt
	s_andn2_b64 vcc, exec, s[4:5]
	s_nop 0
	v_mov_b32_e32 v0, v24
	v_mov_b32_e32 v1, v20
	v_mov_b32_e32 v2, v25
	v_mov_b32_e32 v3, v21
	global_store_dwordx4 v[6:7], v[0:3], off offset:3072 nt
	s_nop 1
	v_mov_b32_e32 v0, v70
	v_mov_b32_e32 v1, v66
	v_mov_b32_e32 v2, v71
	v_mov_b32_e32 v3, v67
	global_store_dwordx4 v[8:9], v[0:3], off nt
	s_nop 1
	v_mov_b32_e32 v0, v64
	v_mov_b32_e32 v1, v36
	v_mov_b32_e32 v2, v65
	v_mov_b32_e32 v3, v37
	global_store_dwordx4 v[8:9], v[0:3], off offset:1024 nt
	s_nop 1
	v_mov_b32_e32 v0, v30
	v_mov_b32_e32 v1, v26
	v_mov_b32_e32 v2, v31
	v_mov_b32_e32 v3, v27
	global_store_dwordx4 v[8:9], v[0:3], off offset:2048 nt
	s_nop 1
	v_mov_b32_e32 v0, v22
	v_mov_b32_e32 v1, v16
	v_mov_b32_e32 v2, v23
	v_mov_b32_e32 v3, v17
	global_store_dwordx4 v[8:9], v[0:3], off offset:3072 nt
	s_nop 1
	v_mov_b32_e32 v0, v84
	v_mov_b32_e32 v1, v72
	v_mov_b32_e32 v2, v85
	v_mov_b32_e32 v3, v73
	global_store_dwordx4 v[4:5], v[0:3], off nt
	s_nop 1
	v_mov_b32_e32 v0, v42
	v_mov_b32_e32 v1, v38
	v_mov_b32_e32 v2, v43
	v_mov_b32_e32 v3, v39
	global_store_dwordx4 v[4:5], v[0:3], off offset:1024 nt
	s_nop 1
	v_mov_b32_e32 v0, v34
	v_mov_b32_e32 v1, v28
	v_mov_b32_e32 v2, v35
	v_mov_b32_e32 v3, v29
	global_store_dwordx4 v[4:5], v[0:3], off offset:2048 nt
	s_nop 1
	v_mov_b32_e32 v0, v14
	v_mov_b32_e32 v1, v18
	v_mov_b32_e32 v2, v15
	v_mov_b32_e32 v3, v19
	global_store_dwordx4 v[4:5], v[0:3], off offset:3072 nt
	s_cbranch_vccnz .LBB0_27
	v_mov_b32_e32 v4, v88
	v_mov_b32_e32 v5, v60
	v_mov_b32_e32 v2, v92
	v_mov_b32_e32 v3, v80
	v_pk_mul_f32 v[4:5], v[4:5], v[4:5]
	v_mov_b32_e32 v6, v40
	v_pk_fma_f32 v[2:3], v[2:3], v[2:3], v[4:5]
	v_mov_b32_e32 v4, v93
	v_mov_b32_e32 v5, v81
	v_pk_fma_f32 v[2:3], v[4:5], v[4:5], v[2:3]
	v_mov_b32_e32 v4, v89
	v_mov_b32_e32 v5, v61
	v_mov_b32_e32 v7, v12
	v_pk_fma_f32 v[2:3], v[4:5], v[4:5], v[2:3]
	v_mov_b32_e32 v4, v56
	v_mov_b32_e32 v5, v32
	v_pk_mul_f32 v[6:7], v[6:7], v[6:7]
	v_mov_b32_e32 v8, v82
	v_pk_fma_f32 v[4:5], v[4:5], v[4:5], v[6:7]
	v_mov_b32_e32 v6, v57
	v_mov_b32_e32 v7, v33
	v_pk_fma_f32 v[4:5], v[6:7], v[6:7], v[4:5]
	v_mov_b32_e32 v6, v41
	v_mov_b32_e32 v7, v13
	v_mov_b32_e32 v9, v74
	v_pk_fma_f32 v[4:5], v[6:7], v[6:7], v[4:5]
	v_mov_b32_e32 v6, v86
	v_mov_b32_e32 v7, v78
	v_pk_mul_f32 v[8:9], v[8:9], v[8:9]
	v_mov_b32_e32 v10, v48
	v_pk_fma_f32 v[6:7], v[6:7], v[6:7], v[8:9]
	v_mov_b32_e32 v8, v87
	v_mov_b32_e32 v9, v79
	v_pk_fma_f32 v[6:7], v[8:9], v[8:9], v[6:7]
	v_mov_b32_e32 v8, v83
	v_mov_b32_e32 v9, v75
	v_mov_b32_e32 v11, v20
	v_pk_fma_f32 v[6:7], v[8:9], v[8:9], v[6:7]
	v_mov_b32_e32 v8, v52
	v_mov_b32_e32 v9, v24
	v_pk_mul_f32 v[10:11], v[10:11], v[10:11]
	s_mov_b32 s0, 0x358637bd
	v_pk_fma_f32 v[8:9], v[8:9], v[8:9], v[10:11]
	v_mov_b32_e32 v10, v53
	v_mov_b32_e32 v11, v25
	v_pk_fma_f32 v[8:9], v[10:11], v[10:11], v[8:9]
	v_mov_b32_e32 v10, v49
	v_mov_b32_e32 v11, v21
	v_pk_fma_f32 v[8:9], v[10:11], v[10:11], v[8:9]
	v_mov_b32_e32 v10, v6
	v_mov_b32_e32 v11, v2
	v_mov_b32_e32 v2, v7
	v_pk_add_f32 v[2:3], v[10:11], v[2:3]
	v_mov_b32_e32 v6, v8
	v_mov_b32_e32 v7, v4
	v_pk_add_f32 v[2:3], v[2:3], v[6:7]
	v_mov_b32_e32 v4, v9
	v_pk_add_f32 v[2:3], v[2:3], v[4:5]
	s_mov_b32 s14, 0x3a800000
	s_mov_b32 s12, 0x800000
	v_mov_b32_e32 v7, v36
	v_mov_b32_e32 v8, v26
	v_mov_b32_e32 v9, v16
	v_pk_mul_f32 v[8:9], v[8:9], v[8:9]
	v_mov_b32_e32 v10, v72
	v_mov_b32_e32 v11, v38
	v_pk_mul_f32 v[10:11], v[10:11], v[10:11]
	v_mov_b32_e32 v50, v28
	v_mov_b32_e32 v51, v18
	v_pk_mul_f32 v[50:51], v[50:51], v[50:51]
	v_add_u32_e32 v0, v172, v168
	v_mul_hi_i32_i24_e32 v1, 0x6000, v0
	v_mul_i32_i24_e32 v0, 0x6000, v0
	v_lshl_add_u64 v[0:1], s[96:97], 0, v[0:1]
	v_lshl_add_u64 v[62:63], v[0:1], 0, v[192:193]
	v_lshl_add_u64 v[58:59], v[102:103], 0, v[118:119]
	s_nop 0
	s_nop 1
	v_add_f32_dpp v3, v3, v3 quad_perm:[1,0,3,2] row_mask:0xf bank_mask:0xf
	v_add_f32_dpp v2, v2, v2 quad_perm:[1,0,3,2] row_mask:0xf bank_mask:0xf
	s_nop 0
	v_add_f32_dpp v3, v3, v3 quad_perm:[2,3,0,1] row_mask:0xf bank_mask:0xf
	v_add_f32_dpp v2, v2, v2 quad_perm:[2,3,0,1] row_mask:0xf bank_mask:0xf
	s_nop 0
	v_add_f32_dpp v3, v3, v3 row_half_mirror row_mask:0xf bank_mask:0xf
	v_add_f32_dpp v2, v2, v2 row_half_mirror row_mask:0xf bank_mask:0xf
	s_nop 0
	v_add_f32_dpp v3, v3, v3 row_mirror row_mask:0xf bank_mask:0xf
	v_add_f32_dpp v2, v2, v2 row_mirror row_mask:0xf bank_mask:0xf
	s_nop 0
	v_mov_b32_e32 v5, v3
	v_mov_b32_e32 v4, v2
	s_nop 0
	v_permlane16_swap_b32_e32 v3, v5
	v_permlane16_swap_b32_e32 v2, v4
	s_nop 0
	v_add_f32_e32 v3, v3, v5
	v_add_f32_e32 v2, v2, v4
	s_nop 0
	v_mov_b32_e32 v5, v3
	v_mov_b32_e32 v4, v2
	s_nop 0
	v_permlane32_swap_b32_e32 v3, v5
	v_permlane32_swap_b32_e32 v2, v4
	s_nop 0
	v_add_f32_e32 v3, v3, v5
	v_add_f32_e32 v2, v2, v4
	s_nop 0
	v_mov_b64_e32 v[4:5], s[0:1]
	v_pk_fma_f32 v[2:3], v[2:3], s[14:15], v[4:5] op_sel_hi:[1,0,0]
	s_nop 0
	v_mul_f32_e32 v6, 0x4b800000, v3
	v_cmp_gt_f32_e64 s[0:1], s12, v3
	v_cmp_gt_f32_e32 vcc, s12, v2
	s_nop 0
	v_cndmask_b32_e64 v3, v3, v6, s[0:1]
	v_rsq_f32_e32 v3, v3
	s_nop 0
	v_mul_f32_e32 v6, 0x45800000, v3
	v_cndmask_b32_e64 v46, v3, v6, s[0:1]
	v_mul_f32_e32 v3, 0x4b800000, v2
	v_cndmask_b32_e32 v2, v2, v3, vcc
	v_rsq_f32_e32 v2, v2
	v_mov_b32_e32 v6, v66
	v_pk_mul_f32 v[6:7], v[6:7], v[6:7]
	v_pk_mul_f32 v[88:89], v[88:89], v[46:47] op_sel_hi:[1,0]
	v_mul_f32_e32 v3, 0x45800000, v2
	v_cndmask_b32_e32 v44, v2, v3, vcc
	v_mov_b32_e32 v2, v70
	v_mov_b32_e32 v3, v64
	v_pk_fma_f32 v[2:3], v[2:3], v[2:3], v[6:7]
	v_mov_b32_e32 v6, v71
	v_mov_b32_e32 v7, v65
	v_pk_fma_f32 v[2:3], v[6:7], v[6:7], v[2:3]
	v_mov_b32_e32 v6, v67
	v_mov_b32_e32 v7, v37
	v_pk_fma_f32 v[2:3], v[6:7], v[6:7], v[2:3]
	v_mov_b32_e32 v6, v30
	v_mov_b32_e32 v7, v22
	v_pk_fma_f32 v[6:7], v[6:7], v[6:7], v[8:9]
	v_mov_b32_e32 v8, v31
	v_mov_b32_e32 v9, v23
	v_pk_fma_f32 v[6:7], v[8:9], v[8:9], v[6:7]
	v_mov_b32_e32 v8, v27
	v_mov_b32_e32 v9, v17
	v_pk_fma_f32 v[6:7], v[8:9], v[8:9], v[6:7]
	v_mov_b32_e32 v8, v84
	v_mov_b32_e32 v9, v42
	v_pk_fma_f32 v[8:9], v[8:9], v[8:9], v[10:11]
	v_mov_b32_e32 v10, v85
	v_mov_b32_e32 v11, v43
	v_pk_fma_f32 v[8:9], v[10:11], v[10:11], v[8:9]
	v_mov_b32_e32 v10, v73
	v_mov_b32_e32 v11, v39
	v_pk_fma_f32 v[8:9], v[10:11], v[10:11], v[8:9]
	v_mov_b32_e32 v10, v34
	v_mov_b32_e32 v11, v14
	v_pk_fma_f32 v[10:11], v[10:11], v[10:11], v[50:51]
	v_mov_b32_e32 v50, v35
	v_mov_b32_e32 v51, v15
	v_pk_fma_f32 v[10:11], v[50:51], v[50:51], v[10:11]
	v_mov_b32_e32 v50, v29
	v_mov_b32_e32 v51, v19
	v_pk_fma_f32 v[10:11], v[50:51], v[50:51], v[10:11]
	v_mov_b32_e32 v50, v8
	v_mov_b32_e32 v51, v2
	v_mov_b32_e32 v2, v9
	v_pk_add_f32 v[2:3], v[50:51], v[2:3]
	v_mov_b32_e32 v8, v10
	v_mov_b32_e32 v9, v6
	v_pk_add_f32 v[2:3], v[2:3], v[8:9]
	v_mov_b32_e32 v6, v11
	v_pk_add_f32 v[2:3], v[2:3], v[6:7]
	v_mov_b32_e32 v107, v193
	v_mov_b32_e32 v109, v193
	v_mov_b32_e32 v111, v193
	s_nop 0
	s_nop 1
	v_add_f32_dpp v3, v3, v3 quad_perm:[1,0,3,2] row_mask:0xf bank_mask:0xf
	v_add_f32_dpp v2, v2, v2 quad_perm:[1,0,3,2] row_mask:0xf bank_mask:0xf
	s_nop 0
	v_add_f32_dpp v3, v3, v3 quad_perm:[2,3,0,1] row_mask:0xf bank_mask:0xf
	v_add_f32_dpp v2, v2, v2 quad_perm:[2,3,0,1] row_mask:0xf bank_mask:0xf
	s_nop 0
	v_add_f32_dpp v3, v3, v3 row_half_mirror row_mask:0xf bank_mask:0xf
	v_add_f32_dpp v2, v2, v2 row_half_mirror row_mask:0xf bank_mask:0xf
	s_nop 0
	v_add_f32_dpp v3, v3, v3 row_mirror row_mask:0xf bank_mask:0xf
	v_add_f32_dpp v2, v2, v2 row_mirror row_mask:0xf bank_mask:0xf
	s_nop 0
	v_mov_b32_e32 v7, v3
	v_mov_b32_e32 v6, v2
	s_nop 0
	v_permlane16_swap_b32_e32 v3, v7
	v_permlane16_swap_b32_e32 v2, v6
	s_nop 0
	v_add_f32_e32 v3, v3, v7
	v_add_f32_e32 v2, v2, v6
	s_nop 0
	v_mov_b32_e32 v7, v3
	v_mov_b32_e32 v6, v2
	s_nop 0
	v_permlane32_swap_b32_e32 v3, v7
	v_permlane32_swap_b32_e32 v2, v6
	s_nop 0
	v_add_f32_e32 v3, v3, v7
	v_add_f32_e32 v2, v2, v6
	s_nop 0
	s_nop 0
	v_pk_fma_f32 v[2:3], v[2:3], s[14:15], v[4:5] op_sel_hi:[1,0,0]
	s_nop 0
	v_mul_f32_e32 v4, 0x4b800000, v3
	v_cmp_gt_f32_e64 s[0:1], s12, v3
	v_cmp_gt_f32_e32 vcc, s12, v2
	s_nop 0
	v_cndmask_b32_e64 v3, v3, v4, s[0:1]
	v_rsq_f32_e32 v3, v3
	s_nop 0
	v_mul_f32_e32 v4, 0x45800000, v3
	v_cndmask_b32_e64 v54, v3, v4, s[0:1]
	v_mul_f32_e32 v3, 0x4b800000, v2
	v_cndmask_b32_e32 v2, v2, v3, vcc
	v_rsq_f32_e32 v2, v2
	s_mov_b64 s[0:1], 0x1000
	v_lshl_add_u64 v[68:69], v[0:1], 0, s[0:1]
	v_lshl_add_u64 v[4:5], v[68:69], 0, v[192:193]
	v_mul_f32_e32 v3, 0x45800000, v2
	v_cndmask_b32_e32 v50, v2, v3, vcc
	global_load_dwordx4 v[0:3], v[100:101], off
	global_load_dwordx4 v[8:11], v[4:5], off
	s_nop 0
	global_load_dwordx4 v[4:7], v[62:63], off
	v_pk_mul_f32 v[66:67], v[66:67], v[54:55] op_sel_hi:[1,0]
	v_pk_mul_f32 v[36:37], v[36:37], v[54:55] op_sel_hi:[1,0]
	v_pk_mul_f32 v[26:27], v[26:27], v[54:55] op_sel_hi:[1,0]
	s_waitcnt vmcnt(2)
	v_mov_b32_e32 v90, v0
	s_waitcnt vmcnt(1)
	v_mov_b32_e32 v76, v8
	v_mov_b32_e32 v77, v10
	v_mov_b32_e32 v10, v9
	v_pk_mul_f32 v[8:9], v[92:93], v[46:47] op_sel_hi:[1,0]
	v_mov_b32_e32 v91, v2
	v_pk_add_f32 v[76:77], v[76:77], 1.0 op_sel_hi:[1,0]
	v_pk_mul_f32 v[8:9], v[8:9], v[90:91]
	s_waitcnt vmcnt(0)
	v_mov_b32_e32 v92, v4
	v_mov_b32_e32 v93, v6
	v_mov_b32_e32 v2, v1
	v_pk_add_f32 v[10:11], v[10:11], 1.0 op_sel_hi:[1,0]
	v_pk_fma_f32 v[8:9], v[8:9], v[76:77], v[92:93]
	v_pk_mul_f32 v[0:1], v[88:89], v[2:3]
	v_mov_b32_e32 v6, v5
	v_pk_fma_f32 v[0:1], v[0:1], v[10:11], v[6:7]
	v_cvt_pk_bf16_f32 v0, v8, v0
	v_cvt_pk_bf16_f32 v1, v9, v1
	v_pk_mul_f32 v[4:5], v[86:87], v[44:45] op_sel_hi:[1,0]
	v_pk_mul_f32 v[8:9], v[82:83], v[44:45] op_sel_hi:[1,0]
	v_pk_mul_f32 v[4:5], v[4:5], v[90:91]
	v_pk_mul_f32 v[8:9], v[8:9], v[2:3]
	v_pk_fma_f32 v[4:5], v[4:5], v[76:77], v[92:93]
	v_pk_fma_f32 v[8:9], v[8:9], v[10:11], v[6:7]
	v_cvt_pk_bf16_f32 v5, v5, v9
	v_cvt_pk_bf16_f32 v4, v4, v8
	v_pk_mul_f32 v[8:9], v[70:71], v[54:55] op_sel_hi:[1,0]
	v_pk_mul_f32 v[66:67], v[2:3], v[66:67]
	v_pk_mul_f32 v[8:9], v[90:91], v[8:9]
	v_pk_fma_f32 v[66:67], v[66:67], v[10:11], v[6:7]
	v_pk_fma_f32 v[8:9], v[8:9], v[76:77], v[92:93]
	v_pk_mul_f32 v[70:71], v[72:73], v[50:51] op_sel_hi:[1,0]
	v_cvt_pk_bf16_f32 v9, v9, v67
	v_and_b32_sdwa v47, v8, v218 dst_sel:DWORD dst_unused:UNUSED_PAD src0_sel:WORD_1 src1_sel:DWORD
	v_add3_u32 v8, v8, v47, s80
	v_and_b32_sdwa v47, v66, v218 dst_sel:DWORD dst_unused:UNUSED_PAD src0_sel:WORD_1 src1_sel:DWORD
	v_add3_u32 v47, v66, v47, s80
	v_pk_mul_f32 v[66:67], v[84:85], v[50:51] op_sel_hi:[1,0]
	v_pk_mul_f32 v[2:3], v[2:3], v[70:71]
	v_pk_mul_f32 v[66:67], v[90:91], v[66:67]
	v_pk_fma_f32 v[2:3], v[10:11], v[2:3], v[6:7]
	v_pk_fma_f32 v[66:67], v[76:77], v[66:67], v[92:93]
	global_store_dwordx2 v[58:59], v[0:1], off
	v_lshl_add_u64 v[0:1], v[102:103], 0, v[116:117]
	v_and_b32_e32 v47, 0xffff0000, v47
	v_cvt_pk_bf16_f32 v3, v67, v3
	v_cvt_pk_bf16_f32 v2, v66, v2
	global_store_dwordx2 v[0:1], v[4:5], off
	v_lshl_add_u64 v[4:5], v[102:103], 0, v[114:115]
	v_or_b32_sdwa v8, v47, v8 dst_sel:DWORD dst_unused:UNUSED_PAD src0_sel:DWORD src1_sel:WORD_1
	global_store_dwordx2 v[4:5], v[8:9], off
	v_lshl_add_u64 v[8:9], v[102:103], 0, v[112:113]
	global_store_dwordx2 v[8:9], v[2:3], off
	v_lshl_add_u64 v[2:3], v[68:69], 0, v[106:107]
	global_load_dwordx4 v[70:73], v[100:101], off offset:1024
	global_load_dwordx4 v[82:85], v[2:3], off
	global_load_dwordx4 v[86:89], v[62:63], off offset:1024
	v_pk_mul_f32 v[10:11], v[80:81], v[46:47] op_sel_hi:[1,0]
	v_pk_mul_f32 v[60:61], v[60:61], v[46:47] op_sel_hi:[1,0]
	s_waitcnt vmcnt(2)
	v_mov_b32_e32 v66, v70
	s_waitcnt vmcnt(1)
	v_mov_b32_e32 v2, v82
	v_mov_b32_e32 v3, v84
	v_mov_b32_e32 v67, v72
	v_pk_add_f32 v[2:3], v[2:3], 1.0 op_sel_hi:[1,0]
	v_mov_b32_e32 v84, v83
	v_pk_mul_f32 v[10:11], v[10:11], v[66:67]
	s_waitcnt vmcnt(0)
	v_mov_b32_e32 v76, v86
	v_mov_b32_e32 v77, v88
	v_mov_b32_e32 v72, v71
	v_pk_add_f32 v[6:7], v[84:85], 1.0 op_sel_hi:[1,0]
	v_pk_fma_f32 v[10:11], v[10:11], v[2:3], v[76:77]
	v_pk_mul_f32 v[60:61], v[60:61], v[72:73]
	v_mov_b32_e32 v88, v87
	v_pk_fma_f32 v[60:61], v[60:61], v[6:7], v[88:89]
	v_and_b32_sdwa v45, v11, v218 dst_sel:DWORD dst_unused:UNUSED_PAD src0_sel:WORD_1 src1_sel:DWORD
	v_cvt_pk_bf16_f32 v10, v10, v60
	v_add3_u32 v11, v11, v45, s80
	v_and_b32_sdwa v45, v61, v218 dst_sel:DWORD dst_unused:UNUSED_PAD src0_sel:WORD_1 src1_sel:DWORD
	v_add3_u32 v45, v61, v45, s80
	v_and_b32_e32 v45, 0xffff0000, v45
	v_or_b32_sdwa v11, v45, v11 dst_sel:DWORD dst_unused:UNUSED_PAD src0_sel:DWORD src1_sel:WORD_1
	global_store_dwordx2 v[58:59], v[10:11], off offset:512
	v_pk_mul_f32 v[10:11], v[78:79], v[44:45] op_sel_hi:[1,0]
	v_pk_mul_f32 v[60:61], v[74:75], v[44:45] op_sel_hi:[1,0]
	v_pk_mul_f32 v[10:11], v[10:11], v[66:67]
	v_pk_mul_f32 v[60:61], v[60:61], v[72:73]
	v_pk_fma_f32 v[10:11], v[10:11], v[2:3], v[76:77]
	v_pk_fma_f32 v[60:61], v[60:61], v[6:7], v[88:89]
	v_cvt_pk_bf16_f32 v11, v11, v61
	v_cvt_pk_bf16_f32 v10, v10, v60
	global_store_dwordx2 v[0:1], v[10:11], off offset:512
	v_pk_mul_f32 v[10:11], v[64:65], v[54:55] op_sel_hi:[1,0]
	v_pk_mul_f32 v[36:37], v[36:37], v[72:73]
	v_pk_mul_f32 v[10:11], v[10:11], v[66:67]
	v_pk_fma_f32 v[36:37], v[36:37], v[6:7], v[88:89]
	v_pk_fma_f32 v[10:11], v[10:11], v[2:3], v[76:77]
	s_nop 0
	v_and_b32_sdwa v45, v11, v218 dst_sel:DWORD dst_unused:UNUSED_PAD src0_sel:WORD_1 src1_sel:DWORD
	v_and_b32_sdwa v47, v10, v218 dst_sel:DWORD dst_unused:UNUSED_PAD src0_sel:WORD_1 src1_sel:DWORD
	v_add3_u32 v10, v10, v47, s80
	v_add3_u32 v11, v11, v45, s80
	v_and_b32_sdwa v45, v37, v218 dst_sel:DWORD dst_unused:UNUSED_PAD src0_sel:WORD_1 src1_sel:DWORD
	v_and_b32_sdwa v47, v36, v218 dst_sel:DWORD dst_unused:UNUSED_PAD src0_sel:WORD_1 src1_sel:DWORD
	v_add3_u32 v37, v37, v45, s80
	v_add3_u32 v36, v36, v47, s80
	v_and_b32_e32 v37, 0xffff0000, v37
	v_and_b32_e32 v36, 0xffff0000, v36
	v_or_b32_sdwa v11, v37, v11 dst_sel:DWORD dst_unused:UNUSED_PAD src0_sel:DWORD src1_sel:WORD_1
	v_or_b32_sdwa v10, v36, v10 dst_sel:DWORD dst_unused:UNUSED_PAD src0_sel:DWORD src1_sel:WORD_1
	global_store_dwordx2 v[4:5], v[10:11], off offset:512
	v_pk_mul_f32 v[10:11], v[42:43], v[50:51] op_sel_hi:[1,0]
	v_pk_mul_f32 v[40:41], v[40:41], v[46:47] op_sel_hi:[1,0]
	v_pk_mul_f32 v[10:11], v[10:11], v[66:67]
	v_pk_mul_f32 v[12:13], v[12:13], v[46:47] op_sel_hi:[1,0]
	v_pk_fma_f32 v[2:3], v[10:11], v[2:3], v[76:77]
	v_pk_mul_f32 v[10:11], v[38:39], v[50:51] op_sel_hi:[1,0]
	s_nop 0
	v_pk_mul_f32 v[10:11], v[10:11], v[72:73]
	s_nop 0
	v_pk_fma_f32 v[6:7], v[10:11], v[6:7], v[88:89]
	v_cvt_pk_bf16_f32 v3, v3, v7
	v_cvt_pk_bf16_f32 v2, v2, v6
	global_store_dwordx2 v[8:9], v[2:3], off offset:512
	v_lshl_add_u64 v[2:3], v[68:69], 0, v[108:109]
	global_load_dwordx4 v[36:39], v[100:101], off offset:2048
	global_load_dwordx4 v[64:67], v[2:3], off
	global_load_dwordx4 v[70:73], v[62:63], off offset:2048
	v_pk_mul_f32 v[10:11], v[56:57], v[46:47] op_sel_hi:[1,0]
	s_waitcnt vmcnt(2)
	v_mov_b32_e32 v42, v36
	s_waitcnt vmcnt(1)
	v_mov_b32_e32 v2, v64
	v_mov_b32_e32 v3, v66
	v_mov_b32_e32 v43, v38
	v_pk_add_f32 v[2:3], v[2:3], 1.0 op_sel_hi:[1,0]
	v_mov_b32_e32 v66, v65
	v_pk_mul_f32 v[10:11], v[10:11], v[42:43]
	s_waitcnt vmcnt(0)
	v_mov_b32_e32 v56, v70
	v_mov_b32_e32 v57, v72
	v_mov_b32_e32 v38, v37
	v_pk_add_f32 v[6:7], v[66:67], 1.0 op_sel_hi:[1,0]
	v_pk_fma_f32 v[10:11], v[10:11], v[2:3], v[56:57]
	v_pk_mul_f32 v[36:37], v[40:41], v[38:39]
	v_mov_b32_e32 v72, v71
	v_pk_fma_f32 v[36:37], v[36:37], v[6:7], v[72:73]
	v_cvt_pk_bf16_f32 v11, v11, v37
	v_cvt_pk_bf16_f32 v10, v10, v36
	global_store_dwordx2 v[58:59], v[10:11], off offset:1024
	v_pk_mul_f32 v[10:11], v[52:53], v[44:45] op_sel_hi:[1,0]
	v_pk_mul_f32 v[36:37], v[48:49], v[44:45] op_sel_hi:[1,0]
	v_pk_mul_f32 v[10:11], v[10:11], v[42:43]
	v_pk_mul_f32 v[36:37], v[36:37], v[38:39]
	v_pk_fma_f32 v[10:11], v[10:11], v[2:3], v[56:57]
	v_pk_fma_f32 v[36:37], v[36:37], v[6:7], v[72:73]
	v_cvt_pk_bf16_f32 v11, v11, v37
	v_cvt_pk_bf16_f32 v10, v10, v36
	global_store_dwordx2 v[0:1], v[10:11], off offset:1024
	v_pk_mul_f32 v[10:11], v[30:31], v[54:55] op_sel_hi:[1,0]
	v_pk_mul_f32 v[26:27], v[26:27], v[38:39]
	v_pk_mul_f32 v[10:11], v[10:11], v[42:43]
	v_pk_fma_f32 v[26:27], v[26:27], v[6:7], v[72:73]
	v_pk_fma_f32 v[10:11], v[10:11], v[2:3], v[56:57]
	s_nop 0
	v_cvt_pk_bf16_f32 v11, v11, v27
	v_cvt_pk_bf16_f32 v10, v10, v26
	global_store_dwordx2 v[4:5], v[10:11], off offset:1024
	v_pk_mul_f32 v[10:11], v[34:35], v[50:51] op_sel_hi:[1,0]
	s_nop 0
	v_pk_mul_f32 v[10:11], v[10:11], v[42:43]
	s_nop 0
	v_pk_fma_f32 v[2:3], v[10:11], v[2:3], v[56:57]
	v_pk_mul_f32 v[10:11], v[28:29], v[50:51] op_sel_hi:[1,0]
	s_nop 0
	v_pk_mul_f32 v[10:11], v[10:11], v[38:39]
	s_nop 0
	v_pk_fma_f32 v[6:7], v[10:11], v[6:7], v[72:73]
	v_cvt_pk_bf16_f32 v3, v3, v7
	v_cvt_pk_bf16_f32 v2, v2, v6
	global_store_dwordx2 v[8:9], v[2:3], off offset:1024
	v_lshl_add_u64 v[2:3], v[68:69], 0, v[110:111]
	global_load_dwordx4 v[26:29], v[100:101], off offset:3072
	global_load_dwordx4 v[34:37], v[2:3], off
	global_load_dwordx4 v[38:41], v[62:63], off offset:3072
	v_pk_mul_f32 v[10:11], v[32:33], v[46:47] op_sel_hi:[1,0]
	s_waitcnt vmcnt(2)
	v_mov_b32_e32 v30, v26
	s_waitcnt vmcnt(1)
	v_mov_b32_e32 v2, v34
	v_mov_b32_e32 v3, v36
	v_mov_b32_e32 v31, v28
	v_pk_add_f32 v[2:3], v[2:3], 1.0 op_sel_hi:[1,0]
	v_mov_b32_e32 v36, v35
	v_pk_mul_f32 v[10:11], v[10:11], v[30:31]
	s_waitcnt vmcnt(0)
	v_mov_b32_e32 v32, v38
	v_mov_b32_e32 v33, v40
	v_mov_b32_e32 v28, v27
	v_pk_add_f32 v[6:7], v[36:37], 1.0 op_sel_hi:[1,0]
	v_pk_fma_f32 v[10:11], v[10:11], v[2:3], v[32:33]
	v_pk_mul_f32 v[12:13], v[12:13], v[28:29]
	v_mov_b32_e32 v40, v39
	v_pk_fma_f32 v[12:13], v[12:13], v[6:7], v[40:41]
	v_cvt_pk_bf16_f32 v11, v11, v13
	v_cvt_pk_bf16_f32 v10, v10, v12
	global_store_dwordx2 v[58:59], v[10:11], off offset:1536
	v_pk_mul_f32 v[10:11], v[24:25], v[44:45] op_sel_hi:[1,0]
	v_pk_mul_f32 v[12:13], v[20:21], v[44:45] op_sel_hi:[1,0]
	v_pk_mul_f32 v[10:11], v[10:11], v[30:31]
	v_pk_mul_f32 v[12:13], v[12:13], v[28:29]
	v_pk_fma_f32 v[10:11], v[10:11], v[2:3], v[32:33]
	v_pk_fma_f32 v[12:13], v[12:13], v[6:7], v[40:41]
	v_cvt_pk_bf16_f32 v11, v11, v13
	v_cvt_pk_bf16_f32 v10, v10, v12
	global_store_dwordx2 v[0:1], v[10:11], off offset:1536
	v_pk_mul_f32 v[0:1], v[22:23], v[54:55] op_sel_hi:[1,0]
	v_pk_mul_f32 v[10:11], v[16:17], v[54:55] op_sel_hi:[1,0]
	v_pk_mul_f32 v[0:1], v[0:1], v[30:31]
	v_pk_mul_f32 v[10:11], v[10:11], v[28:29]
	v_pk_fma_f32 v[0:1], v[0:1], v[2:3], v[32:33]
	v_pk_fma_f32 v[10:11], v[10:11], v[6:7], v[40:41]
	v_cvt_pk_bf16_f32 v1, v1, v11
	v_cvt_pk_bf16_f32 v0, v0, v10
	global_store_dwordx2 v[4:5], v[0:1], off offset:1536
	v_pk_mul_f32 v[0:1], v[14:15], v[50:51] op_sel_hi:[1,0]
	s_nop 0
	v_pk_mul_f32 v[0:1], v[0:1], v[30:31]
	s_nop 0
	v_pk_fma_f32 v[0:1], v[0:1], v[2:3], v[32:33]
	v_pk_mul_f32 v[2:3], v[18:19], v[50:51] op_sel_hi:[1,0]
	v_and_b32_sdwa v4, v1, v218 dst_sel:DWORD dst_unused:UNUSED_PAD src0_sel:WORD_1 src1_sel:DWORD
	v_pk_mul_f32 v[2:3], v[2:3], v[28:29]
	v_and_b32_sdwa v5, v0, v218 dst_sel:DWORD dst_unused:UNUSED_PAD src0_sel:WORD_1 src1_sel:DWORD
	v_pk_fma_f32 v[2:3], v[2:3], v[6:7], v[40:41]
	v_add3_u32 v0, v0, v5, s80
	v_add3_u32 v1, v1, v4, s80
	v_and_b32_sdwa v4, v3, v218 dst_sel:DWORD dst_unused:UNUSED_PAD src0_sel:WORD_1 src1_sel:DWORD
	v_and_b32_sdwa v5, v2, v218 dst_sel:DWORD dst_unused:UNUSED_PAD src0_sel:WORD_1 src1_sel:DWORD
	v_add3_u32 v3, v3, v4, s80
	v_add3_u32 v2, v2, v5, s80
	v_and_b32_e32 v3, 0xffff0000, v3
	v_and_b32_e32 v2, 0xffff0000, v2
	v_or_b32_sdwa v1, v3, v1 dst_sel:DWORD dst_unused:UNUSED_PAD src0_sel:DWORD src1_sel:WORD_1
	v_or_b32_sdwa v0, v2, v0 dst_sel:DWORD dst_unused:UNUSED_PAD src0_sel:DWORD src1_sel:WORD_1
	global_store_dwordx2 v[8:9], v[0:1], off offset:1536
	s_branch .LBB0_27

.LBB0_34:
	v_cmp_gt_i32_e32 vcc, 0, v40
	v_min_i32_e32 v0, 0x4000, v26
	v_mov_b32_e32 v2, s23
	v_mov_b32_e32 v3, s89
	v_ashrrev_i32_e32 v31, 13, v0
	v_cndmask_b32_e32 v1, 0, v27, vcc
	v_cndmask_b32_e32 v0, v40, v26, vcc
	v_cndmask_b32_e32 v3, v2, v3, vcc
	v_mov_b32_e32 v2, s22
	v_mov_b32_e32 v4, s88
	v_cndmask_b32_e32 v2, v2, v4, vcc
	v_lshlrev_b64 v[0:1], 12, v[0:1]
	v_lshl_add_u64 v[0:1], v[2:3], 0, v[0:1]
	v_lshl_add_u64 v[36:37], v[0:1], 0, v[192:193]
	global_load_dwordx4 v[12:15], v[36:37], off nt
	global_load_dwordx4 v[8:11], v[36:37], off offset:1024 nt
	global_load_dwordx4 v[4:7], v[36:37], off offset:2048 nt
	global_load_dwordx4 v[0:3], v[36:37], off offset:3072 nt
	global_load_dwordx2 v[56:57], v[28:29], off nt
	global_load_dwordx2 v[64:65], v[28:29], off offset:512 nt
	global_load_dwordx2 v[72:73], v[28:29], off offset:1024 nt
	global_load_dwordx2 v[80:81], v[28:29], off offset:1536 nt
	v_mul_hi_i32_i24_e32 v39, 0x6000, v31
	v_mul_i32_i24_e32 v38, 0x6000, v31
	v_lshl_add_u64 v[38:39], s[90:91], 0, v[38:39]
	s_waitcnt vmcnt(11)
	v_lshl_add_u64 v[52:53], v[38:39], 0, v[192:193]
	v_lshl_add_u64 v[76:77], v[52:53], 0, s[34:35]
	v_add_co_u32_e32 v52, vcc, s24, v52
	global_load_dwordx4 v[48:51], v[16:17], off
	s_nop 0
	v_addc_co_u32_e32 v53, vcc, 0, v53, vcc
	global_load_dwordx4 v[52:55], v[52:53], off
	s_mov_b32 s4, 0xf823c000
	v_add_u32_e32 v40, s20, v40
	v_lshl_add_u64 v[26:27], v[26:27], 0, s[20:21]
	s_waitcnt vmcnt(5)
	v_and_b32_e32 v39, 0xffff0000, v56
	s_waitcnt vmcnt(4)
	v_and_b32_e32 v85, 0xffff0000, v64
	v_lshlrev_b32_e32 v38, 16, v56
	v_lshlrev_b32_e32 v84, 16, v64
	v_mov_b32_e32 v66, v39
	v_mov_b32_e32 v67, v85
	v_lshlrev_b32_e32 v82, 16, v57
	v_and_b32_e32 v87, 0xffff0000, v65
	v_lshlrev_b32_e32 v86, 16, v65
	v_mov_b32_e32 v64, v38
	v_mov_b32_e32 v65, v84
	v_pk_mul_f32 v[66:67], v[66:67], v[66:67]
	v_and_b32_e32 v83, 0xffff0000, v57
	global_load_dwordx4 v[56:59], v[16:17], off offset:1024
	global_load_dwordx4 v[60:63], v[76:77], off offset:1024
	v_pk_fma_f32 v[64:65], v[64:65], v[64:65], v[66:67]
	v_mov_b32_e32 v66, v82
	v_mov_b32_e32 v67, v86
	v_mov_b32_e32 v68, v83
	v_mov_b32_e32 v69, v87
	v_pk_fma_f32 v[64:65], v[66:67], v[66:67], v[64:65]
	s_waitcnt vmcnt(5)
	v_and_b32_e32 v91, 0xffff0000, v72
	v_pk_fma_f32 v[88:89], v[68:69], v[68:69], v[64:65]
	global_load_dwordx4 v[64:67], v[16:17], off offset:2048
	global_load_dwordx4 v[68:71], v[76:77], off offset:2048
	v_lshlrev_b32_e32 v90, 16, v72
	v_and_b32_e32 v93, 0xffff0000, v73
	v_lshlrev_b32_e32 v92, 16, v73
	global_load_dwordx4 v[72:75], v[16:17], off offset:3072
	s_nop 0
	global_load_dwordx4 v[76:79], v[76:77], off offset:3072
	s_waitcnt vmcnt(8)
	v_and_b32_e32 v95, 0xffff0000, v80
	v_lshlrev_b32_e32 v94, 16, v80
	v_mov_b32_e32 v98, v91
	v_mov_b32_e32 v99, v95
	v_and_b32_e32 v97, 0xffff0000, v81
	v_lshlrev_b32_e32 v96, 16, v81
	v_mov_b32_e32 v80, v90
	v_mov_b32_e32 v81, v94
	v_pk_mul_f32 v[98:99], v[98:99], v[98:99]
	v_mov_b32_e32 v100, v93
	v_pk_fma_f32 v[80:81], v[80:81], v[80:81], v[98:99]
	v_mov_b32_e32 v98, v92
	v_mov_b32_e32 v99, v96
	v_mov_b32_e32 v101, v97
	v_pk_fma_f32 v[80:81], v[98:99], v[98:99], v[80:81]
	v_add_f32_e32 v33, v88, v89
	v_pk_fma_f32 v[80:81], v[100:101], v[100:101], v[80:81]
	s_nop 0
	v_add_f32_e32 v33, v33, v80
	v_add_f32_e32 v33, v33, v81
	s_nop 0
	s_nop 1
	v_add_f32_dpp v33, v33, v33 quad_perm:[1,0,3,2] row_mask:0xf bank_mask:0xf
	s_nop 1
	v_add_f32_dpp v33, v33, v33 quad_perm:[2,3,0,1] row_mask:0xf bank_mask:0xf
	s_nop 1
	v_add_f32_dpp v33, v33, v33 row_half_mirror row_mask:0xf bank_mask:0xf
	s_nop 1
	v_add_f32_dpp v33, v33, v33 row_mirror row_mask:0xf bank_mask:0xf
	s_nop 1
	v_mov_b32_e32 v35, v33
	s_nop 1
	v_permlane16_swap_b32_e32 v33, v35
	s_nop 1
	v_add_f32_e32 v33, v33, v35
	s_nop 1
	v_mov_b32_e32 v35, v33
	s_nop 1
	v_permlane32_swap_b32_e32 v33, v35
	s_nop 1
	v_add_f32_e32 v33, v33, v35
	s_nop 1
	v_fmamk_f32 v33, v33, 0x3a800000, v219
	v_cmp_gt_f32_e32 vcc, s25, v33
	v_mul_f32_e32 v35, 0x4b800000, v33
	s_nop 0
	v_cndmask_b32_e32 v33, v33, v35, vcc
	v_rsq_f32_e32 v33, v33
	s_nop 0
	v_mul_f32_e32 v35, 0x45800000, v33
	v_cndmask_b32_e32 v80, v33, v35, vcc
	v_pk_mul_f32 v[38:39], v[80:81], v[38:39] op_sel_hi:[0,1]
	s_waitcnt vmcnt(7)
	v_pk_mul_f32 v[38:39], v[48:49], v[38:39]
	v_pk_mul_f32 v[48:49], v[80:81], v[82:83] op_sel_hi:[0,1]
	v_pk_mul_f32 v[50:51], v[50:51], v[48:49]
	s_waitcnt vmcnt(6)
	v_pk_fma_f32 v[48:49], v[52:53], v[38:39], v[12:13]
	v_pk_mul_f32 v[12:13], v[80:81], v[84:85] op_sel_hi:[0,1]
	v_pk_fma_f32 v[50:51], v[54:55], v[50:51], v[14:15]
	s_waitcnt vmcnt(5)
	v_pk_mul_f32 v[12:13], v[56:57], v[12:13]
	v_pk_mul_f32 v[14:15], v[80:81], v[86:87] op_sel_hi:[0,1]
	v_pk_mul_f32 v[14:15], v[58:59], v[14:15]
	s_waitcnt vmcnt(4)
	v_pk_fma_f32 v[8:9], v[60:61], v[12:13], v[8:9]
	v_pk_mul_f32 v[12:13], v[80:81], v[90:91] op_sel_hi:[0,1]
	v_pk_fma_f32 v[10:11], v[62:63], v[14:15], v[10:11]
	s_waitcnt vmcnt(3)
	v_pk_mul_f32 v[12:13], v[12:13], v[64:65]
	v_pk_mul_f32 v[14:15], v[80:81], v[92:93] op_sel_hi:[0,1]
	v_pk_mul_f32 v[14:15], v[14:15], v[66:67]
	s_waitcnt vmcnt(2)
	v_pk_fma_f32 v[4:5], v[12:13], v[68:69], v[4:5]
	v_pk_mul_f32 v[12:13], v[80:81], v[94:95] op_sel_hi:[0,1]
	v_pk_fma_f32 v[6:7], v[14:15], v[70:71], v[6:7]
	s_waitcnt vmcnt(1)
	v_pk_mul_f32 v[12:13], v[12:13], v[72:73]
	v_pk_mul_f32 v[14:15], v[80:81], v[96:97] op_sel_hi:[0,1]
	v_pk_mul_f32 v[14:15], v[14:15], v[74:75]
	s_waitcnt vmcnt(0)
	v_pk_fma_f32 v[0:1], v[12:13], v[76:77], v[0:1]
	v_add_u32_e32 v12, 3, v31
	v_pk_fma_f32 v[2:3], v[14:15], v[78:79], v[2:3]
	global_store_dwordx4 v[36:37], v[48:51], off nt
	global_store_dwordx4 v[36:37], v[8:11], off offset:1024 nt
	global_store_dwordx4 v[36:37], v[4:7], off offset:2048 nt
	global_store_dwordx4 v[36:37], v[0:3], off offset:3072 nt
	v_mul_hi_i32_i24_e32 v13, 0x6000, v12
	v_mul_i32_i24_e32 v12, 0x6000, v12
	v_mov_b32_e32 v36, v49
	v_mov_b32_e32 v37, v9
	v_lshl_add_u64 v[14:15], s[96:97], 0, v[12:13]
	v_mov_b32_e32 v12, v48
	v_mov_b32_e32 v13, v8
	v_pk_mul_f32 v[36:37], v[36:37], v[36:37]
	v_mov_b32_e32 v38, v5
	v_pk_fma_f32 v[12:13], v[12:13], v[12:13], v[36:37]
	v_mov_b32_e32 v36, v50
	v_mov_b32_e32 v37, v10
	v_pk_fma_f32 v[12:13], v[36:37], v[36:37], v[12:13]
	v_mov_b32_e32 v36, v51
	v_mov_b32_e32 v37, v11
	v_mov_b32_e32 v39, v1
	v_pk_fma_f32 v[12:13], v[36:37], v[36:37], v[12:13]
	v_mov_b32_e32 v36, v4
	v_mov_b32_e32 v37, v0
	v_pk_mul_f32 v[38:39], v[38:39], v[38:39]
	v_add_f32_e32 v12, v12, v13
	v_pk_fma_f32 v[36:37], v[36:37], v[36:37], v[38:39]
	v_mov_b32_e32 v38, v6
	v_mov_b32_e32 v39, v2
	v_pk_fma_f32 v[36:37], v[38:39], v[38:39], v[36:37]
	v_mov_b32_e32 v38, v7
	v_mov_b32_e32 v39, v3
	v_pk_fma_f32 v[36:37], v[38:39], v[38:39], v[36:37]
	s_nop 0
	v_add_f32_e32 v12, v12, v36
	v_add_f32_e32 v12, v12, v37
	v_lshl_add_u64 v[36:37], v[14:15], 0, s[28:29]
	v_lshl_add_u64 v[38:39], v[36:37], 0, v[192:193]
	v_lshl_add_u64 v[14:15], v[14:15], 0, v[192:193]
	global_load_dwordx4 v[52:55], v[18:19], off
	global_load_dwordx4 v[56:59], v[38:39], off
	global_load_dwordx4 v[60:63], v[14:15], off
	v_mov_b32_e32 v38, v48
	v_mov_b32_e32 v39, v50
	v_mov_b32_e32 v50, v49
	s_nop 0
	s_nop 1
	v_add_f32_dpp v12, v12, v12 quad_perm:[1,0,3,2] row_mask:0xf bank_mask:0xf
	s_nop 1
	v_add_f32_dpp v12, v12, v12 quad_perm:[2,3,0,1] row_mask:0xf bank_mask:0xf
	s_nop 1
	v_add_f32_dpp v12, v12, v12 row_half_mirror row_mask:0xf bank_mask:0xf
	s_nop 1
	v_add_f32_dpp v12, v12, v12 row_mirror row_mask:0xf bank_mask:0xf
	s_nop 1
	v_mov_b32_e32 v13, v12
	s_nop 1
	v_permlane16_swap_b32_e32 v12, v13
	s_nop 1
	v_add_f32_e32 v12, v12, v13
	s_nop 1
	v_mov_b32_e32 v13, v12
	s_nop 1
	v_permlane32_swap_b32_e32 v12, v13
	s_nop 1
	v_add_f32_e32 v12, v12, v13
	s_nop 1
	v_fmamk_f32 v12, v12, 0x3a800000, v219
	v_cmp_gt_f32_e32 vcc, s25, v12
	v_mul_f32_e32 v13, 0x4b800000, v12
	s_waitcnt vmcnt(2)
	v_mov_b32_e32 v64, v52
	v_cndmask_b32_e32 v12, v12, v13, vcc
	v_rsq_f32_e32 v12, v12
	v_mov_b32_e32 v65, v54
	v_mov_b32_e32 v54, v53
	s_waitcnt vmcnt(0)
	v_mov_b32_e32 v67, v62
	v_mul_f32_e32 v13, 0x45800000, v12
	v_cndmask_b32_e32 v12, v12, v13, vcc
	v_pk_mul_f32 v[38:39], v[38:39], v[12:13] op_sel_hi:[1,0]
	v_pk_mul_f32 v[48:49], v[50:51], v[12:13] op_sel_hi:[1,0]
	v_pk_mul_f32 v[38:39], v[64:65], v[38:39]
	v_mov_b32_e32 v65, v58
	v_mov_b32_e32 v58, v57
	v_mov_b32_e32 v64, v56
	v_pk_mul_f32 v[48:49], v[54:55], v[48:49]
	v_pk_add_f32 v[50:51], v[58:59], 1.0 op_sel_hi:[1,0]
	v_mov_b32_e32 v62, v61
	v_pk_add_f32 v[64:65], v[64:65], 1.0 op_sel_hi:[1,0]
	v_mov_b32_e32 v66, v60
	v_pk_fma_f32 v[48:49], v[50:51], v[48:49], v[62:63]
	v_pk_fma_f32 v[38:39], v[64:65], v[38:39], v[66:67]
	v_and_b32_sdwa v33, v49, v218 dst_sel:DWORD dst_unused:UNUSED_PAD src0_sel:WORD_1 src1_sel:DWORD
	v_and_b32_sdwa v13, v39, v218 dst_sel:DWORD dst_unused:UNUSED_PAD src0_sel:WORD_1 src1_sel:DWORD
	v_cvt_pk_bf16_f32 v38, v38, v48
	v_add3_u32 v33, v49, v33, s80
	v_add3_u32 v13, v39, v13, s80
	v_and_b32_e32 v33, 0xffff0000, v33
	v_add_co_u32_e32 v48, vcc, s4, v28
	v_or_b32_sdwa v39, v33, v13 dst_sel:DWORD dst_unused:UNUSED_PAD src0_sel:DWORD src1_sel:WORD_1
	s_nop 0
	v_addc_co_u32_e32 v49, vcc, -1, v29, vcc
	global_store_dwordx2 v[48:49], v[38:39], off
	v_mov_b32_e32 v31, v193
	v_lshl_add_u64 v[38:39], v[36:37], 0, v[30:31]
	global_load_dwordx4 v[48:51], v[20:21], off
	global_load_dwordx4 v[52:55], v[38:39], off
	global_load_dwordx4 v[56:59], v[14:15], off offset:1024
	v_mov_b32_e32 v38, v8
	v_mov_b32_e32 v39, v10
	v_pk_mul_f32 v[38:39], v[38:39], v[12:13] op_sel_hi:[1,0]
	v_mov_b32_e32 v10, v9
	v_pk_mul_f32 v[8:9], v[10:11], v[12:13] op_sel_hi:[1,0]
	s_mov_b32 s4, 0xf823d000
	v_mov_b32_e32 v33, v193
	v_mov_b32_e32 v35, v193
	s_waitcnt vmcnt(2)
	v_mov_b32_e32 v60, v48
	v_mov_b32_e32 v61, v50
	v_pk_mul_f32 v[38:39], v[38:39], v[60:61]
	s_waitcnt vmcnt(1)
	v_mov_b32_e32 v60, v52
	v_mov_b32_e32 v61, v54
	v_pk_add_f32 v[60:61], v[60:61], 1.0 op_sel_hi:[1,0]
	s_waitcnt vmcnt(0)
	v_mov_b32_e32 v62, v56
	v_mov_b32_e32 v63, v58
	v_mov_b32_e32 v50, v49
	v_mov_b32_e32 v54, v53
	v_pk_fma_f32 v[38:39], v[38:39], v[60:61], v[62:63]
	v_pk_mul_f32 v[8:9], v[8:9], v[50:51]
	v_pk_add_f32 v[10:11], v[54:55], 1.0 op_sel_hi:[1,0]
	v_mov_b32_e32 v58, v57
	v_pk_fma_f32 v[8:9], v[8:9], v[10:11], v[58:59]
	v_and_b32_sdwa v11, v38, v218 dst_sel:DWORD dst_unused:UNUSED_PAD src0_sel:WORD_1 src1_sel:DWORD
	v_add3_u32 v13, v38, v11, s80
	v_and_b32_sdwa v31, v8, v218 dst_sel:DWORD dst_unused:UNUSED_PAD src0_sel:WORD_1 src1_sel:DWORD
	v_cvt_pk_bf16_f32 v11, v39, v9
	v_add3_u32 v8, v8, v31, s80
	v_and_b32_e32 v8, 0xffff0000, v8
	v_or_b32_sdwa v10, v8, v13 dst_sel:DWORD dst_unused:UNUSED_PAD src0_sel:DWORD src1_sel:WORD_1
	v_add_co_u32_e32 v8, vcc, s4, v28
	s_nop 1
	v_addc_co_u32_e32 v9, vcc, -1, v29, vcc
	global_store_dwordx2 v[8:9], v[10:11], off offset:-3584
	v_lshl_add_u64 v[10:11], v[36:37], 0, v[32:33]
	global_load_dwordx4 v[48:51], v[22:23], off
	global_load_dwordx4 v[52:55], v[10:11], off
	global_load_dwordx4 v[56:59], v[14:15], off offset:2048
	v_mov_b32_e32 v10, v4
	v_mov_b32_e32 v11, v6
	v_pk_mul_f32 v[10:11], v[10:11], v[12:13] op_sel_hi:[1,0]
	v_mov_b32_e32 v6, v5
	v_pk_mul_f32 v[4:5], v[6:7], v[12:13] op_sel_hi:[1,0]
	v_cmp_lt_i32_e32 vcc, s26, v40
	v_lshl_add_u64 v[28:29], v[28:29], 0, s[30:31]
	s_or_b64 s[2:3], vcc, s[2:3]
	s_waitcnt vmcnt(2)
	v_mov_b32_e32 v38, v48
	v_mov_b32_e32 v39, v50
	v_pk_mul_f32 v[10:11], v[10:11], v[38:39]
	s_waitcnt vmcnt(1)
	v_mov_b32_e32 v38, v52
	v_mov_b32_e32 v39, v54
	v_pk_add_f32 v[38:39], v[38:39], 1.0 op_sel_hi:[1,0]
	s_waitcnt vmcnt(0)
	v_mov_b32_e32 v60, v56
	v_mov_b32_e32 v61, v58
	v_mov_b32_e32 v50, v49
	v_mov_b32_e32 v54, v53
	v_pk_fma_f32 v[10:11], v[10:11], v[38:39], v[60:61]
	v_pk_mul_f32 v[4:5], v[4:5], v[50:51]
	v_pk_add_f32 v[6:7], v[54:55], 1.0 op_sel_hi:[1,0]
	v_mov_b32_e32 v58, v57
	v_pk_fma_f32 v[4:5], v[4:5], v[6:7], v[58:59]
	v_cvt_pk_bf16_f32 v4, v10, v4
	v_cvt_pk_bf16_f32 v5, v11, v5
	global_store_dwordx2 v[8:9], v[4:5], off offset:-3072
	v_lshl_add_u64 v[10:11], v[36:37], 0, v[34:35]
	global_load_dwordx4 v[4:7], v[24:25], off
	global_load_dwordx4 v[36:39], v[10:11], off
	global_load_dwordx4 v[48:51], v[14:15], off offset:3072
	v_mov_b32_e32 v10, v0
	v_mov_b32_e32 v11, v2
	v_pk_mul_f32 v[10:11], v[10:11], v[12:13] op_sel_hi:[1,0]
	v_mov_b32_e32 v2, v1
	v_pk_mul_f32 v[0:1], v[2:3], v[12:13] op_sel_hi:[1,0]
	s_waitcnt vmcnt(2)
	v_mov_b32_e32 v14, v4
	v_mov_b32_e32 v15, v6
	v_pk_mul_f32 v[10:11], v[10:11], v[14:15]
	s_waitcnt vmcnt(1)
	v_mov_b32_e32 v15, v38
	v_mov_b32_e32 v6, v5
	v_mov_b32_e32 v38, v37
	v_mov_b32_e32 v14, v36
	s_waitcnt vmcnt(0)
	v_mov_b32_e32 v53, v50
	v_pk_mul_f32 v[0:1], v[0:1], v[6:7]
	v_pk_add_f32 v[2:3], v[38:39], 1.0 op_sel_hi:[1,0]
	v_mov_b32_e32 v50, v49
	v_pk_add_f32 v[14:15], v[14:15], 1.0 op_sel_hi:[1,0]
	v_mov_b32_e32 v52, v48
	v_pk_fma_f32 v[0:1], v[0:1], v[2:3], v[50:51]
	v_pk_fma_f32 v[10:11], v[10:11], v[14:15], v[52:53]
	v_cvt_pk_bf16_f32 v1, v11, v1
	v_cvt_pk_bf16_f32 v0, v10, v0
	global_store_dwordx2 v[8:9], v[0:1], off offset:-2560
	s_andn2_b64 exec, exec, s[2:3]
	s_cbranch_execnz .LBB0_34

.LBB0_173:
	v_mov_b32_e32 v107, v193
	v_lshl_add_u64 v[28:29], v[0:1], 0, v[106:107]
	v_add_co_u32_e32 v4, vcc, 0x1000, v28
	v_min_i32_e32 v2, 0x4000, v104
	s_nop 0
	v_addc_co_u32_e32 v5, vcc, 0, v29, vcc
	v_ashrrev_i32_e32 v2, 13, v2
	v_add_co_u32_e32 v24, vcc, 0x2000, v28
	v_add_u32_e32 v2, s4, v2
	s_nop 0
	v_addc_co_u32_e32 v25, vcc, 0, v29, vcc
	v_mul_hi_i32_i24_e32 v123, 0x6000, v2
	v_mul_i32_i24_e32 v122, 0x6000, v2
	global_load_dwordx4 v[32:35], v[28:29], off nt
	global_load_dwordx4 v[16:19], v[28:29], off offset:1024 nt
	global_load_dwordx4 v[8:11], v[28:29], off offset:2048 nt
	global_load_dwordx4 v[0:3], v[28:29], off offset:3072 nt
	v_add_co_u32_e32 v28, vcc, 0x3000, v28
	v_lshlrev_b64 v[120:121], 11, v[104:105]
	s_nop 0
	v_addc_co_u32_e32 v29, vcc, 0, v29, vcc
	s_waitcnt vmcnt(4)
	v_lshl_add_u64 v[66:67], v[96:97], 0, v[120:121]
	global_load_dwordx4 v[36:39], v[4:5], off nt
	global_load_dwordx4 v[20:23], v[4:5], off offset:1024 nt
	global_load_dwordx4 v[12:15], v[4:5], off offset:2048 nt
	s_nop 0
	global_load_dwordx4 v[4:7], v[4:5], off offset:3072 nt
	s_nop 0
	global_load_dwordx4 v[60:63], v[24:25], off nt
	global_load_dwordx4 v[56:59], v[24:25], off offset:1024 nt
	global_load_dwordx4 v[40:43], v[24:25], off offset:2048 nt
	s_nop 0
	global_load_dwordx4 v[24:27], v[24:25], off offset:3072 nt
	s_nop 0
	global_load_dwordx4 v[52:55], v[28:29], off nt
	global_load_dwordx4 v[48:51], v[28:29], off offset:1024 nt
	global_load_dwordx4 v[44:47], v[28:29], off offset:2048 nt
	s_nop 0
	global_load_dwordx4 v[28:31], v[28:29], off offset:3072 nt
	s_nop 0
	global_load_dwordx2 v[72:73], v[66:67], off nt
	global_load_dwordx2 v[80:81], v[66:67], off offset:512 nt
	global_load_dwordx2 v[88:89], v[66:67], off offset:1024 nt
	global_load_dwordx2 v[126:127], v[66:67], off offset:1536 nt
	v_add_u32_e32 v66, 1, v104
	v_ashrrev_i32_e32 v67, 31, v66
	v_lshlrev_b64 v[118:119], 11, v[66:67]
	v_lshl_add_u64 v[66:67], v[96:97], 0, v[118:119]
	global_load_dwordx2 v[74:75], v[66:67], off nt
	global_load_dwordx2 v[82:83], v[66:67], off offset:512 nt
	global_load_dwordx2 v[90:91], v[66:67], off offset:1024 nt
	global_load_dwordx2 v[162:163], v[66:67], off offset:1536 nt
	v_add_u32_e32 v66, 2, v104
	v_ashrrev_i32_e32 v67, 31, v66
	v_lshlrev_b64 v[116:117], 11, v[66:67]
	v_lshl_add_u64 v[66:67], v[96:97], 0, v[116:117]
	global_load_dwordx2 v[76:77], v[66:67], off nt
	global_load_dwordx2 v[84:85], v[66:67], off offset:512 nt
	global_load_dwordx2 v[92:93], v[66:67], off offset:1024 nt
	global_load_dwordx2 v[132:133], v[66:67], off offset:1536 nt
	v_add_u32_e32 v66, 3, v104
	v_ashrrev_i32_e32 v67, 31, v66
	v_lshlrev_b64 v[114:115], 11, v[66:67]
	v_lshl_add_u64 v[66:67], v[96:97], 0, v[114:115]
	global_load_dwordx2 v[78:79], v[66:67], off nt
	global_load_dwordx2 v[86:87], v[66:67], off offset:512 nt
	global_load_dwordx2 v[178:179], v[66:67], off offset:1024 nt
	global_load_dwordx2 v[138:139], v[66:67], off offset:1536 nt
	v_lshl_add_u64 v[64:65], s[90:91], 0, v[122:123]
	v_lshl_add_u64 v[68:69], v[64:65], 0, v[106:107]
	s_mov_b64 s[0:1], 0x345a000
	v_lshl_add_u64 v[94:95], v[68:69], 0, s[0:1]
	s_mov_b32 s0, 0x345a000
	v_add_co_u32_e32 v68, vcc, s0, v68
	global_load_dwordx4 v[64:67], v[98:99], off
	s_nop 0
	v_addc_co_u32_e32 v69, vcc, 0, v69, vcc
	global_load_dwordx4 v[68:71], v[68:69], off
	s_mov_b32 s0, 0x358637bd
	s_mov_b32 s8, 0x3a800000
	s_mov_b32 s6, 0x800000
	v_mov_b32_e32 v111, v193
	v_mov_b32_e32 v113, v193
	s_add_i32 s5, s5, s93
	s_cmpk_gt_i32 s5, 0x3ff
	s_waitcnt vmcnt(17)
	v_and_b32_e32 v157, 0xffff0000, v72
	s_waitcnt vmcnt(16)
	v_and_b32_e32 v175, 0xffff0000, v80
	v_lshlrev_b32_e32 v156, 16, v72
	v_lshlrev_b32_e32 v174, 16, v80
	v_mov_b32_e32 v140, v157
	v_mov_b32_e32 v141, v175
	v_lshlrev_b32_e32 v168, 16, v73
	v_and_b32_e32 v177, 0xffff0000, v81
	v_lshlrev_b32_e32 v176, 16, v81
	v_mov_b32_e32 v80, v156
	v_mov_b32_e32 v81, v174
	v_pk_mul_f32 v[140:141], v[140:141], v[140:141]
	v_and_b32_e32 v169, 0xffff0000, v73
	s_waitcnt vmcnt(13)
	v_and_b32_e32 v165, 0xffff0000, v74
	v_pk_fma_f32 v[80:81], v[80:81], v[80:81], v[140:141]
	v_mov_b32_e32 v140, v168
	v_mov_b32_e32 v141, v176
	s_waitcnt vmcnt(12)
	v_and_b32_e32 v171, 0xffff0000, v82
	v_lshlrev_b32_e32 v164, 16, v74
	v_mov_b32_e32 v142, v169
	v_mov_b32_e32 v143, v177
	v_pk_fma_f32 v[80:81], v[140:141], v[140:141], v[80:81]
	v_lshlrev_b32_e32 v170, 16, v82
	v_and_b32_e32 v173, 0xffff0000, v83
	v_lshlrev_b32_e32 v172, 16, v83
	v_mov_b32_e32 v82, v165
	v_mov_b32_e32 v83, v171
	v_lshlrev_b32_e32 v166, 16, v75
	v_pk_fma_f32 v[188:189], v[142:143], v[142:143], v[80:81]
	v_mov_b32_e32 v80, v164
	v_mov_b32_e32 v81, v170
	v_pk_mul_f32 v[82:83], v[82:83], v[82:83]
	v_and_b32_e32 v167, 0xffff0000, v75
	s_waitcnt vmcnt(9)
	v_and_b32_e32 v137, 0xffff0000, v76
	v_pk_fma_f32 v[80:81], v[80:81], v[80:81], v[82:83]
	v_mov_b32_e32 v82, v166
	v_mov_b32_e32 v83, v172
	s_waitcnt vmcnt(8)
	v_and_b32_e32 v147, 0xffff0000, v84
	v_lshlrev_b32_e32 v136, 16, v76
	v_mov_b32_e32 v140, v167
	v_mov_b32_e32 v141, v173
	v_pk_fma_f32 v[80:81], v[82:83], v[82:83], v[80:81]
	v_lshlrev_b32_e32 v146, 16, v84
	v_mov_b32_e32 v82, v137
	v_mov_b32_e32 v83, v147
	v_lshlrev_b32_e32 v134, 16, v77
	v_pk_fma_f32 v[190:191], v[140:141], v[140:141], v[80:81]
	v_lshlrev_b32_e32 v144, 16, v85
	v_mov_b32_e32 v80, v136
	v_mov_b32_e32 v81, v146
	v_pk_mul_f32 v[82:83], v[82:83], v[82:83]
	v_and_b32_e32 v135, 0xffff0000, v77
	s_waitcnt vmcnt(5)
	v_and_b32_e32 v131, 0xffff0000, v78
	v_and_b32_e32 v145, 0xffff0000, v85
	v_pk_fma_f32 v[80:81], v[80:81], v[80:81], v[82:83]
	v_mov_b32_e32 v82, v134
	v_mov_b32_e32 v83, v144
	s_waitcnt vmcnt(4)
	v_and_b32_e32 v143, 0xffff0000, v86
	v_lshlrev_b32_e32 v130, 16, v78
	v_and_b32_e32 v129, 0xffff0000, v79
	v_lshlrev_b32_e32 v128, 16, v79
	global_load_dwordx4 v[72:75], v[98:99], off offset:1024
	global_load_dwordx4 v[76:79], v[94:95], off offset:1024
	v_mov_b32_e32 v84, v135
	v_mov_b32_e32 v85, v145
	v_pk_fma_f32 v[80:81], v[82:83], v[82:83], v[80:81]
	v_lshlrev_b32_e32 v142, 16, v86
	v_mov_b32_e32 v82, v131
	v_mov_b32_e32 v83, v143
	v_pk_fma_f32 v[158:159], v[84:85], v[84:85], v[80:81]
	v_lshlrev_b32_e32 v140, 16, v87
	v_mov_b32_e32 v80, v130
	v_mov_b32_e32 v81, v142
	v_pk_mul_f32 v[82:83], v[82:83], v[82:83]
	v_and_b32_e32 v141, 0xffff0000, v87
	v_pk_fma_f32 v[80:81], v[80:81], v[80:81], v[82:83]
	v_mov_b32_e32 v82, v128
	v_mov_b32_e32 v83, v140
	v_mov_b32_e32 v84, v129
	v_mov_b32_e32 v85, v141
	v_pk_fma_f32 v[80:81], v[82:83], v[82:83], v[80:81]
	v_and_b32_e32 v185, 0xffff0000, v88
	v_pk_fma_f32 v[160:161], v[84:85], v[84:85], v[80:81]
	global_load_dwordx4 v[80:83], v[98:99], off offset:2048
	global_load_dwordx4 v[84:87], v[94:95], off offset:2048
	v_lshlrev_b32_e32 v184, 16, v88
	v_and_b32_e32 v187, 0xffff0000, v89
	v_lshlrev_b32_e32 v186, 16, v89
	v_and_b32_e32 v181, 0xffff0000, v90
	v_lshlrev_b32_e32 v180, 16, v90
	v_and_b32_e32 v183, 0xffff0000, v91
	v_lshlrev_b32_e32 v182, 16, v91
	v_and_b32_e32 v155, 0xffff0000, v92
	v_lshlrev_b32_e32 v154, 16, v92
	v_and_b32_e32 v153, 0xffff0000, v93
	v_lshlrev_b32_e32 v152, 16, v93
	global_load_dwordx4 v[88:91], v[98:99], off offset:3072
	s_nop 0
	global_load_dwordx4 v[92:95], v[94:95], off offset:3072
	v_and_b32_e32 v205, 0xffff0000, v126
	s_waitcnt vmcnt(9)
	v_and_b32_e32 v151, 0xffff0000, v178
	v_lshlrev_b32_e32 v150, 16, v178
	v_and_b32_e32 v149, 0xffff0000, v179
	v_lshlrev_b32_e32 v148, 16, v179
	v_lshlrev_b32_e32 v204, 16, v126
	v_mov_b32_e32 v178, v185
	v_mov_b32_e32 v179, v205
	v_and_b32_e32 v225, 0xffff0000, v127
	v_lshlrev_b32_e32 v224, 16, v127
	v_mov_b32_e32 v126, v184
	v_mov_b32_e32 v127, v204
	v_pk_mul_f32 v[178:179], v[178:179], v[178:179]
	v_mov_b32_e32 v194, v187
	v_pk_fma_f32 v[126:127], v[126:127], v[126:127], v[178:179]
	v_mov_b32_e32 v178, v186
	v_mov_b32_e32 v179, v224
	v_pk_fma_f32 v[126:127], v[178:179], v[178:179], v[126:127]
	v_and_b32_e32 v179, 0xffff0000, v162
	v_mov_b32_e32 v195, v225
	v_lshlrev_b32_e32 v178, 16, v162
	v_mov_b32_e32 v232, v181
	v_mov_b32_e32 v233, v179
	v_pk_fma_f32 v[126:127], v[194:195], v[194:195], v[126:127]
	v_and_b32_e32 v195, 0xffff0000, v163
	v_lshlrev_b32_e32 v194, 16, v163
	v_mov_b32_e32 v162, v180
	v_mov_b32_e32 v163, v178
	v_pk_mul_f32 v[232:233], v[232:233], v[232:233]
	v_mov_b32_e32 v234, v183
	v_pk_fma_f32 v[162:163], v[162:163], v[162:163], v[232:233]
	v_mov_b32_e32 v232, v182
	v_mov_b32_e32 v233, v194
	v_mov_b32_e32 v235, v195
	v_pk_fma_f32 v[162:163], v[232:233], v[232:233], v[162:163]
	v_mov_b32_e32 v232, v190
	v_pk_fma_f32 v[162:163], v[234:235], v[234:235], v[162:163]
	v_mov_b32_e32 v233, v188
	v_mov_b32_e32 v188, v191
	v_pk_add_f32 v[188:189], v[232:233], v[188:189]
	v_mov_b32_e32 v190, v162
	v_mov_b32_e32 v191, v126
	v_pk_add_f32 v[188:189], v[188:189], v[190:191]
	v_mov_b32_e32 v126, v163
	v_pk_add_f32 v[126:127], v[188:189], v[126:127]
	v_mov_b32_e32 v163, v127
	v_mov_b32_e32 v162, v126
	s_nop 0
	v_add_f32_dpp v163, v163, v163 quad_perm:[1,0,3,2] row_mask:0xf bank_mask:0xf
	v_add_f32_dpp v162, v162, v162 quad_perm:[1,0,3,2] row_mask:0xf bank_mask:0xf
	s_nop 0
	v_add_f32_dpp v163, v163, v163 quad_perm:[2,3,0,1] row_mask:0xf bank_mask:0xf
	v_add_f32_dpp v162, v162, v162 quad_perm:[2,3,0,1] row_mask:0xf bank_mask:0xf
	s_nop 0
	v_add_f32_dpp v163, v163, v163 row_half_mirror row_mask:0xf bank_mask:0xf
	v_add_f32_dpp v162, v162, v162 row_half_mirror row_mask:0xf bank_mask:0xf
	s_nop 0
	v_add_f32_dpp v163, v163, v163 row_mirror row_mask:0xf bank_mask:0xf
	v_add_f32_dpp v162, v162, v162 row_mirror row_mask:0xf bank_mask:0xf
	s_nop 0
	v_mov_b32_e32 v127, v163
	v_mov_b32_e32 v126, v162
	s_nop 0
	v_permlane16_swap_b32_e32 v163, v127
	v_permlane16_swap_b32_e32 v162, v126
	s_nop 0
	v_add_f32_e32 v163, v163, v127
	v_add_f32_e32 v162, v162, v126
	s_nop 0
	v_mov_b32_e32 v127, v163
	v_mov_b32_e32 v126, v162
	s_nop 0
	v_permlane32_swap_b32_e32 v163, v127
	v_permlane32_swap_b32_e32 v162, v126
	s_nop 0
	v_add_f32_e32 v163, v163, v127
	v_add_f32_e32 v162, v162, v126
	s_nop 0
	v_mov_b64_e32 v[126:127], s[0:1]
	v_pk_fma_f32 v[162:163], v[162:163], s[8:9], v[126:127] op_sel_hi:[1,0,0]
	s_nop 0
	v_mul_f32_e32 v105, 0x4b800000, v163
	v_cmp_gt_f32_e64 s[0:1], s6, v163
	v_cmp_gt_f32_e32 vcc, s6, v162
	s_nop 0
	v_cndmask_b32_e64 v105, v163, v105, s[0:1]
	v_rsq_f32_e32 v105, v105
	s_nop 0
	v_mul_f32_e32 v109, 0x45800000, v105
	v_cndmask_b32_e64 v188, v105, v109, s[0:1]
	v_pk_mul_f32 v[156:157], v[188:189], v[156:157] op_sel_hi:[0,1]
	s_waitcnt vmcnt(7)
	v_pk_mul_f32 v[156:157], v[156:157], v[64:65]
	v_mul_f32_e32 v105, 0x4b800000, v162
	s_waitcnt vmcnt(6)
	v_pk_fma_f32 v[32:33], v[156:157], v[68:69], v[32:33]
	v_pk_mul_f32 v[156:157], v[188:189], v[168:169] op_sel_hi:[0,1]
	v_pk_mul_f32 v[156:157], v[156:157], v[66:67]
	v_cndmask_b32_e32 v105, v162, v105, vcc
	v_pk_fma_f32 v[34:35], v[156:157], v[70:71], v[34:35]
	v_pk_mul_f32 v[156:157], v[188:189], v[174:175] op_sel_hi:[0,1]
	s_waitcnt vmcnt(5)
	v_pk_mul_f32 v[156:157], v[156:157], v[72:73]
	v_rsq_f32_e32 v105, v105
	s_waitcnt vmcnt(4)
	v_pk_fma_f32 v[16:17], v[156:157], v[76:77], v[16:17]
	v_pk_mul_f32 v[156:157], v[188:189], v[176:177] op_sel_hi:[0,1]
	v_pk_mul_f32 v[156:157], v[156:157], v[74:75]
	v_mul_f32_e32 v109, 0x45800000, v105
	v_pk_fma_f32 v[18:19], v[156:157], v[78:79], v[18:19]
	v_pk_mul_f32 v[156:157], v[188:189], v[184:185] op_sel_hi:[0,1]
	s_waitcnt vmcnt(3)
	v_pk_mul_f32 v[156:157], v[156:157], v[80:81]
	v_mov_b32_e32 v168, v151
	s_waitcnt vmcnt(2)
	v_pk_fma_f32 v[8:9], v[156:157], v[84:85], v[8:9]
	v_pk_mul_f32 v[156:157], v[188:189], v[186:187] op_sel_hi:[0,1]
	v_pk_mul_f32 v[156:157], v[156:157], v[82:83]
	s_nop 0
	v_pk_fma_f32 v[10:11], v[156:157], v[86:87], v[10:11]
	v_pk_mul_f32 v[156:157], v[188:189], v[204:205] op_sel_hi:[0,1]
	s_waitcnt vmcnt(1)
	v_pk_mul_f32 v[156:157], v[156:157], v[88:89]
	s_waitcnt vmcnt(0)
	v_pk_fma_f32 v[0:1], v[156:157], v[92:93], v[0:1]
	v_pk_mul_f32 v[156:157], v[188:189], v[224:225] op_sel_hi:[0,1]
	v_pk_mul_f32 v[156:157], v[156:157], v[90:91]
	s_nop 0
	v_pk_fma_f32 v[2:3], v[156:157], v[94:95], v[2:3]
	v_cndmask_b32_e32 v156, v105, v109, vcc
	v_pk_mul_f32 v[162:163], v[156:157], v[164:165] op_sel_hi:[0,1]
	v_pk_mul_f32 v[162:163], v[162:163], v[64:65]
	v_and_b32_e32 v165, 0xffff0000, v133
	v_pk_fma_f32 v[36:37], v[162:163], v[68:69], v[36:37]
	v_pk_mul_f32 v[162:163], v[156:157], v[166:167] op_sel_hi:[0,1]
	v_pk_mul_f32 v[162:163], v[162:163], v[66:67]
	v_lshlrev_b32_e32 v164, 16, v133
	v_pk_fma_f32 v[38:39], v[162:163], v[70:71], v[38:39]
	v_pk_mul_f32 v[162:163], v[156:157], v[170:171] op_sel_hi:[0,1]
	v_pk_mul_f32 v[162:163], v[162:163], v[72:73]
	v_mov_b32_e32 v166, v153
	v_pk_fma_f32 v[20:21], v[162:163], v[76:77], v[20:21]
	v_pk_mul_f32 v[162:163], v[156:157], v[172:173] op_sel_hi:[0,1]
	v_pk_mul_f32 v[162:163], v[162:163], v[74:75]
	v_mov_b32_e32 v167, v165
	v_pk_fma_f32 v[22:23], v[162:163], v[78:79], v[22:23]
	v_pk_mul_f32 v[162:163], v[156:157], v[180:181] op_sel_hi:[0,1]
	v_pk_mul_f32 v[162:163], v[162:163], v[80:81]
	v_mov_b32_e32 v170, v149
	v_pk_fma_f32 v[12:13], v[162:163], v[84:85], v[12:13]
	v_pk_mul_f32 v[162:163], v[156:157], v[182:183] op_sel_hi:[0,1]
	v_pk_mul_f32 v[162:163], v[162:163], v[82:83]
	s_nop 0
	v_pk_fma_f32 v[14:15], v[162:163], v[86:87], v[14:15]
	v_pk_mul_f32 v[162:163], v[156:157], v[178:179] op_sel_hi:[0,1]
	v_pk_mul_f32 v[162:163], v[162:163], v[88:89]
	v_pk_mul_f32 v[156:157], v[156:157], v[194:195] op_sel_hi:[0,1]
	v_pk_fma_f32 v[4:5], v[162:163], v[92:93], v[4:5]
	v_pk_mul_f32 v[156:157], v[156:157], v[90:91]
	v_and_b32_e32 v163, 0xffff0000, v132
	v_pk_fma_f32 v[6:7], v[156:157], v[94:95], v[6:7]
	v_lshlrev_b32_e32 v162, 16, v132
	v_mov_b32_e32 v156, v155
	v_mov_b32_e32 v157, v163
	v_mov_b32_e32 v132, v154
	v_mov_b32_e32 v133, v162
	v_pk_mul_f32 v[156:157], v[156:157], v[156:157]
	s_nop 0
	v_pk_fma_f32 v[132:133], v[132:133], v[132:133], v[156:157]
	v_mov_b32_e32 v156, v152
	v_mov_b32_e32 v157, v164
	v_pk_fma_f32 v[132:133], v[156:157], v[156:157], v[132:133]
	v_and_b32_e32 v157, 0xffff0000, v138
	v_lshlrev_b32_e32 v156, 16, v138
	v_mov_b32_e32 v169, v157
	v_pk_fma_f32 v[166:167], v[166:167], v[166:167], v[132:133]
	v_and_b32_e32 v133, 0xffff0000, v139
	v_lshlrev_b32_e32 v132, 16, v139
	v_mov_b32_e32 v138, v150
	v_mov_b32_e32 v139, v156
	v_pk_mul_f32 v[168:169], v[168:169], v[168:169]
	v_mov_b32_e32 v171, v133
	v_pk_fma_f32 v[138:139], v[138:139], v[138:139], v[168:169]
	v_mov_b32_e32 v168, v148
	v_mov_b32_e32 v169, v132
	v_pk_fma_f32 v[138:139], v[168:169], v[168:169], v[138:139]
	v_mov_b32_e32 v168, v160
	v_pk_fma_f32 v[138:139], v[170:171], v[170:171], v[138:139]
	v_mov_b32_e32 v169, v158
	v_mov_b32_e32 v158, v161
	v_pk_add_f32 v[158:159], v[168:169], v[158:159]
	v_mov_b32_e32 v160, v138
	v_mov_b32_e32 v161, v166
	v_pk_add_f32 v[158:159], v[158:159], v[160:161]
	v_mov_b32_e32 v166, v139
	v_pk_add_f32 v[138:139], v[158:159], v[166:167]
	s_nop 0
	s_nop 1
	v_add_f32_dpp v139, v139, v139 quad_perm:[1,0,3,2] row_mask:0xf bank_mask:0xf
	v_add_f32_dpp v138, v138, v138 quad_perm:[1,0,3,2] row_mask:0xf bank_mask:0xf
	s_nop 0
	v_add_f32_dpp v139, v139, v139 quad_perm:[2,3,0,1] row_mask:0xf bank_mask:0xf
	v_add_f32_dpp v138, v138, v138 quad_perm:[2,3,0,1] row_mask:0xf bank_mask:0xf
	s_nop 0
	v_add_f32_dpp v139, v139, v139 row_half_mirror row_mask:0xf bank_mask:0xf
	v_add_f32_dpp v138, v138, v138 row_half_mirror row_mask:0xf bank_mask:0xf
	s_nop 0
	v_add_f32_dpp v139, v139, v139 row_mirror row_mask:0xf bank_mask:0xf
	v_add_f32_dpp v138, v138, v138 row_mirror row_mask:0xf bank_mask:0xf
	s_nop 0
	v_mov_b32_e32 v207, v139
	v_mov_b32_e32 v158, v138
	s_nop 0
	v_permlane16_swap_b32_e32 v139, v207
	v_permlane16_swap_b32_e32 v138, v158
	s_nop 0
	v_add_f32_e32 v139, v139, v207
	v_add_f32_e32 v138, v138, v158
	s_nop 0
	v_mov_b32_e32 v207, v139
	v_mov_b32_e32 v158, v138
	s_nop 0
	v_permlane32_swap_b32_e32 v139, v207
	v_permlane32_swap_b32_e32 v138, v158
	s_nop 0
	v_add_f32_e32 v139, v139, v207
	v_add_f32_e32 v138, v138, v158
	s_nop 0
	s_nop 0
	v_pk_fma_f32 v[138:139], v[138:139], s[8:9], v[126:127] op_sel_hi:[1,0,0]
	s_nop 0
	v_mul_f32_e32 v105, 0x4b800000, v139
	v_cmp_gt_f32_e64 s[0:1], s6, v139
	v_cmp_gt_f32_e32 vcc, s6, v138
	s_nop 0
	v_cndmask_b32_e64 v105, v139, v105, s[0:1]
	v_rsq_f32_e32 v105, v105
	s_nop 0
	v_mul_f32_e32 v109, 0x45800000, v105
	v_cndmask_b32_e64 v158, v105, v109, s[0:1]
	v_pk_mul_f32 v[134:135], v[158:159], v[134:135] op_sel_hi:[0,1]
	v_pk_mul_f32 v[134:135], v[66:67], v[134:135]
	v_mul_f32_e32 v105, 0x4b800000, v138
	v_pk_fma_f32 v[62:63], v[134:135], v[70:71], v[62:63]
	v_pk_mul_f32 v[134:135], v[158:159], v[146:147] op_sel_hi:[0,1]
	v_pk_mul_f32 v[134:135], v[134:135], v[72:73]
	v_cndmask_b32_e32 v105, v138, v105, vcc
	v_pk_fma_f32 v[56:57], v[134:135], v[76:77], v[56:57]
	v_pk_mul_f32 v[134:135], v[158:159], v[144:145] op_sel_hi:[0,1]
	v_pk_mul_f32 v[134:135], v[134:135], v[74:75]
	v_rsq_f32_e32 v105, v105
	v_pk_fma_f32 v[58:59], v[134:135], v[78:79], v[58:59]
	v_pk_mul_f32 v[134:135], v[158:159], v[154:155] op_sel_hi:[0,1]
	v_pk_mul_f32 v[134:135], v[134:135], v[80:81]
	v_mul_f32_e32 v109, 0x45800000, v105
	v_pk_fma_f32 v[40:41], v[134:135], v[84:85], v[40:41]
	v_pk_mul_f32 v[134:135], v[158:159], v[152:153] op_sel_hi:[0,1]
	v_pk_mul_f32 v[134:135], v[134:135], v[82:83]
	v_pk_mul_f32 v[136:137], v[158:159], v[136:137] op_sel_hi:[0,1]
	v_pk_fma_f32 v[42:43], v[134:135], v[86:87], v[42:43]
	v_pk_mul_f32 v[134:135], v[158:159], v[162:163] op_sel_hi:[0,1]
	v_pk_mul_f32 v[134:135], v[134:135], v[88:89]
	v_pk_mul_f32 v[136:137], v[64:65], v[136:137]
	v_pk_fma_f32 v[24:25], v[134:135], v[92:93], v[24:25]
	v_pk_mul_f32 v[134:135], v[158:159], v[164:165] op_sel_hi:[0,1]
	v_pk_mul_f32 v[134:135], v[134:135], v[90:91]
	s_movk_i32 s0, 0x1000
	v_pk_fma_f32 v[26:27], v[134:135], v[94:95], v[26:27]
	v_cndmask_b32_e32 v134, v105, v109, vcc
	v_pk_mul_f32 v[130:131], v[134:135], v[130:131] op_sel_hi:[0,1]
	v_pk_mul_f32 v[64:65], v[64:65], v[130:131]
	v_pk_fma_f32 v[60:61], v[68:69], v[136:137], v[60:61]
	v_pk_fma_f32 v[52:53], v[68:69], v[64:65], v[52:53]
	v_pk_mul_f32 v[64:65], v[134:135], v[128:129] op_sel_hi:[0,1]
	v_pk_mul_f32 v[64:65], v[66:67], v[64:65]
	v_mov_b32_e32 v109, v193
	v_pk_fma_f32 v[54:55], v[70:71], v[64:65], v[54:55]
	v_pk_mul_f32 v[64:65], v[134:135], v[142:143] op_sel_hi:[0,1]
	v_pk_mul_f32 v[64:65], v[72:73], v[64:65]
	v_mov_b32_e32 v70, v9
	v_pk_fma_f32 v[48:49], v[64:65], v[76:77], v[48:49]
	v_pk_mul_f32 v[64:65], v[134:135], v[140:141] op_sel_hi:[0,1]
	v_pk_mul_f32 v[64:65], v[64:65], v[74:75]
	v_mov_b32_e32 v71, v1
	v_pk_fma_f32 v[50:51], v[64:65], v[78:79], v[50:51]
	v_pk_mul_f32 v[64:65], v[134:135], v[150:151] op_sel_hi:[0,1]
	v_pk_mul_f32 v[64:65], v[64:65], v[80:81]
	v_pk_mul_f32 v[70:71], v[70:71], v[70:71]
	v_pk_fma_f32 v[44:45], v[64:65], v[84:85], v[44:45]
	v_pk_mul_f32 v[64:65], v[134:135], v[148:149] op_sel_hi:[0,1]
	v_pk_mul_f32 v[64:65], v[64:65], v[82:83]
	v_mov_b32_e32 v72, v37
	v_pk_fma_f32 v[46:47], v[64:65], v[86:87], v[46:47]
	v_pk_mul_f32 v[64:65], v[134:135], v[156:157] op_sel_hi:[0,1]
	v_pk_mul_f32 v[64:65], v[64:65], v[88:89]
	v_mov_b32_e32 v73, v21
	v_pk_fma_f32 v[28:29], v[64:65], v[92:93], v[28:29]
	v_pk_mul_f32 v[64:65], v[134:135], v[132:133] op_sel_hi:[0,1]
	v_pk_mul_f32 v[64:65], v[64:65], v[90:91]
	v_pk_mul_f32 v[72:73], v[72:73], v[72:73]
	v_pk_fma_f32 v[30:31], v[64:65], v[94:95], v[30:31]
	v_lshl_add_u64 v[64:65], v[124:125], 0, v[106:107]
	v_add_co_u32_e32 v66, vcc, s0, v64
	s_movk_i32 s0, 0x2000
	s_nop 0
	v_addc_co_u32_e32 v67, vcc, 0, v65, vcc
	v_add_co_u32_e32 v68, vcc, s0, v64
	global_store_dwordx4 v[64:65], v[32:35], off nt
	global_store_dwordx4 v[64:65], v[16:19], off offset:1024 nt
	global_store_dwordx4 v[64:65], v[8:11], off offset:2048 nt
	global_store_dwordx4 v[64:65], v[0:3], off offset:3072 nt
	v_addc_co_u32_e32 v69, vcc, 0, v65, vcc
	global_store_dwordx4 v[68:69], v[36:39], off offset:-4096 nt
	global_store_dwordx4 v[66:67], v[20:23], off offset:1024 nt
	global_store_dwordx4 v[66:67], v[12:15], off offset:2048 nt
	global_store_dwordx4 v[66:67], v[4:7], off offset:3072 nt
	global_store_dwordx4 v[68:69], v[60:63], off nt
	global_store_dwordx4 v[68:69], v[56:59], off offset:1024 nt
	global_store_dwordx4 v[68:69], v[40:43], off offset:2048 nt
	global_store_dwordx4 v[68:69], v[24:27], off offset:3072 nt
	v_mov_b32_e32 v68, v33
	v_mov_b32_e32 v69, v17
	v_mov_b32_e32 v66, v32
	v_mov_b32_e32 v67, v16
	v_pk_mul_f32 v[68:69], v[68:69], v[68:69]
	v_mov_b32_e32 v74, v13
	v_pk_fma_f32 v[66:67], v[66:67], v[66:67], v[68:69]
	v_mov_b32_e32 v68, v34
	v_mov_b32_e32 v69, v18
	v_pk_fma_f32 v[66:67], v[68:69], v[68:69], v[66:67]
	v_mov_b32_e32 v68, v35
	v_mov_b32_e32 v69, v19
	v_pk_fma_f32 v[66:67], v[68:69], v[68:69], v[66:67]
	v_mov_b32_e32 v68, v8
	v_mov_b32_e32 v69, v0
	v_pk_fma_f32 v[68:69], v[68:69], v[68:69], v[70:71]
	v_mov_b32_e32 v70, v10
	v_mov_b32_e32 v71, v2
	v_pk_fma_f32 v[68:69], v[70:71], v[70:71], v[68:69]
	v_mov_b32_e32 v70, v11
	v_mov_b32_e32 v71, v3
	v_pk_fma_f32 v[68:69], v[70:71], v[70:71], v[68:69]
	v_mov_b32_e32 v70, v36
	v_mov_b32_e32 v71, v20
	v_pk_fma_f32 v[70:71], v[70:71], v[70:71], v[72:73]
	v_mov_b32_e32 v72, v38
	v_mov_b32_e32 v73, v22
	v_pk_fma_f32 v[70:71], v[72:73], v[72:73], v[70:71]
	v_mov_b32_e32 v72, v39
	v_mov_b32_e32 v73, v23
	v_mov_b32_e32 v75, v5
	v_pk_fma_f32 v[70:71], v[72:73], v[72:73], v[70:71]
	v_mov_b32_e32 v72, v12
	v_mov_b32_e32 v73, v4
	v_pk_mul_f32 v[74:75], v[74:75], v[74:75]
	v_add_co_u32_e32 v64, vcc, s73, v64
	v_pk_fma_f32 v[72:73], v[72:73], v[72:73], v[74:75]
	v_mov_b32_e32 v74, v14
	v_mov_b32_e32 v75, v6
	v_pk_fma_f32 v[72:73], v[74:75], v[74:75], v[72:73]
	v_mov_b32_e32 v74, v15
	v_mov_b32_e32 v75, v7
	v_pk_fma_f32 v[72:73], v[74:75], v[74:75], v[72:73]
	v_mov_b32_e32 v74, v70
	v_mov_b32_e32 v75, v66
	v_mov_b32_e32 v66, v71
	v_pk_add_f32 v[66:67], v[74:75], v[66:67]
	v_mov_b32_e32 v70, v72
	v_mov_b32_e32 v71, v68
	v_pk_add_f32 v[66:67], v[66:67], v[70:71]
	v_mov_b32_e32 v68, v73
	v_pk_add_f32 v[66:67], v[66:67], v[68:69]
	v_addc_co_u32_e32 v65, vcc, 0, v65, vcc
	global_store_dwordx4 v[64:65], v[52:55], off nt
	global_store_dwordx4 v[64:65], v[48:51], off offset:1024 nt
	global_store_dwordx4 v[64:65], v[44:47], off offset:2048 nt
	global_store_dwordx4 v[64:65], v[28:31], off offset:3072 nt
	v_lshl_add_u64 v[64:65], s[96:97], 0, v[122:123]
	s_mov_b64 s[0:1], 0x3000
	v_lshl_add_u64 v[76:77], v[64:65], 0, s[0:1]
	v_mov_b32_e32 v70, v41
	v_mov_b32_e32 v71, v25
	v_pk_mul_f32 v[70:71], v[70:71], v[70:71]
	v_mov_b32_e32 v72, v53
	v_mov_b32_e32 v73, v49
	v_pk_mul_f32 v[72:73], v[72:73], v[72:73]
	v_mov_b32_e32 v74, v45
	v_mov_b32_e32 v75, v29
	v_pk_mul_f32 v[74:75], v[74:75], v[74:75]
	v_lshl_add_u64 v[86:87], v[102:103], 0, v[120:121]
	s_nop 0
	s_nop 1
	v_add_f32_dpp v67, v67, v67 quad_perm:[1,0,3,2] row_mask:0xf bank_mask:0xf
	v_add_f32_dpp v66, v66, v66 quad_perm:[1,0,3,2] row_mask:0xf bank_mask:0xf
	s_nop 0
	v_add_f32_dpp v67, v67, v67 quad_perm:[2,3,0,1] row_mask:0xf bank_mask:0xf
	v_add_f32_dpp v66, v66, v66 quad_perm:[2,3,0,1] row_mask:0xf bank_mask:0xf
	s_nop 0
	v_add_f32_dpp v67, v67, v67 row_half_mirror row_mask:0xf bank_mask:0xf
	v_add_f32_dpp v66, v66, v66 row_half_mirror row_mask:0xf bank_mask:0xf
	s_nop 0
	v_add_f32_dpp v67, v67, v67 row_mirror row_mask:0xf bank_mask:0xf
	v_add_f32_dpp v66, v66, v66 row_mirror row_mask:0xf bank_mask:0xf
	s_nop 0
	v_mov_b32_e32 v69, v67
	v_mov_b32_e32 v68, v66
	s_nop 0
	v_permlane16_swap_b32_e32 v67, v69
	v_permlane16_swap_b32_e32 v66, v68
	s_nop 0
	v_add_f32_e32 v67, v67, v69
	v_add_f32_e32 v66, v66, v68
	s_nop 0
	v_mov_b32_e32 v69, v67
	v_mov_b32_e32 v68, v66
	s_nop 0
	v_permlane32_swap_b32_e32 v67, v69
	v_permlane32_swap_b32_e32 v66, v68
	s_nop 0
	v_add_f32_e32 v67, v67, v69
	v_add_f32_e32 v66, v66, v68
	s_nop 0
	s_nop 0
	v_pk_fma_f32 v[66:67], v[66:67], s[8:9], v[126:127] op_sel_hi:[1,0,0]
	v_mov_b32_e32 v69, v57
	v_mul_f32_e32 v68, 0x4b800000, v67
	v_cmp_gt_f32_e64 s[0:1], s6, v67
	v_cmp_gt_f32_e32 vcc, s6, v66
	s_nop 0
	v_cndmask_b32_e64 v67, v67, v68, s[0:1]
	v_rsq_f32_e32 v67, v67
	s_nop 0
	v_mul_f32_e32 v68, 0x45800000, v67
	v_cndmask_b32_e64 v80, v67, v68, s[0:1]
	v_mul_f32_e32 v67, 0x4b800000, v66
	v_cndmask_b32_e32 v66, v66, v67, vcc
	v_rsq_f32_e32 v66, v66
	v_mov_b32_e32 v68, v61
	v_pk_mul_f32 v[68:69], v[68:69], v[68:69]
	v_mul_f32_e32 v67, 0x45800000, v66
	v_cndmask_b32_e32 v78, v66, v67, vcc
	v_mov_b32_e32 v66, v60
	v_mov_b32_e32 v67, v56
	v_pk_fma_f32 v[66:67], v[66:67], v[66:67], v[68:69]
	v_mov_b32_e32 v68, v62
	v_mov_b32_e32 v69, v58
	v_pk_fma_f32 v[66:67], v[68:69], v[68:69], v[66:67]
	v_mov_b32_e32 v68, v63
	v_mov_b32_e32 v69, v59
	v_pk_fma_f32 v[66:67], v[68:69], v[68:69], v[66:67]
	v_mov_b32_e32 v68, v40
	v_mov_b32_e32 v69, v24
	v_pk_fma_f32 v[68:69], v[68:69], v[68:69], v[70:71]
	v_mov_b32_e32 v70, v42
	v_mov_b32_e32 v71, v26
	v_pk_fma_f32 v[68:69], v[70:71], v[70:71], v[68:69]
	v_mov_b32_e32 v70, v43
	v_mov_b32_e32 v71, v27
	v_pk_fma_f32 v[68:69], v[70:71], v[70:71], v[68:69]
	v_mov_b32_e32 v70, v52
	v_mov_b32_e32 v71, v48
	v_pk_fma_f32 v[70:71], v[70:71], v[70:71], v[72:73]
	v_mov_b32_e32 v72, v54
	v_mov_b32_e32 v73, v50
	v_pk_fma_f32 v[70:71], v[72:73], v[72:73], v[70:71]
	v_mov_b32_e32 v72, v55
	v_mov_b32_e32 v73, v51
	v_pk_fma_f32 v[70:71], v[72:73], v[72:73], v[70:71]
	v_mov_b32_e32 v72, v44
	v_mov_b32_e32 v73, v28
	v_pk_fma_f32 v[72:73], v[72:73], v[72:73], v[74:75]
	v_mov_b32_e32 v74, v46
	v_mov_b32_e32 v75, v30
	v_pk_fma_f32 v[72:73], v[74:75], v[74:75], v[72:73]
	v_mov_b32_e32 v74, v47
	v_mov_b32_e32 v75, v31
	v_pk_fma_f32 v[72:73], v[74:75], v[74:75], v[72:73]
	v_mov_b32_e32 v74, v70
	v_mov_b32_e32 v75, v66
	v_mov_b32_e32 v66, v71
	v_pk_add_f32 v[66:67], v[74:75], v[66:67]
	v_mov_b32_e32 v70, v72
	v_mov_b32_e32 v71, v68
	v_pk_add_f32 v[66:67], v[66:67], v[70:71]
	v_mov_b32_e32 v68, v73
	v_pk_add_f32 v[66:67], v[66:67], v[68:69]
	v_lshl_add_u64 v[70:71], v[76:77], 0, v[106:107]
	s_nop 0
	s_nop 1
	v_add_f32_dpp v67, v67, v67 quad_perm:[1,0,3,2] row_mask:0xf bank_mask:0xf
	v_add_f32_dpp v66, v66, v66 quad_perm:[1,0,3,2] row_mask:0xf bank_mask:0xf
	s_nop 0
	v_add_f32_dpp v67, v67, v67 quad_perm:[2,3,0,1] row_mask:0xf bank_mask:0xf
	v_add_f32_dpp v66, v66, v66 quad_perm:[2,3,0,1] row_mask:0xf bank_mask:0xf
	s_nop 0
	v_add_f32_dpp v67, v67, v67 row_half_mirror row_mask:0xf bank_mask:0xf
	v_add_f32_dpp v66, v66, v66 row_half_mirror row_mask:0xf bank_mask:0xf
	s_nop 0
	v_add_f32_dpp v67, v67, v67 row_mirror row_mask:0xf bank_mask:0xf
	v_add_f32_dpp v66, v66, v66 row_mirror row_mask:0xf bank_mask:0xf
	s_nop 0
	v_mov_b32_e32 v69, v67
	v_mov_b32_e32 v68, v66
	s_nop 0
	v_permlane16_swap_b32_e32 v67, v69
	v_permlane16_swap_b32_e32 v66, v68
	s_nop 0
	v_add_f32_e32 v67, v67, v69
	v_add_f32_e32 v66, v66, v68
	s_nop 0
	v_mov_b32_e32 v69, v67
	v_mov_b32_e32 v68, v66
	s_nop 0
	v_permlane32_swap_b32_e32 v67, v69
	v_permlane32_swap_b32_e32 v66, v68
	s_nop 0
	v_add_f32_e32 v67, v67, v69
	v_add_f32_e32 v66, v66, v68
	s_nop 0
	s_nop 0
	v_pk_fma_f32 v[66:67], v[66:67], s[8:9], v[126:127] op_sel_hi:[1,0,0]
	s_nop 0
	v_mul_f32_e32 v68, 0x4b800000, v67
	v_cmp_gt_f32_e64 s[0:1], s6, v67
	v_cmp_gt_f32_e32 vcc, s6, v66
	s_nop 0
	v_cndmask_b32_e64 v67, v67, v68, s[0:1]
	v_rsq_f32_e32 v67, v67
	s_nop 0
	v_mul_f32_e32 v68, 0x45800000, v67
	v_cndmask_b32_e64 v84, v67, v68, s[0:1]
	v_mul_f32_e32 v67, 0x4b800000, v66
	v_cndmask_b32_e32 v66, v66, v67, vcc
	v_rsq_f32_e32 v66, v66
	s_mov_b64 s[0:1], 0x4000
	v_lshl_add_u64 v[88:89], v[64:65], 0, s[0:1]
	v_lshl_add_u64 v[68:69], v[88:89], 0, v[106:107]
	v_mul_f32_e32 v67, 0x45800000, v66
	v_cndmask_b32_e32 v82, v66, v67, vcc
	global_load_dwordx4 v[64:67], v[100:101], off
	global_load_dwordx4 v[72:75], v[68:69], off
	s_nop 0
	global_load_dwordx4 v[68:71], v[70:71], off
	v_readlane_b32 s0, v255, 7
	s_waitcnt vmcnt(2)
	v_mov_b32_e32 v93, v66
	s_waitcnt vmcnt(1)
	v_mov_b32_e32 v91, v74
	v_mov_b32_e32 v74, v73
	v_mov_b32_e32 v90, v72
	v_pk_add_f32 v[72:73], v[74:75], 1.0 op_sel_hi:[1,0]
	v_mov_b32_e32 v75, v34
	v_mov_b32_e32 v34, v33
	v_mov_b32_e32 v74, v32
	v_pk_mul_f32 v[32:33], v[34:35], v[80:81] op_sel_hi:[1,0]
	v_mov_b32_e32 v66, v65
	v_pk_mul_f32 v[74:75], v[74:75], v[80:81] op_sel_hi:[1,0]
	v_mov_b32_e32 v92, v64
	s_waitcnt vmcnt(0)
	v_mov_b32_e32 v95, v70
	v_pk_mul_f32 v[32:33], v[32:33], v[66:67]
	v_mov_b32_e32 v70, v69
	v_pk_add_f32 v[90:91], v[90:91], 1.0 op_sel_hi:[1,0]
	v_pk_mul_f32 v[74:75], v[74:75], v[92:93]
	v_mov_b32_e32 v94, v68
	v_pk_fma_f32 v[32:33], v[32:33], v[72:73], v[70:71]
	v_pk_fma_f32 v[74:75], v[74:75], v[90:91], v[94:95]
	v_cvt_pk_bf16_f32 v33, v75, v33
	v_cvt_pk_bf16_f32 v32, v74, v32
	v_mov_b32_e32 v34, v36
	v_mov_b32_e32 v35, v38
	v_pk_mul_f32 v[34:35], v[34:35], v[78:79] op_sel_hi:[1,0]
	v_mov_b32_e32 v38, v37
	v_pk_mul_f32 v[34:35], v[34:35], v[92:93]
	v_pk_mul_f32 v[36:37], v[38:39], v[78:79] op_sel_hi:[1,0]
	v_pk_fma_f32 v[34:35], v[34:35], v[90:91], v[94:95]
	v_pk_mul_f32 v[36:37], v[36:37], v[66:67]
	v_and_b32_sdwa v38, v35, v218 dst_sel:DWORD dst_unused:UNUSED_PAD src0_sel:WORD_1 src1_sel:DWORD
	v_pk_fma_f32 v[36:37], v[36:37], v[72:73], v[70:71]
	v_cvt_pk_bf16_f32 v34, v34, v36
	v_add3_u32 v35, v35, v38, s80
	v_and_b32_sdwa v38, v37, v218 dst_sel:DWORD dst_unused:UNUSED_PAD src0_sel:WORD_1 src1_sel:DWORD
	v_add3_u32 v37, v37, v38, s80
	v_and_b32_e32 v37, 0xffff0000, v37
	v_or_b32_sdwa v35, v37, v35 dst_sel:DWORD dst_unused:UNUSED_PAD src0_sel:DWORD src1_sel:WORD_1
	v_mov_b32_e32 v36, v60
	v_mov_b32_e32 v37, v62
	v_pk_mul_f32 v[36:37], v[36:37], v[84:85] op_sel_hi:[1,0]
	v_mov_b32_e32 v62, v61
	v_pk_mul_f32 v[36:37], v[92:93], v[36:37]
	v_pk_mul_f32 v[38:39], v[62:63], v[84:85] op_sel_hi:[1,0]
	v_pk_fma_f32 v[36:37], v[36:37], v[90:91], v[94:95]
	v_pk_mul_f32 v[38:39], v[66:67], v[38:39]
	v_and_b32_sdwa v60, v37, v218 dst_sel:DWORD dst_unused:UNUSED_PAD src0_sel:WORD_1 src1_sel:DWORD
	v_pk_fma_f32 v[38:39], v[38:39], v[72:73], v[70:71]
	v_cvt_pk_bf16_f32 v36, v36, v38
	v_add3_u32 v37, v37, v60, s80
	v_and_b32_sdwa v60, v39, v218 dst_sel:DWORD dst_unused:UNUSED_PAD src0_sel:WORD_1 src1_sel:DWORD
	v_add3_u32 v39, v39, v60, s80
	v_and_b32_e32 v39, 0xffff0000, v39
	v_or_b32_sdwa v37, v39, v37 dst_sel:DWORD dst_unused:UNUSED_PAD src0_sel:DWORD src1_sel:WORD_1
	v_mov_b32_e32 v38, v52
	v_mov_b32_e32 v39, v54
	v_pk_mul_f32 v[38:39], v[38:39], v[82:83] op_sel_hi:[1,0]
	v_mov_b32_e32 v54, v53
	v_pk_mul_f32 v[38:39], v[92:93], v[38:39]
	v_pk_mul_f32 v[52:53], v[54:55], v[82:83] op_sel_hi:[1,0]
	v_pk_fma_f32 v[38:39], v[90:91], v[38:39], v[94:95]
	v_pk_mul_f32 v[52:53], v[66:67], v[52:53]
	v_and_b32_sdwa v54, v39, v218 dst_sel:DWORD dst_unused:UNUSED_PAD src0_sel:WORD_1 src1_sel:DWORD
	v_pk_fma_f32 v[52:53], v[72:73], v[52:53], v[70:71]
	v_cvt_pk_bf16_f32 v38, v38, v52
	v_add3_u32 v39, v39, v54, s80
	v_and_b32_sdwa v54, v53, v218 dst_sel:DWORD dst_unused:UNUSED_PAD src0_sel:WORD_1 src1_sel:DWORD
	global_store_dwordx2 v[86:87], v[32:33], off
	v_lshl_add_u64 v[32:33], v[102:103], 0, v[118:119]
	v_add3_u32 v53, v53, v54, s80
	global_store_dwordx2 v[32:33], v[34:35], off
	v_lshl_add_u64 v[34:35], v[102:103], 0, v[116:117]
	v_and_b32_e32 v53, 0xffff0000, v53
	global_store_dwordx2 v[34:35], v[36:37], off
	v_lshl_add_u64 v[36:37], v[102:103], 0, v[114:115]
	v_or_b32_sdwa v39, v53, v39 dst_sel:DWORD dst_unused:UNUSED_PAD src0_sel:DWORD src1_sel:WORD_1
	global_store_dwordx2 v[36:37], v[38:39], off
	v_lshl_add_u64 v[64:65], v[76:77], 0, v[108:109]
	v_lshl_add_u64 v[38:39], v[88:89], 0, v[108:109]
	global_load_dwordx4 v[52:55], v[100:101], off offset:1024
	global_load_dwordx4 v[60:63], v[38:39], off
	s_nop 0
	global_load_dwordx4 v[64:67], v[64:65], off
	v_add_u32_e32 v104, s0, v104
	s_waitcnt vmcnt(2)
	v_mov_b32_e32 v69, v54
	s_waitcnt vmcnt(1)
	v_mov_b32_e32 v39, v62
	v_mov_b32_e32 v62, v61
	v_mov_b32_e32 v38, v60
	v_pk_add_f32 v[60:61], v[62:63], 1.0 op_sel_hi:[1,0]
	v_mov_b32_e32 v63, v18
	v_mov_b32_e32 v18, v17
	v_mov_b32_e32 v62, v16
	v_pk_mul_f32 v[16:17], v[18:19], v[80:81] op_sel_hi:[1,0]
	v_mov_b32_e32 v54, v53
	v_pk_mul_f32 v[62:63], v[62:63], v[80:81] op_sel_hi:[1,0]
	v_mov_b32_e32 v68, v52
	s_waitcnt vmcnt(0)
	v_mov_b32_e32 v71, v66
	v_pk_mul_f32 v[16:17], v[16:17], v[54:55]
	v_mov_b32_e32 v66, v65
	v_pk_add_f32 v[38:39], v[38:39], 1.0 op_sel_hi:[1,0]
	v_pk_mul_f32 v[62:63], v[62:63], v[68:69]
	v_mov_b32_e32 v70, v64
	v_pk_fma_f32 v[16:17], v[16:17], v[60:61], v[66:67]
	v_pk_fma_f32 v[62:63], v[62:63], v[38:39], v[70:71]
	v_cvt_pk_bf16_f32 v17, v63, v17
	v_cvt_pk_bf16_f32 v16, v62, v16
	global_store_dwordx2 v[86:87], v[16:17], off offset:512
	v_mov_b32_e32 v16, v20
	v_mov_b32_e32 v17, v22
	v_pk_mul_f32 v[16:17], v[16:17], v[78:79] op_sel_hi:[1,0]
	v_mov_b32_e32 v22, v21
	v_pk_mul_f32 v[16:17], v[16:17], v[68:69]
	v_pk_mul_f32 v[18:19], v[22:23], v[78:79] op_sel_hi:[1,0]
	v_pk_fma_f32 v[16:17], v[16:17], v[38:39], v[70:71]
	v_pk_mul_f32 v[18:19], v[18:19], v[54:55]
	v_and_b32_sdwa v20, v17, v218 dst_sel:DWORD dst_unused:UNUSED_PAD src0_sel:WORD_1 src1_sel:DWORD
	v_pk_fma_f32 v[18:19], v[18:19], v[60:61], v[66:67]
	v_cvt_pk_bf16_f32 v16, v16, v18
	v_add3_u32 v17, v17, v20, s80
	v_and_b32_sdwa v20, v19, v218 dst_sel:DWORD dst_unused:UNUSED_PAD src0_sel:WORD_1 src1_sel:DWORD
	v_add3_u32 v19, v19, v20, s80
	v_and_b32_e32 v19, 0xffff0000, v19
	v_or_b32_sdwa v17, v19, v17 dst_sel:DWORD dst_unused:UNUSED_PAD src0_sel:DWORD src1_sel:WORD_1
	global_store_dwordx2 v[32:33], v[16:17], off offset:512
	v_mov_b32_e32 v16, v56
	v_mov_b32_e32 v17, v58
	v_pk_mul_f32 v[16:17], v[16:17], v[84:85] op_sel_hi:[1,0]
	v_mov_b32_e32 v58, v57
	v_pk_mul_f32 v[16:17], v[16:17], v[68:69]
	v_pk_mul_f32 v[18:19], v[58:59], v[84:85] op_sel_hi:[1,0]
	v_pk_fma_f32 v[16:17], v[16:17], v[38:39], v[70:71]
	v_pk_mul_f32 v[18:19], v[18:19], v[54:55]
	v_and_b32_sdwa v20, v17, v218 dst_sel:DWORD dst_unused:UNUSED_PAD src0_sel:WORD_1 src1_sel:DWORD
	v_pk_fma_f32 v[18:19], v[18:19], v[60:61], v[66:67]
	v_cvt_pk_bf16_f32 v16, v16, v18
	v_add3_u32 v17, v17, v20, s80
	v_and_b32_sdwa v20, v19, v218 dst_sel:DWORD dst_unused:UNUSED_PAD src0_sel:WORD_1 src1_sel:DWORD
	v_add3_u32 v19, v19, v20, s80
	v_and_b32_e32 v19, 0xffff0000, v19
	v_or_b32_sdwa v17, v19, v17 dst_sel:DWORD dst_unused:UNUSED_PAD src0_sel:DWORD src1_sel:WORD_1
	global_store_dwordx2 v[34:35], v[16:17], off offset:512
	v_mov_b32_e32 v16, v48
	v_mov_b32_e32 v17, v50
	v_pk_mul_f32 v[16:17], v[16:17], v[82:83] op_sel_hi:[1,0]
	v_mov_b32_e32 v50, v49
	v_pk_mul_f32 v[16:17], v[16:17], v[68:69]
	v_pk_mul_f32 v[18:19], v[50:51], v[82:83] op_sel_hi:[1,0]
	v_pk_fma_f32 v[16:17], v[16:17], v[38:39], v[70:71]
	v_pk_mul_f32 v[18:19], v[18:19], v[54:55]
	v_and_b32_sdwa v20, v17, v218 dst_sel:DWORD dst_unused:UNUSED_PAD src0_sel:WORD_1 src1_sel:DWORD
	v_pk_fma_f32 v[18:19], v[18:19], v[60:61], v[66:67]
	v_cvt_pk_bf16_f32 v16, v16, v18
	v_add3_u32 v17, v17, v20, s80
	v_and_b32_sdwa v20, v19, v218 dst_sel:DWORD dst_unused:UNUSED_PAD src0_sel:WORD_1 src1_sel:DWORD
	v_add3_u32 v19, v19, v20, s80
	v_and_b32_e32 v19, 0xffff0000, v19
	v_or_b32_sdwa v17, v19, v17 dst_sel:DWORD dst_unused:UNUSED_PAD src0_sel:DWORD src1_sel:WORD_1
	global_store_dwordx2 v[36:37], v[16:17], off offset:512
	v_lshl_add_u64 v[20:21], v[88:89], 0, v[110:111]
	v_lshl_add_u64 v[38:39], v[76:77], 0, v[110:111]
	global_load_dwordx4 v[16:19], v[100:101], off offset:2048
	s_nop 0
	global_load_dwordx4 v[20:23], v[20:21], off
	s_nop 0
	global_load_dwordx4 v[48:51], v[38:39], off
	s_waitcnt vmcnt(2)
	v_mov_b32_e32 v53, v18
	s_waitcnt vmcnt(1)
	v_mov_b32_e32 v39, v22
	v_mov_b32_e32 v22, v21
	v_mov_b32_e32 v38, v20
	v_pk_add_f32 v[20:21], v[22:23], 1.0 op_sel_hi:[1,0]
	v_mov_b32_e32 v23, v10
	v_mov_b32_e32 v10, v9
	v_mov_b32_e32 v22, v8
	v_pk_mul_f32 v[8:9], v[10:11], v[80:81] op_sel_hi:[1,0]
	v_mov_b32_e32 v18, v17
	v_pk_mul_f32 v[22:23], v[22:23], v[80:81] op_sel_hi:[1,0]
	v_mov_b32_e32 v52, v16
	s_waitcnt vmcnt(0)
	v_mov_b32_e32 v55, v50
	v_pk_mul_f32 v[8:9], v[8:9], v[18:19]
	v_mov_b32_e32 v50, v49
	v_pk_add_f32 v[38:39], v[38:39], 1.0 op_sel_hi:[1,0]
	v_pk_mul_f32 v[22:23], v[22:23], v[52:53]
	v_mov_b32_e32 v54, v48
	v_pk_fma_f32 v[8:9], v[8:9], v[20:21], v[50:51]
	v_pk_fma_f32 v[22:23], v[22:23], v[38:39], v[54:55]
	v_cvt_pk_bf16_f32 v9, v23, v9
	v_cvt_pk_bf16_f32 v8, v22, v8
	global_store_dwordx2 v[86:87], v[8:9], off offset:1024
	v_mov_b32_e32 v8, v12
	v_mov_b32_e32 v9, v14
	v_pk_mul_f32 v[8:9], v[8:9], v[78:79] op_sel_hi:[1,0]
	v_mov_b32_e32 v14, v13
	v_pk_mul_f32 v[8:9], v[8:9], v[52:53]
	v_pk_mul_f32 v[10:11], v[14:15], v[78:79] op_sel_hi:[1,0]
	v_pk_fma_f32 v[8:9], v[8:9], v[38:39], v[54:55]
	v_pk_mul_f32 v[10:11], v[10:11], v[18:19]
	v_and_b32_sdwa v12, v9, v218 dst_sel:DWORD dst_unused:UNUSED_PAD src0_sel:WORD_1 src1_sel:DWORD
	v_pk_fma_f32 v[10:11], v[10:11], v[20:21], v[50:51]
	v_cvt_pk_bf16_f32 v8, v8, v10
	v_add3_u32 v9, v9, v12, s80
	v_and_b32_sdwa v12, v11, v218 dst_sel:DWORD dst_unused:UNUSED_PAD src0_sel:WORD_1 src1_sel:DWORD
	v_add3_u32 v11, v11, v12, s80
	v_and_b32_e32 v11, 0xffff0000, v11
	v_or_b32_sdwa v9, v11, v9 dst_sel:DWORD dst_unused:UNUSED_PAD src0_sel:DWORD src1_sel:WORD_1
	global_store_dwordx2 v[32:33], v[8:9], off offset:1024
	v_mov_b32_e32 v8, v40
	v_mov_b32_e32 v9, v42
	v_pk_mul_f32 v[8:9], v[8:9], v[84:85] op_sel_hi:[1,0]
	v_mov_b32_e32 v42, v41
	v_pk_mul_f32 v[8:9], v[8:9], v[52:53]
	v_pk_mul_f32 v[10:11], v[42:43], v[84:85] op_sel_hi:[1,0]
	v_pk_fma_f32 v[8:9], v[8:9], v[38:39], v[54:55]
	v_pk_mul_f32 v[10:11], v[10:11], v[18:19]
	v_and_b32_sdwa v12, v9, v218 dst_sel:DWORD dst_unused:UNUSED_PAD src0_sel:WORD_1 src1_sel:DWORD
	v_pk_fma_f32 v[10:11], v[10:11], v[20:21], v[50:51]
	v_cvt_pk_bf16_f32 v8, v8, v10
	v_add3_u32 v9, v9, v12, s80
	v_and_b32_sdwa v12, v11, v218 dst_sel:DWORD dst_unused:UNUSED_PAD src0_sel:WORD_1 src1_sel:DWORD
	v_add3_u32 v11, v11, v12, s80
	v_and_b32_e32 v11, 0xffff0000, v11
	v_or_b32_sdwa v9, v11, v9 dst_sel:DWORD dst_unused:UNUSED_PAD src0_sel:DWORD src1_sel:WORD_1
	global_store_dwordx2 v[34:35], v[8:9], off offset:1024
	v_mov_b32_e32 v8, v44
	v_mov_b32_e32 v9, v46
	v_pk_mul_f32 v[8:9], v[8:9], v[82:83] op_sel_hi:[1,0]
	v_mov_b32_e32 v46, v45
	v_pk_mul_f32 v[8:9], v[8:9], v[52:53]
	v_pk_mul_f32 v[10:11], v[46:47], v[82:83] op_sel_hi:[1,0]
	v_pk_fma_f32 v[8:9], v[8:9], v[38:39], v[54:55]
	v_pk_mul_f32 v[10:11], v[10:11], v[18:19]
	v_and_b32_sdwa v12, v9, v218 dst_sel:DWORD dst_unused:UNUSED_PAD src0_sel:WORD_1 src1_sel:DWORD
	v_pk_fma_f32 v[10:11], v[10:11], v[20:21], v[50:51]
	v_cvt_pk_bf16_f32 v8, v8, v10
	v_add3_u32 v9, v9, v12, s80
	v_and_b32_sdwa v12, v11, v218 dst_sel:DWORD dst_unused:UNUSED_PAD src0_sel:WORD_1 src1_sel:DWORD
	v_add3_u32 v11, v11, v12, s80
	v_and_b32_e32 v11, 0xffff0000, v11
	v_or_b32_sdwa v9, v11, v9 dst_sel:DWORD dst_unused:UNUSED_PAD src0_sel:DWORD src1_sel:WORD_1
	global_store_dwordx2 v[36:37], v[8:9], off offset:1024
	v_lshl_add_u64 v[12:13], v[88:89], 0, v[112:113]
	v_lshl_add_u64 v[16:17], v[76:77], 0, v[112:113]
	global_load_dwordx4 v[8:11], v[100:101], off offset:3072
	s_nop 0
	global_load_dwordx4 v[12:15], v[12:13], off
	s_nop 0
	global_load_dwordx4 v[16:19], v[16:17], off
	s_waitcnt vmcnt(2)
	v_mov_b32_e32 v23, v10
	s_waitcnt vmcnt(1)
	v_mov_b32_e32 v21, v14
	v_mov_b32_e32 v14, v13
	v_mov_b32_e32 v20, v12
	v_pk_add_f32 v[12:13], v[14:15], 1.0 op_sel_hi:[1,0]
	v_mov_b32_e32 v15, v2
	v_mov_b32_e32 v2, v1
	v_mov_b32_e32 v14, v0
	v_pk_mul_f32 v[0:1], v[2:3], v[80:81] op_sel_hi:[1,0]
	v_mov_b32_e32 v10, v9
	v_pk_mul_f32 v[14:15], v[14:15], v[80:81] op_sel_hi:[1,0]
	v_mov_b32_e32 v22, v8
	s_waitcnt vmcnt(0)
	v_mov_b32_e32 v39, v18
	v_pk_mul_f32 v[0:1], v[0:1], v[10:11]
	v_mov_b32_e32 v18, v17
	v_pk_add_f32 v[20:21], v[20:21], 1.0 op_sel_hi:[1,0]
	v_pk_mul_f32 v[14:15], v[14:15], v[22:23]
	v_mov_b32_e32 v38, v16
	v_pk_fma_f32 v[0:1], v[0:1], v[12:13], v[18:19]
	v_pk_fma_f32 v[14:15], v[14:15], v[20:21], v[38:39]
	v_cvt_pk_bf16_f32 v1, v15, v1
	v_cvt_pk_bf16_f32 v0, v14, v0
	global_store_dwordx2 v[86:87], v[0:1], off offset:1536
	v_mov_b32_e32 v0, v4
	v_mov_b32_e32 v1, v6
	v_pk_mul_f32 v[0:1], v[0:1], v[78:79] op_sel_hi:[1,0]
	v_mov_b32_e32 v6, v5
	v_pk_mul_f32 v[0:1], v[0:1], v[22:23]
	v_pk_mul_f32 v[2:3], v[6:7], v[78:79] op_sel_hi:[1,0]
	v_pk_fma_f32 v[0:1], v[0:1], v[20:21], v[38:39]
	v_pk_mul_f32 v[2:3], v[2:3], v[10:11]
	v_and_b32_sdwa v4, v1, v218 dst_sel:DWORD dst_unused:UNUSED_PAD src0_sel:WORD_1 src1_sel:DWORD
	v_pk_fma_f32 v[2:3], v[2:3], v[12:13], v[18:19]
	v_cvt_pk_bf16_f32 v0, v0, v2
	v_add3_u32 v1, v1, v4, s80
	v_and_b32_sdwa v4, v3, v218 dst_sel:DWORD dst_unused:UNUSED_PAD src0_sel:WORD_1 src1_sel:DWORD
	v_add3_u32 v3, v3, v4, s80
	v_and_b32_e32 v3, 0xffff0000, v3
	v_or_b32_sdwa v1, v3, v1 dst_sel:DWORD dst_unused:UNUSED_PAD src0_sel:DWORD src1_sel:WORD_1
	global_store_dwordx2 v[32:33], v[0:1], off offset:1536
	v_mov_b32_e32 v0, v24
	v_mov_b32_e32 v1, v26
	v_pk_mul_f32 v[0:1], v[0:1], v[84:85] op_sel_hi:[1,0]
	v_mov_b32_e32 v26, v25
	v_pk_mul_f32 v[0:1], v[0:1], v[22:23]
	v_pk_mul_f32 v[2:3], v[26:27], v[84:85] op_sel_hi:[1,0]
	v_pk_fma_f32 v[0:1], v[0:1], v[20:21], v[38:39]
	v_pk_mul_f32 v[2:3], v[2:3], v[10:11]
	v_and_b32_sdwa v4, v1, v218 dst_sel:DWORD dst_unused:UNUSED_PAD src0_sel:WORD_1 src1_sel:DWORD
	v_pk_fma_f32 v[2:3], v[2:3], v[12:13], v[18:19]
	v_cvt_pk_bf16_f32 v0, v0, v2
	v_add3_u32 v1, v1, v4, s80
	v_and_b32_sdwa v4, v3, v218 dst_sel:DWORD dst_unused:UNUSED_PAD src0_sel:WORD_1 src1_sel:DWORD
	v_add3_u32 v3, v3, v4, s80
	v_and_b32_e32 v3, 0xffff0000, v3
	v_or_b32_sdwa v1, v3, v1 dst_sel:DWORD dst_unused:UNUSED_PAD src0_sel:DWORD src1_sel:WORD_1
	global_store_dwordx2 v[34:35], v[0:1], off offset:1536
	v_mov_b32_e32 v0, v28
	v_mov_b32_e32 v1, v30
	v_pk_mul_f32 v[0:1], v[0:1], v[82:83] op_sel_hi:[1,0]
	v_mov_b32_e32 v30, v29
	v_pk_mul_f32 v[0:1], v[0:1], v[22:23]
	v_pk_mul_f32 v[2:3], v[30:31], v[82:83] op_sel_hi:[1,0]
	v_pk_fma_f32 v[0:1], v[0:1], v[20:21], v[38:39]
	v_pk_mul_f32 v[2:3], v[2:3], v[10:11]
	v_and_b32_sdwa v4, v1, v218 dst_sel:DWORD dst_unused:UNUSED_PAD src0_sel:WORD_1 src1_sel:DWORD
	v_pk_fma_f32 v[2:3], v[2:3], v[12:13], v[18:19]
	v_cvt_pk_bf16_f32 v0, v0, v2
	v_add3_u32 v1, v1, v4, s80
	v_and_b32_sdwa v4, v3, v218 dst_sel:DWORD dst_unused:UNUSED_PAD src0_sel:WORD_1 src1_sel:DWORD
	v_add3_u32 v3, v3, v4, s80
	v_and_b32_e32 v3, 0xffff0000, v3
	v_or_b32_sdwa v1, v3, v1 dst_sel:DWORD dst_unused:UNUSED_PAD src0_sel:DWORD src1_sel:WORD_1
	global_store_dwordx2 v[36:37], v[0:1], off offset:1536
	s_cbranch_scc1 .LBB0_179

.LBB0_182:
	v_min_i32_e32 v2, 0x4000, v16
	v_ashrrev_i32_e32 v2, 13, v2
	v_mov_b32_e32 v53, v193
	v_lshlrev_b64 v[60:61], 11, v[16:17]
	v_add_u32_e32 v2, s8, v2
	v_lshl_add_u64 v[0:1], v[0:1], 0, v[52:53]
	v_lshl_add_u64 v[16:17], v[44:45], 0, v[60:61]
	v_mul_hi_i32_i24_e32 v63, 0x6000, v2
	v_mul_i32_i24_e32 v62, 0x6000, v2
	global_load_dwordx4 v[12:15], v[0:1], off nt
	global_load_dwordx4 v[8:11], v[0:1], off offset:1024 nt
	global_load_dwordx4 v[4:7], v[0:1], off offset:2048 nt
	s_nop 0
	global_load_dwordx4 v[0:3], v[0:1], off offset:3072 nt
	s_nop 0
	global_load_dwordx2 v[24:25], v[16:17], off nt
	global_load_dwordx2 v[32:33], v[16:17], off offset:512 nt
	global_load_dwordx2 v[40:41], v[16:17], off offset:1024 nt
	global_load_dwordx2 v[76:77], v[16:17], off offset:1536 nt
	v_lshl_add_u64 v[18:19], s[90:91], 0, v[62:63]
	v_lshl_add_u64 v[20:21], v[18:19], 0, v[52:53]
	s_mov_b64 s[0:1], 0x345a000
	v_lshl_add_u64 v[84:85], v[20:21], 0, s[0:1]
	s_mov_b32 s0, 0x345a000
	v_add_co_u32_e32 v20, vcc, s0, v20
	global_load_dwordx4 v[16:19], v[46:47], off
	s_nop 0
	v_addc_co_u32_e32 v21, vcc, 0, v21, vcc
	global_load_dwordx4 v[20:23], v[20:21], off
	s_mov_b32 s0, 0x800000
	s_mov_b64 s[10:11], 0x3000
	v_mov_b32_e32 v59, v193
	s_waitcnt vmcnt(5)
	v_and_b32_e32 v67, 0xffff0000, v24
	s_waitcnt vmcnt(4)
	v_and_b32_e32 v69, 0xffff0000, v32
	v_lshlrev_b32_e32 v66, 16, v24
	v_lshlrev_b32_e32 v68, 16, v32
	v_mov_b32_e32 v34, v67
	v_mov_b32_e32 v35, v69
	v_lshlrev_b32_e32 v70, 16, v25
	v_and_b32_e32 v73, 0xffff0000, v33
	v_lshlrev_b32_e32 v72, 16, v33
	v_mov_b32_e32 v32, v66
	v_mov_b32_e32 v33, v68
	v_pk_mul_f32 v[34:35], v[34:35], v[34:35]
	v_and_b32_e32 v71, 0xffff0000, v25
	global_load_dwordx4 v[28:31], v[46:47], off offset:1024
	global_load_dwordx4 v[24:27], v[84:85], off offset:1024
	v_pk_fma_f32 v[32:33], v[32:33], v[32:33], v[34:35]
	v_mov_b32_e32 v34, v70
	v_mov_b32_e32 v35, v72
	v_mov_b32_e32 v36, v71
	v_mov_b32_e32 v37, v73
	v_pk_fma_f32 v[32:33], v[34:35], v[34:35], v[32:33]
	s_waitcnt vmcnt(5)
	v_and_b32_e32 v75, 0xffff0000, v40
	v_pk_fma_f32 v[78:79], v[36:37], v[36:37], v[32:33]
	global_load_dwordx4 v[36:39], v[46:47], off offset:2048
	global_load_dwordx4 v[32:35], v[84:85], off offset:2048
	v_lshlrev_b32_e32 v74, 16, v40
	v_and_b32_e32 v83, 0xffff0000, v41
	v_lshlrev_b32_e32 v82, 16, v41
	global_load_dwordx4 v[40:43], v[46:47], off offset:3072
	global_load_dwordx4 v[92:95], v[84:85], off offset:3072
	s_waitcnt vmcnt(8)
	v_and_b32_e32 v81, 0xffff0000, v76
	v_lshlrev_b32_e32 v80, 16, v76
	v_mov_b32_e32 v96, v75
	v_mov_b32_e32 v97, v81
	v_and_b32_e32 v85, 0xffff0000, v77
	v_lshlrev_b32_e32 v84, 16, v77
	v_mov_b32_e32 v76, v74
	v_mov_b32_e32 v77, v80
	v_pk_mul_f32 v[96:97], v[96:97], v[96:97]
	v_mov_b32_e32 v98, v83
	v_pk_fma_f32 v[76:77], v[76:77], v[76:77], v[96:97]
	v_mov_b32_e32 v96, v82
	v_mov_b32_e32 v97, v84
	v_mov_b32_e32 v99, v85
	v_pk_fma_f32 v[76:77], v[96:97], v[96:97], v[76:77]
	v_add_f32_e32 v55, v78, v79
	v_pk_fma_f32 v[76:77], v[98:99], v[98:99], v[76:77]
	s_nop 0
	v_add_f32_e32 v55, v55, v76
	v_add_f32_e32 v55, v55, v77
	s_nop 0
	s_nop 1
	v_add_f32_dpp v55, v55, v55 quad_perm:[1,0,3,2] row_mask:0xf bank_mask:0xf
	s_nop 1
	v_add_f32_dpp v55, v55, v55 quad_perm:[2,3,0,1] row_mask:0xf bank_mask:0xf
	s_nop 1
	v_add_f32_dpp v55, v55, v55 row_half_mirror row_mask:0xf bank_mask:0xf
	s_nop 1
	v_add_f32_dpp v55, v55, v55 row_mirror row_mask:0xf bank_mask:0xf
	s_nop 1
	v_mov_b32_e32 v57, v55
	s_nop 1
	v_permlane16_swap_b32_e32 v55, v57
	s_nop 1
	v_add_f32_e32 v55, v55, v57
	s_nop 1
	v_mov_b32_e32 v57, v55
	s_nop 1
	v_permlane32_swap_b32_e32 v55, v57
	s_nop 1
	v_add_f32_e32 v55, v55, v57
	s_nop 1
	v_fmamk_f32 v55, v55, 0x3a800000, v219
	v_cmp_gt_f32_e32 vcc, s0, v55
	v_mul_f32_e32 v57, 0x4b800000, v55
	s_nop 0
	v_cndmask_b32_e32 v55, v55, v57, vcc
	v_rsq_f32_e32 v55, v55
	s_nop 0
	v_mul_f32_e32 v57, 0x45800000, v55
	v_cndmask_b32_e32 v76, v55, v57, vcc
	v_pk_mul_f32 v[66:67], v[76:77], v[66:67] op_sel_hi:[0,1]
	s_waitcnt vmcnt(7)
	v_pk_mul_f32 v[16:17], v[16:17], v[66:67]
	v_pk_mul_f32 v[66:67], v[76:77], v[70:71] op_sel_hi:[0,1]
	s_waitcnt vmcnt(6)
	v_pk_fma_f32 v[12:13], v[20:21], v[16:17], v[12:13]
	v_pk_mul_f32 v[16:17], v[76:77], v[68:69] op_sel_hi:[0,1]
	v_pk_mul_f32 v[18:19], v[18:19], v[66:67]
	s_waitcnt vmcnt(5)
	v_pk_mul_f32 v[16:17], v[28:29], v[16:17]
	v_pk_fma_f32 v[14:15], v[22:23], v[18:19], v[14:15]
	v_pk_mul_f32 v[18:19], v[76:77], v[72:73] op_sel_hi:[0,1]
	s_waitcnt vmcnt(4)
	v_pk_fma_f32 v[8:9], v[24:25], v[16:17], v[8:9]
	v_pk_mul_f32 v[16:17], v[76:77], v[74:75] op_sel_hi:[0,1]
	v_pk_mul_f32 v[18:19], v[30:31], v[18:19]
	s_waitcnt vmcnt(3)
	v_pk_mul_f32 v[16:17], v[16:17], v[36:37]
	v_pk_fma_f32 v[10:11], v[26:27], v[18:19], v[10:11]
	v_pk_mul_f32 v[18:19], v[76:77], v[82:83] op_sel_hi:[0,1]
	s_waitcnt vmcnt(2)
	v_pk_fma_f32 v[4:5], v[16:17], v[32:33], v[4:5]
	v_pk_mul_f32 v[16:17], v[76:77], v[80:81] op_sel_hi:[0,1]
	v_mov_b32_e32 v22, v13
	v_mov_b32_e32 v23, v9
	v_pk_mul_f32 v[18:19], v[18:19], v[38:39]
	s_waitcnt vmcnt(1)
	v_pk_mul_f32 v[16:17], v[16:17], v[40:41]
	v_mov_b32_e32 v20, v12
	v_mov_b32_e32 v21, v8
	v_pk_mul_f32 v[22:23], v[22:23], v[22:23]
	v_pk_fma_f32 v[6:7], v[18:19], v[34:35], v[6:7]
	v_pk_mul_f32 v[18:19], v[76:77], v[84:85] op_sel_hi:[0,1]
	s_waitcnt vmcnt(0)
	v_pk_fma_f32 v[0:1], v[16:17], v[92:93], v[0:1]
	v_pk_fma_f32 v[20:21], v[20:21], v[20:21], v[22:23]
	v_mov_b32_e32 v22, v14
	v_mov_b32_e32 v23, v10
	v_pk_mul_f32 v[18:19], v[18:19], v[42:43]
	v_pk_fma_f32 v[20:21], v[22:23], v[22:23], v[20:21]
	v_mov_b32_e32 v22, v15
	v_mov_b32_e32 v23, v11
	v_mov_b32_e32 v24, v5
	v_mov_b32_e32 v25, v1
	v_pk_fma_f32 v[2:3], v[18:19], v[94:95], v[2:3]
	v_pk_fma_f32 v[20:21], v[22:23], v[22:23], v[20:21]
	v_mov_b32_e32 v22, v4
	v_mov_b32_e32 v23, v0
	v_pk_mul_f32 v[24:25], v[24:25], v[24:25]
	v_lshl_add_u64 v[16:17], v[64:65], 0, v[52:53]
	v_pk_fma_f32 v[22:23], v[22:23], v[22:23], v[24:25]
	v_mov_b32_e32 v24, v6
	v_mov_b32_e32 v25, v2
	v_pk_fma_f32 v[22:23], v[24:25], v[24:25], v[22:23]
	v_mov_b32_e32 v24, v7
	v_mov_b32_e32 v25, v3
	v_pk_fma_f32 v[22:23], v[24:25], v[24:25], v[22:23]
	v_add_f32_e32 v20, v20, v21
	global_store_dwordx4 v[16:17], v[12:15], off nt
	global_store_dwordx4 v[16:17], v[8:11], off offset:1024 nt
	global_store_dwordx4 v[16:17], v[4:7], off offset:2048 nt
	global_store_dwordx4 v[16:17], v[0:3], off offset:3072 nt
	v_lshl_add_u64 v[16:17], s[96:97], 0, v[62:63]
	v_add_f32_e32 v20, v20, v22
	v_lshl_add_u64 v[18:19], v[16:17], 0, s[10:11]
	v_add_f32_e32 v22, v20, v23
	s_mov_b64 s[10:11], 0x4000
	v_lshl_add_u64 v[20:21], v[16:17], 0, s[10:11]
	ds_bpermute_b32 v16, v86, v22
	v_lshl_add_u64 v[26:27], v[20:21], 0, v[52:53]
	v_lshl_add_u64 v[30:31], v[18:19], 0, v[52:53]
	v_mov_b32_e32 v34, v12
	v_mov_b32_e32 v35, v14
	s_waitcnt lgkmcnt(0)
	v_add_f32_e32 v16, v22, v16
	global_load_dwordx4 v[22:25], v[48:49], off
	s_nop 0
	global_load_dwordx4 v[26:29], v[26:27], off
	s_nop 0
	global_load_dwordx4 v[30:33], v[30:31], off
	ds_bpermute_b32 v17, v87, v16
	v_mov_b32_e32 v14, v13
	v_mov_b32_e32 v55, v193
	v_mov_b32_e32 v57, v193
	s_waitcnt lgkmcnt(0)
	v_add_f32_e32 v16, v16, v17
	ds_bpermute_b32 v17, v88, v16
	s_waitcnt lgkmcnt(0)
	v_add_f32_e32 v16, v16, v17
	ds_bpermute_b32 v17, v89, v16
	s_waitcnt lgkmcnt(0)
	v_add_f32_e32 v16, v16, v17
	ds_bpermute_b32 v17, v90, v16
	s_waitcnt lgkmcnt(0)
	v_add_f32_e32 v16, v16, v17
	ds_bpermute_b32 v17, v91, v16
	s_waitcnt lgkmcnt(0)
	v_add_f32_e32 v16, v16, v17
	v_fmamk_f32 v16, v16, 0x3a800000, v219
	v_cmp_gt_f32_e32 vcc, s0, v16
	v_mul_f32_e32 v17, 0x4b800000, v16
	v_readlane_b32 s0, v255, 11
	v_cndmask_b32_e32 v16, v16, v17, vcc
	v_rsq_f32_e32 v16, v16
	v_add_u32_e32 v192, s0, v192
	s_movk_i32 s0, 0x1ff
	v_readlane_b32 s1, v255, 12
	v_mul_f32_e32 v17, 0x45800000, v16
	v_cndmask_b32_e32 v16, v16, v17, vcc
	v_pk_mul_f32 v[34:35], v[34:35], v[16:17] op_sel_hi:[1,0]
	v_pk_mul_f32 v[12:13], v[14:15], v[16:17] op_sel_hi:[1,0]
	v_cmp_lt_i32_e32 vcc, s0, v192
	s_or_b64 s[6:7], vcc, s[6:7]
	s_waitcnt vmcnt(2)
	v_mov_b32_e32 v36, v22
	v_mov_b32_e32 v37, v24
	v_pk_mul_f32 v[34:35], v[36:37], v[34:35]
	s_waitcnt vmcnt(1)
	v_mov_b32_e32 v36, v26
	v_mov_b32_e32 v37, v28
	v_pk_add_f32 v[36:37], v[36:37], 1.0 op_sel_hi:[1,0]
	s_waitcnt vmcnt(0)
	v_mov_b32_e32 v38, v30
	v_mov_b32_e32 v39, v32
	v_mov_b32_e32 v24, v23
	v_mov_b32_e32 v28, v27
	v_pk_fma_f32 v[34:35], v[36:37], v[34:35], v[38:39]
	v_pk_mul_f32 v[12:13], v[24:25], v[12:13]
	v_pk_add_f32 v[14:15], v[28:29], 1.0 op_sel_hi:[1,0]
	v_mov_b32_e32 v32, v31
	v_pk_fma_f32 v[12:13], v[14:15], v[12:13], v[32:33]
	v_and_b32_sdwa v15, v34, v218 dst_sel:DWORD dst_unused:UNUSED_PAD src0_sel:WORD_1 src1_sel:DWORD
	v_add3_u32 v17, v34, v15, s80
	v_and_b32_sdwa v22, v12, v218 dst_sel:DWORD dst_unused:UNUSED_PAD src0_sel:WORD_1 src1_sel:DWORD
	v_cvt_pk_bf16_f32 v15, v35, v13
	v_add3_u32 v12, v12, v22, s80
	v_and_b32_e32 v12, 0xffff0000, v12
	v_or_b32_sdwa v14, v12, v17 dst_sel:DWORD dst_unused:UNUSED_PAD src0_sel:DWORD src1_sel:WORD_1
	v_lshl_add_u64 v[12:13], v[50:51], 0, v[60:61]
	global_store_dwordx2 v[12:13], v[14:15], off
	v_lshl_add_u64 v[30:31], v[18:19], 0, v[54:55]
	v_lshl_add_u64 v[14:15], v[20:21], 0, v[54:55]
	global_load_dwordx4 v[22:25], v[48:49], off offset:1024
	global_load_dwordx4 v[26:29], v[14:15], off
	s_nop 0
	global_load_dwordx4 v[30:33], v[30:31], off
	v_mov_b32_e32 v14, v8
	v_mov_b32_e32 v15, v10
	v_pk_mul_f32 v[14:15], v[14:15], v[16:17] op_sel_hi:[1,0]
	v_mov_b32_e32 v10, v9
	v_pk_mul_f32 v[8:9], v[10:11], v[16:17] op_sel_hi:[1,0]
	s_waitcnt vmcnt(2)
	v_mov_b32_e32 v34, v22
	v_mov_b32_e32 v35, v24
	v_pk_mul_f32 v[14:15], v[14:15], v[34:35]
	s_waitcnt vmcnt(1)
	v_mov_b32_e32 v34, v26
	v_mov_b32_e32 v35, v28
	v_pk_add_f32 v[34:35], v[34:35], 1.0 op_sel_hi:[1,0]
	s_waitcnt vmcnt(0)
	v_mov_b32_e32 v36, v30
	v_mov_b32_e32 v37, v32
	v_mov_b32_e32 v24, v23
	v_mov_b32_e32 v28, v27
	v_pk_fma_f32 v[14:15], v[14:15], v[34:35], v[36:37]
	v_pk_mul_f32 v[8:9], v[8:9], v[24:25]
	v_pk_add_f32 v[10:11], v[28:29], 1.0 op_sel_hi:[1,0]
	v_mov_b32_e32 v32, v31
	v_pk_fma_f32 v[8:9], v[8:9], v[10:11], v[32:33]
	v_cvt_pk_bf16_f32 v8, v14, v8
	v_cvt_pk_bf16_f32 v9, v15, v9
	global_store_dwordx2 v[12:13], v[8:9], off offset:512
	v_lshl_add_u64 v[26:27], v[18:19], 0, v[56:57]
	v_lshl_add_u64 v[14:15], v[20:21], 0, v[56:57]
	global_load_dwordx4 v[8:11], v[48:49], off offset:2048
	global_load_dwordx4 v[22:25], v[14:15], off
	s_nop 0
	global_load_dwordx4 v[26:29], v[26:27], off
	v_mov_b32_e32 v14, v4
	v_mov_b32_e32 v15, v6
	v_pk_mul_f32 v[14:15], v[14:15], v[16:17] op_sel_hi:[1,0]
	v_mov_b32_e32 v6, v5
	v_pk_mul_f32 v[4:5], v[6:7], v[16:17] op_sel_hi:[1,0]
	s_waitcnt vmcnt(2)
	v_mov_b32_e32 v30, v8
	v_mov_b32_e32 v31, v10
	v_pk_mul_f32 v[14:15], v[14:15], v[30:31]
	s_waitcnt vmcnt(1)
	v_mov_b32_e32 v31, v24
	v_mov_b32_e32 v10, v9
	v_mov_b32_e32 v24, v23
	v_mov_b32_e32 v30, v22
	s_waitcnt vmcnt(0)
	v_mov_b32_e32 v33, v28
	v_pk_mul_f32 v[4:5], v[4:5], v[10:11]
	v_pk_add_f32 v[6:7], v[24:25], 1.0 op_sel_hi:[1,0]
	v_mov_b32_e32 v28, v27
	v_pk_add_f32 v[30:31], v[30:31], 1.0 op_sel_hi:[1,0]
	v_mov_b32_e32 v32, v26
	v_pk_fma_f32 v[4:5], v[4:5], v[6:7], v[28:29]
	v_pk_fma_f32 v[14:15], v[14:15], v[30:31], v[32:33]
	v_cvt_pk_bf16_f32 v5, v15, v5
	v_cvt_pk_bf16_f32 v4, v14, v4
	global_store_dwordx2 v[12:13], v[4:5], off offset:1024
	v_lshl_add_u64 v[8:9], v[20:21], 0, v[58:59]
	v_lshl_add_u64 v[14:15], v[18:19], 0, v[58:59]
	global_load_dwordx4 v[4:7], v[48:49], off offset:3072
	s_nop 0
	global_load_dwordx4 v[8:11], v[8:9], off
	s_nop 0
	global_load_dwordx4 v[18:21], v[14:15], off
	v_mov_b32_e32 v14, v0
	v_mov_b32_e32 v15, v2
	v_pk_mul_f32 v[14:15], v[14:15], v[16:17] op_sel_hi:[1,0]
	v_mov_b32_e32 v2, v1
	v_pk_mul_f32 v[0:1], v[2:3], v[16:17] op_sel_hi:[1,0]
	s_waitcnt vmcnt(2)
	v_mov_b32_e32 v22, v4
	v_mov_b32_e32 v23, v6
	v_pk_mul_f32 v[14:15], v[14:15], v[22:23]
	s_waitcnt vmcnt(1)
	v_mov_b32_e32 v23, v10
	v_mov_b32_e32 v6, v5
	v_mov_b32_e32 v10, v9
	v_mov_b32_e32 v22, v8
	s_waitcnt vmcnt(0)
	v_mov_b32_e32 v25, v20
	v_pk_mul_f32 v[0:1], v[0:1], v[6:7]
	v_pk_add_f32 v[2:3], v[10:11], 1.0 op_sel_hi:[1,0]
	v_mov_b32_e32 v20, v19
	v_pk_add_f32 v[22:23], v[22:23], 1.0 op_sel_hi:[1,0]
	v_mov_b32_e32 v24, v18
	v_pk_fma_f32 v[0:1], v[0:1], v[2:3], v[20:21]
	v_pk_fma_f32 v[14:15], v[14:15], v[22:23], v[24:25]
	v_cvt_pk_bf16_f32 v1, v15, v1
	v_cvt_pk_bf16_f32 v0, v14, v0
	global_store_dwordx2 v[12:13], v[0:1], off offset:1536
	s_andn2_b64 exec, exec, s[6:7]
	s_cbranch_execz .LBB0_188

.LBB0_1023:
	s_or_b64 exec, exec, s[0:1]
	v_lshl_add_u64 v[0:1], v[0:1], 0, v[192:193]
	global_load_dwordx4 v[60:63], v[0:1], off nt
	global_load_dwordx4 v[44:47], v[0:1], off offset:1024 nt
	global_load_dwordx4 v[28:31], v[0:1], off offset:2048 nt
	global_load_dwordx4 v[12:15], v[0:1], off offset:3072 nt
	v_add_co_u32_e32 v2, vcc, 0x1000, v0
	v_min_i32_e32 v67, 0x4000, v80
	s_nop 0
	v_addc_co_u32_e32 v3, vcc, 0, v1, vcc
	global_load_dwordx4 v[56:59], v[2:3], off nt
	global_load_dwordx4 v[40:43], v[2:3], off offset:1024 nt
	global_load_dwordx4 v[24:27], v[2:3], off offset:2048 nt
	global_load_dwordx4 v[8:11], v[2:3], off offset:3072 nt
	v_add_co_u32_e32 v2, vcc, 0x2000, v0
	s_mov_b64 s[0:1], vcc
	s_nop 0
	v_addc_co_u32_e64 v3, s[0:1], 0, v1, s[0:1]
	global_load_dwordx4 v[52:55], v[2:3], off nt
	global_load_dwordx4 v[36:39], v[2:3], off offset:1024 nt
	global_load_dwordx4 v[20:23], v[2:3], off offset:2048 nt
	global_load_dwordx4 v[4:7], v[2:3], off offset:3072 nt
	v_add_co_u32_e32 v0, vcc, 0x3000, v0
	v_ashrrev_i32_e32 v67, 13, v67
	s_nop 0
	v_addc_co_u32_e32 v1, vcc, 0, v1, vcc
	global_load_dwordx4 v[48:51], v[0:1], off nt
	global_load_dwordx4 v[32:35], v[0:1], off offset:1024 nt
	global_load_dwordx4 v[16:19], v[0:1], off offset:2048 nt
	s_nop 0
	global_load_dwordx4 v[0:3], v[0:1], off offset:3072 nt
	s_mov_b64 s[0:1], 0x1000
	v_mov_b32_e32 v136, v193
	v_mov_b32_e32 v137, v193
	v_mul_hi_i32_i24_e32 v138, 0x6000, v67
	v_mul_i32_i24_e32 v139, 0x6000, v67
	v_mov_b32_e32 v140, v139
	v_mov_b32_e32 v141, v138
	v_lshl_add_u64 v[142:143], s[96:97], 0, v[140:141]
	v_lshl_add_u64 v[140:141], v[142:143], 0, s[0:1]
	v_lshl_add_u64 v[144:145], v[140:141], 0, v[192:193]
	global_load_dwordx4 v[146:149], v[144:145], off
	global_load_dwordx4 v[150:153], v[76:77], off
	v_lshl_add_u64 v[138:139], v[142:143], 0, v[192:193]
	global_load_dwordx4 v[154:157], v[138:139], off
	v_mov_b32_e32 v158, v193
	v_mov_b32_e32 v160, v82
	v_mov_b32_e32 v161, v158
	v_lshl_add_u64 v[162:163], v[140:141], 0, v[160:161]
	global_load_dwordx4 v[164:167], v[162:163], off
	global_load_dwordx4 v[172:175], v[76:77], off offset:1024
	global_load_dwordx4 v[180:183], v[138:139], off offset:1024
	v_mov_b32_e32 v160, v84
	v_mov_b32_e32 v161, v136
	v_lshl_add_u64 v[176:177], v[140:141], 0, v[160:161]
	global_load_dwordx4 v[184:187], v[176:177], off
	global_load_dwordx4 v[188:191], v[76:77], off offset:2048
	global_load_dwordx4 v[232:235], v[138:139], off offset:2048
	v_mov_b32_e32 v160, v86
	v_mov_b32_e32 v161, v137
	v_lshl_add_u64 v[224:225], v[140:141], 0, v[160:161]
	global_load_dwordx4 v[236:239], v[224:225], off
	global_load_dwordx4 v[240:243], v[76:77], off offset:3072
	global_load_dwordx4 v[248:251], v[138:139], off offset:3072
	s_mov_b64 s[0:1], 0x1000
	s_mov_b32 s6, 0x3a800000
	s_mov_b32 s2, 0x800000
	v_mov_b32_e32 v85, v193
	v_mov_b32_e32 v87, v193
	s_add_i32 s4, s4, s93
	s_cmpk_gt_i32 s4, 0x3ff
	s_waitcnt vmcnt(27)
	v_mov_b32_e32 v94, v61
	s_waitcnt vmcnt(26)
	v_mov_b32_e32 v95, v45
	s_waitcnt vmcnt(25)
	v_mov_b32_e32 v102, v29
	s_waitcnt vmcnt(24)
	v_mov_b32_e32 v103, v13
	v_mov_b32_e32 v90, v60
	v_mov_b32_e32 v91, v44
	v_mov_b32_e32 v100, v28
	v_mov_b32_e32 v101, v12
	v_pk_mul_f32 v[94:95], v[94:95], v[94:95]
	v_pk_mul_f32 v[102:103], v[102:103], v[102:103]
	v_mov_b32_e32 v96, v62
	v_mov_b32_e32 v97, v46
	v_pk_fma_f32 v[90:91], v[90:91], v[90:91], v[94:95]
	v_pk_fma_f32 v[94:95], v[100:101], v[100:101], v[102:103]
	s_waitcnt vmcnt(23)
	v_mov_b32_e32 v102, v57
	s_waitcnt vmcnt(22)
	v_mov_b32_e32 v103, v41
	v_mov_b32_e32 v100, v56
	v_mov_b32_e32 v101, v40
	s_waitcnt vmcnt(21)
	v_mov_b32_e32 v114, v25
	s_waitcnt vmcnt(20)
	v_mov_b32_e32 v115, v9
	v_pk_fma_f32 v[90:91], v[96:97], v[96:97], v[90:91]
	v_pk_mul_f32 v[96:97], v[102:103], v[102:103]
	v_mov_b32_e32 v98, v63
	v_mov_b32_e32 v99, v47
	v_mov_b32_e32 v108, v58
	v_mov_b32_e32 v109, v42
	v_mov_b32_e32 v112, v24
	v_mov_b32_e32 v113, v8
	v_pk_mul_f32 v[102:103], v[114:115], v[114:115]
	v_pk_fma_f32 v[96:97], v[100:101], v[100:101], v[96:97]
	v_mov_b32_e32 v104, v30
	v_mov_b32_e32 v105, v14
	v_mov_b32_e32 v110, v59
	v_mov_b32_e32 v111, v43
	v_mov_b32_e32 v116, v26
	v_mov_b32_e32 v117, v10
	v_pk_fma_f32 v[90:91], v[98:99], v[98:99], v[90:91]
	v_pk_fma_f32 v[98:99], v[112:113], v[112:113], v[102:103]
	v_pk_fma_f32 v[96:97], v[108:109], v[108:109], v[96:97]
	v_mov_b32_e32 v106, v31
	v_mov_b32_e32 v107, v15
	v_mov_b32_e32 v118, v27
	v_mov_b32_e32 v119, v11
	v_pk_fma_f32 v[94:95], v[104:105], v[104:105], v[94:95]
	v_pk_fma_f32 v[98:99], v[116:117], v[116:117], v[98:99]
	v_pk_fma_f32 v[96:97], v[110:111], v[110:111], v[96:97]
	v_pk_fma_f32 v[94:95], v[106:107], v[106:107], v[94:95]
	v_mov_b32_e32 v101, v90
	v_pk_fma_f32 v[98:99], v[118:119], v[118:119], v[98:99]
	v_mov_b32_e32 v100, v96
	v_mov_b32_e32 v90, v97
	v_mov_b32_e32 v103, v94
	v_mov_b32_e32 v102, v98
	v_pk_add_f32 v[90:91], v[100:101], v[90:91]
	v_mov_b32_e32 v94, v99
	v_pk_add_f32 v[90:91], v[90:91], v[102:103]
	v_add_u32_e32 v96, 1, v80
	v_pk_add_f32 v[90:91], v[90:91], v[94:95]
	ds_bpermute_b32 v95, v65, v91
	ds_bpermute_b32 v94, v65, v90
	v_ashrrev_i32_e32 v97, 31, v96
	v_mul_hi_i32_i24_e32 v105, 0x6000, v67
	v_mul_i32_i24_e32 v104, 0x6000, v67
	v_lshlrev_b64 v[102:103], 11, v[96:97]
	s_waitcnt lgkmcnt(0)
	v_pk_add_f32 v[90:91], v[90:91], v[94:95]
	ds_bpermute_b32 v95, v71, v91
	ds_bpermute_b32 v94, v71, v90
	v_lshl_add_u64 v[96:97], s[96:97], 0, v[104:105]
	s_waitcnt vmcnt(19)
	v_mov_b32_e32 v104, v52
	s_waitcnt vmcnt(18)
	v_mov_b32_e32 v105, v36
	s_waitcnt vmcnt(13)
	v_mov_b32_e32 v108, v17
	s_waitcnt lgkmcnt(0)
	v_pk_add_f32 v[90:91], v[90:91], v[94:95]
	ds_bpermute_b32 v95, v73, v91
	ds_bpermute_b32 v94, v73, v90
	s_waitcnt vmcnt(12)
	v_mov_b32_e32 v109, v1
	v_pk_mul_f32 v[108:109], v[108:109], v[108:109]
	v_mov_b32_e32 v128, v19
	v_mov_b32_e32 v129, v3
	s_waitcnt lgkmcnt(0)
	v_pk_add_f32 v[116:117], v[90:91], v[94:95]
	v_mov_b32_e32 v90, v53
	v_mov_b32_e32 v91, v37
	v_pk_mul_f32 v[90:91], v[90:91], v[90:91]
	v_mov_b32_e32 v94, v54
	v_pk_fma_f32 v[90:91], v[104:105], v[104:105], v[90:91]
	v_mov_b32_e32 v95, v38
	v_pk_fma_f32 v[90:91], v[94:95], v[94:95], v[90:91]
	v_mov_b32_e32 v94, v55
	v_mov_b32_e32 v95, v39
	v_pk_fma_f32 v[120:121], v[94:95], v[94:95], v[90:91]
	v_mov_b32_e32 v94, v21
	v_mov_b32_e32 v95, v5
	v_mov_b32_e32 v90, v20
	v_mov_b32_e32 v91, v4
	v_pk_mul_f32 v[94:95], v[94:95], v[94:95]
	ds_bpermute_b32 v119, v75, v117
	v_pk_fma_f32 v[90:91], v[90:91], v[90:91], v[94:95]
	v_mov_b32_e32 v94, v22
	v_mov_b32_e32 v95, v6
	v_pk_fma_f32 v[90:91], v[94:95], v[94:95], v[90:91]
	v_mov_b32_e32 v94, v23
	v_mov_b32_e32 v95, v7
	v_pk_fma_f32 v[122:123], v[94:95], v[94:95], v[90:91]
	v_mov_b32_e32 v94, v49
	v_mov_b32_e32 v95, v33
	v_mov_b32_e32 v90, v48
	v_mov_b32_e32 v91, v32
	v_pk_mul_f32 v[94:95], v[94:95], v[94:95]
	ds_bpermute_b32 v118, v75, v116
	v_pk_fma_f32 v[90:91], v[90:91], v[90:91], v[94:95]
	v_mov_b32_e32 v94, v50
	v_mov_b32_e32 v95, v34
	v_pk_fma_f32 v[90:91], v[94:95], v[94:95], v[90:91]
	v_mov_b32_e32 v94, v51
	v_mov_b32_e32 v95, v35
	v_pk_fma_f32 v[124:125], v[94:95], v[94:95], v[90:91]
	v_lshl_add_u64 v[90:91], v[96:97], 0, s[0:1]
	v_lshl_add_u64 v[104:105], v[90:91], 0, v[192:193]
	v_mov_b32_e32 v94, v16
	v_mov_b32_e32 v95, v0
	v_pk_fma_f32 v[94:95], v[94:95], v[94:95], v[108:109]
	v_mov_b32_e32 v108, v18
	v_mov_b32_e32 v109, v2
	v_pk_fma_f32 v[126:127], v[108:109], v[108:109], v[94:95]
	v_lshl_add_u64 v[94:95], v[96:97], 0, v[192:193]
	v_pk_fma_f32 v[96:97], v[128:129], v[128:129], v[126:127]
	v_mov_b32_e32 v126, v124
	v_mov_b32_e32 v127, v120
	v_mov_b32_e32 v120, v125
	v_pk_add_f32 v[120:121], v[126:127], v[120:121]
	v_mov_b32_e32 v124, v96
	v_mov_b32_e32 v125, v122
	v_pk_add_f32 v[120:121], v[120:121], v[124:125]
	v_mov_b32_e32 v122, v97
	v_pk_add_f32 v[96:97], v[120:121], v[122:123]
	ds_bpermute_b32 v121, v65, v97
	ds_bpermute_b32 v120, v65, v96
	v_add_u32_e32 v100, 2, v80
	v_ashrrev_i32_e32 v101, 31, v100
	v_lshlrev_b64 v[122:123], 11, v[100:101]
	s_waitcnt lgkmcnt(2)
	v_pk_add_f32 v[100:101], v[116:117], v[118:119]
	s_waitcnt lgkmcnt(0)
	v_pk_add_f32 v[96:97], v[96:97], v[120:121]
	ds_bpermute_b32 v119, v71, v97
	ds_bpermute_b32 v118, v71, v96
	ds_bpermute_b32 v117, v89, v101
	ds_bpermute_b32 v116, v89, v100
	s_mov_b32 s0, 0x358637bd
	v_lshlrev_b64 v[98:99], 11, v[80:81]
	s_waitcnt lgkmcnt(2)
	v_pk_add_f32 v[96:97], v[96:97], v[118:119]
	ds_bpermute_b32 v119, v73, v97
	ds_bpermute_b32 v118, v73, v96
	s_waitcnt lgkmcnt(2)
	v_pk_add_f32 v[100:101], v[100:101], v[116:117]
	ds_bpermute_b32 v117, v93, v101
	ds_bpermute_b32 v116, v93, v100
	v_add_u32_e32 v120, 3, v80
	s_waitcnt lgkmcnt(2)
	v_pk_add_f32 v[96:97], v[96:97], v[118:119]
	ds_bpermute_b32 v119, v75, v97
	ds_bpermute_b32 v118, v75, v96
	s_waitcnt lgkmcnt(2)
	v_pk_add_f32 v[100:101], v[100:101], v[116:117]
	v_mov_b64_e32 v[116:117], s[0:1]
	v_pk_fma_f32 v[100:101], v[100:101], s[6:7], v[116:117] op_sel_hi:[1,0,0]
	v_lshl_add_u64 v[98:99], v[78:79], 0, v[98:99]
	s_waitcnt lgkmcnt(0)
	v_pk_add_f32 v[96:97], v[96:97], v[118:119]
	ds_bpermute_b32 v119, v89, v97
	ds_bpermute_b32 v118, v89, v96
	v_mul_f32_e32 v67, 0x4b800000, v101
	v_cmp_gt_f32_e32 vcc, s2, v101
	v_mul_f32_e32 v69, 0x4b800000, v100
	v_cmp_gt_f32_e64 s[0:1], s2, v100
	s_waitcnt lgkmcnt(0)
	v_pk_add_f32 v[96:97], v[96:97], v[118:119]
	ds_bpermute_b32 v119, v93, v97
	ds_bpermute_b32 v118, v93, v96
	v_cndmask_b32_e32 v67, v101, v67, vcc
	v_rsq_f32_e32 v67, v67
	v_cndmask_b32_e64 v69, v100, v69, s[0:1]
	v_rsq_f32_e32 v69, v69
	s_waitcnt lgkmcnt(0)
	v_pk_add_f32 v[96:97], v[96:97], v[118:119]
	v_mul_f32_e32 v81, 0x45800000, v67
	v_pk_fma_f32 v[96:97], v[96:97], s[6:7], v[116:117] op_sel_hi:[1,0,0]
	v_cndmask_b32_e32 v100, v67, v81, vcc
	v_mul_f32_e32 v81, 0x4b800000, v97
	v_cmp_gt_f32_e32 vcc, s2, v97
	v_mul_f32_e32 v83, 0x4b800000, v96
	v_cmp_gt_f32_e64 s[2:3], s2, v96
	v_cndmask_b32_e32 v81, v97, v81, vcc
	v_rsq_f32_e32 v81, v81
	v_cndmask_b32_e64 v83, v96, v83, s[2:3]
	v_rsq_f32_e32 v83, v83
	v_mul_f32_e32 v67, 0x45800000, v69
	v_cndmask_b32_e64 v96, v69, v67, s[0:1]
	v_mul_f32_e32 v67, 0x45800000, v81
	v_cndmask_b32_e32 v92, v81, v67, vcc
	v_mul_f32_e32 v67, 0x45800000, v83
	v_cndmask_b32_e64 v88, v83, v67, s[2:3]
	v_ashrrev_i32_e32 v121, 31, v120
	v_lshlrev_b64 v[120:121], 11, v[120:121]
	v_mov_b32_e32 v83, v193
	s_waitcnt vmcnt(11)
	v_mov_b32_e32 v104, v146
	v_mov_b32_e32 v105, v147
	v_mov_b32_e32 v106, v148
	v_mov_b32_e32 v107, v149
	v_mov_b32_e32 v117, v106
	v_mov_b32_e32 v106, v105
	v_mov_b32_e32 v116, v104
	v_pk_add_f32 v[104:105], v[106:107], 1.0 op_sel_hi:[1,0]
	v_mov_b32_e32 v107, v62
	v_mov_b32_e32 v62, v61
	v_mov_b32_e32 v106, v60
	s_waitcnt vmcnt(10)
	v_mov_b32_e32 v108, v150
	v_mov_b32_e32 v109, v151
	v_mov_b32_e32 v110, v152
	v_mov_b32_e32 v111, v153
	v_mov_b32_e32 v119, v110
	v_pk_mul_f32 v[60:61], v[62:63], v[100:101] op_sel_hi:[1,0]
	v_mov_b32_e32 v110, v109
	v_pk_mul_f32 v[106:107], v[106:107], v[100:101] op_sel_hi:[1,0]
	v_mov_b32_e32 v118, v108
	s_waitcnt vmcnt(9)
	v_mov_b32_e32 v112, v154
	v_mov_b32_e32 v113, v155
	v_mov_b32_e32 v114, v156
	v_mov_b32_e32 v115, v157
	v_mov_b32_e32 v125, v114
	v_pk_mul_f32 v[60:61], v[60:61], v[110:111]
	v_mov_b32_e32 v114, v113
	v_pk_add_f32 v[116:117], v[116:117], 1.0 op_sel_hi:[1,0]
	v_pk_mul_f32 v[106:107], v[106:107], v[118:119]
	v_mov_b32_e32 v124, v112
	v_pk_fma_f32 v[60:61], v[60:61], v[104:105], v[114:115]
	v_pk_fma_f32 v[106:107], v[106:107], v[116:117], v[124:125]
	v_cvt_pk_bf16_f32 v61, v107, v61
	v_cvt_pk_bf16_f32 v60, v106, v60
	v_mov_b32_e32 v62, v56
	v_mov_b32_e32 v63, v58
	v_pk_mul_f32 v[62:63], v[62:63], v[96:97] op_sel_hi:[1,0]
	v_mov_b32_e32 v58, v57
	v_pk_mul_f32 v[62:63], v[62:63], v[118:119]
	v_pk_mul_f32 v[56:57], v[58:59], v[96:97] op_sel_hi:[1,0]
	v_pk_fma_f32 v[62:63], v[62:63], v[116:117], v[124:125]
	v_pk_mul_f32 v[56:57], v[56:57], v[110:111]
	v_pk_fma_f32 v[56:57], v[56:57], v[104:105], v[114:115]
	v_cvt_pk_bf16_f32 v56, v62, v56
	v_cvt_pk_bf16_f32 v57, v63, v57
	v_mov_b32_e32 v58, v52
	v_mov_b32_e32 v59, v54
	v_pk_mul_f32 v[58:59], v[58:59], v[92:93] op_sel_hi:[1,0]
	v_mov_b32_e32 v54, v53
	v_pk_mul_f32 v[58:59], v[118:119], v[58:59]
	v_pk_mul_f32 v[52:53], v[54:55], v[92:93] op_sel_hi:[1,0]
	v_pk_fma_f32 v[58:59], v[58:59], v[116:117], v[124:125]
	v_pk_mul_f32 v[52:53], v[110:111], v[52:53]
	v_pk_fma_f32 v[52:53], v[52:53], v[104:105], v[114:115]
	v_cvt_pk_bf16_f32 v52, v58, v52
	v_cvt_pk_bf16_f32 v53, v59, v53
	v_mov_b32_e32 v54, v48
	v_mov_b32_e32 v55, v50
	v_pk_mul_f32 v[54:55], v[54:55], v[88:89] op_sel_hi:[1,0]
	v_mov_b32_e32 v50, v49
	v_pk_mul_f32 v[54:55], v[118:119], v[54:55]
	v_pk_mul_f32 v[48:49], v[50:51], v[88:89] op_sel_hi:[1,0]
	v_pk_fma_f32 v[54:55], v[116:117], v[54:55], v[124:125]
	v_pk_mul_f32 v[48:49], v[110:111], v[48:49]
	v_pk_fma_f32 v[48:49], v[104:105], v[48:49], v[114:115]
	v_cvt_pk_bf16_f32 v48, v54, v48
	v_cvt_pk_bf16_f32 v49, v55, v49
	global_store_dwordx2 v[98:99], v[60:61], off
	v_lshl_add_u64 v[60:61], v[78:79], 0, v[102:103]
	global_store_dwordx2 v[60:61], v[56:57], off
	v_lshl_add_u64 v[56:57], v[78:79], 0, v[122:123]
	global_store_dwordx2 v[56:57], v[52:53], off
	v_lshl_add_u64 v[52:53], v[78:79], 0, v[120:121]
	global_store_dwordx2 v[52:53], v[48:49], off
	v_lshl_add_u64 v[48:49], v[90:91], 0, v[82:83]
	s_nop 0
	v_readlane_b32 s0, v255, 7
	s_waitcnt vmcnt(12)
	v_mov_b32_e32 v48, v164
	v_mov_b32_e32 v49, v165
	v_mov_b32_e32 v50, v166
	v_mov_b32_e32 v51, v167
	v_mov_b32_e32 v55, v50
	v_mov_b32_e32 v50, v49
	v_mov_b32_e32 v54, v48
	v_pk_add_f32 v[48:49], v[50:51], 1.0 op_sel_hi:[1,0]
	v_mov_b32_e32 v50, v44
	v_mov_b32_e32 v51, v46
	v_pk_mul_f32 v[50:51], v[50:51], v[100:101] op_sel_hi:[1,0]
	s_waitcnt vmcnt(11)
	v_mov_b32_e32 v102, v172
	v_mov_b32_e32 v103, v173
	v_mov_b32_e32 v104, v174
	v_mov_b32_e32 v105, v175
	v_mov_b32_e32 v58, v102
	v_mov_b32_e32 v59, v104
	v_mov_b32_e32 v46, v45
	v_pk_add_f32 v[54:55], v[54:55], 1.0 op_sel_hi:[1,0]
	v_pk_mul_f32 v[50:51], v[50:51], v[58:59]
	s_waitcnt vmcnt(10)
	v_mov_b32_e32 v106, v180
	v_mov_b32_e32 v107, v181
	v_mov_b32_e32 v108, v182
	v_mov_b32_e32 v109, v183
	v_mov_b32_e32 v62, v106
	v_mov_b32_e32 v63, v108
	v_pk_mul_f32 v[44:45], v[46:47], v[100:101] op_sel_hi:[1,0]
	v_mov_b32_e32 v104, v103
	v_pk_fma_f32 v[50:51], v[50:51], v[54:55], v[62:63]
	v_pk_mul_f32 v[44:45], v[44:45], v[104:105]
	v_mov_b32_e32 v108, v107
	v_pk_fma_f32 v[44:45], v[44:45], v[48:49], v[108:109]
	v_cvt_pk_bf16_f32 v44, v50, v44
	v_cvt_pk_bf16_f32 v45, v51, v45
	global_store_dwordx2 v[98:99], v[44:45], off offset:512
	v_mov_b32_e32 v44, v40
	v_mov_b32_e32 v45, v42
	v_pk_mul_f32 v[44:45], v[44:45], v[96:97] op_sel_hi:[1,0]
	v_mov_b32_e32 v42, v41
	v_pk_mul_f32 v[44:45], v[44:45], v[58:59]
	v_pk_mul_f32 v[40:41], v[42:43], v[96:97] op_sel_hi:[1,0]
	v_pk_fma_f32 v[44:45], v[44:45], v[54:55], v[62:63]
	v_pk_mul_f32 v[40:41], v[40:41], v[104:105]
	v_pk_fma_f32 v[40:41], v[40:41], v[48:49], v[108:109]
	v_cvt_pk_bf16_f32 v40, v44, v40
	v_cvt_pk_bf16_f32 v41, v45, v41
	global_store_dwordx2 v[60:61], v[40:41], off offset:512
	v_mov_b32_e32 v40, v36
	v_mov_b32_e32 v41, v38
	v_pk_mul_f32 v[40:41], v[40:41], v[92:93] op_sel_hi:[1,0]
	v_mov_b32_e32 v38, v37
	v_pk_mul_f32 v[40:41], v[40:41], v[58:59]
	v_pk_mul_f32 v[36:37], v[38:39], v[92:93] op_sel_hi:[1,0]
	v_pk_fma_f32 v[40:41], v[40:41], v[54:55], v[62:63]
	v_pk_mul_f32 v[36:37], v[36:37], v[104:105]
	v_pk_fma_f32 v[36:37], v[36:37], v[48:49], v[108:109]
	v_cvt_pk_bf16_f32 v36, v40, v36
	v_cvt_pk_bf16_f32 v37, v41, v37
	global_store_dwordx2 v[56:57], v[36:37], off offset:512
	v_mov_b32_e32 v36, v32
	v_mov_b32_e32 v37, v34
	v_pk_mul_f32 v[36:37], v[36:37], v[88:89] op_sel_hi:[1,0]
	v_mov_b32_e32 v34, v33
	v_pk_mul_f32 v[36:37], v[36:37], v[58:59]
	v_pk_mul_f32 v[32:33], v[34:35], v[88:89] op_sel_hi:[1,0]
	v_pk_fma_f32 v[36:37], v[36:37], v[54:55], v[62:63]
	v_pk_mul_f32 v[32:33], v[32:33], v[104:105]
	v_pk_fma_f32 v[32:33], v[32:33], v[48:49], v[108:109]
	v_cvt_pk_bf16_f32 v32, v36, v32
	v_cvt_pk_bf16_f32 v33, v37, v33
	global_store_dwordx2 v[52:53], v[32:33], off offset:512
	v_lshl_add_u64 v[32:33], v[90:91], 0, v[84:85]
	s_nop 0
	v_add_u32_e32 v80, s0, v80
	s_waitcnt vmcnt(13)
	v_mov_b32_e32 v32, v184
	v_mov_b32_e32 v33, v185
	v_mov_b32_e32 v34, v186
	v_mov_b32_e32 v35, v187
	v_mov_b32_e32 v45, v34
	v_mov_b32_e32 v34, v33
	v_mov_b32_e32 v44, v32
	v_pk_add_f32 v[32:33], v[34:35], 1.0 op_sel_hi:[1,0]
	v_mov_b32_e32 v34, v28
	v_mov_b32_e32 v35, v30
	v_pk_mul_f32 v[34:35], v[34:35], v[100:101] op_sel_hi:[1,0]
	s_waitcnt vmcnt(12)
	v_mov_b32_e32 v36, v188
	v_mov_b32_e32 v37, v189
	v_mov_b32_e32 v38, v190
	v_mov_b32_e32 v39, v191
	v_mov_b32_e32 v46, v36
	v_mov_b32_e32 v47, v38
	v_mov_b32_e32 v30, v29
	v_pk_add_f32 v[44:45], v[44:45], 1.0 op_sel_hi:[1,0]
	v_pk_mul_f32 v[34:35], v[34:35], v[46:47]
	s_waitcnt vmcnt(11)
	v_mov_b32_e32 v40, v232
	v_mov_b32_e32 v41, v233
	v_mov_b32_e32 v42, v234
	v_mov_b32_e32 v43, v235
	v_mov_b32_e32 v48, v40
	v_mov_b32_e32 v49, v42
	v_pk_mul_f32 v[28:29], v[30:31], v[100:101] op_sel_hi:[1,0]
	v_mov_b32_e32 v38, v37
	v_pk_fma_f32 v[34:35], v[34:35], v[44:45], v[48:49]
	v_pk_mul_f32 v[28:29], v[28:29], v[38:39]
	v_mov_b32_e32 v42, v41
	v_pk_fma_f32 v[28:29], v[28:29], v[32:33], v[42:43]
	v_cvt_pk_bf16_f32 v28, v34, v28
	v_cvt_pk_bf16_f32 v29, v35, v29
	global_store_dwordx2 v[98:99], v[28:29], off offset:1024
	v_mov_b32_e32 v28, v24
	v_mov_b32_e32 v29, v26
	v_pk_mul_f32 v[28:29], v[28:29], v[96:97] op_sel_hi:[1,0]
	v_mov_b32_e32 v26, v25
	v_pk_mul_f32 v[28:29], v[28:29], v[46:47]
	v_pk_mul_f32 v[24:25], v[26:27], v[96:97] op_sel_hi:[1,0]
	v_pk_fma_f32 v[28:29], v[28:29], v[44:45], v[48:49]
	v_pk_mul_f32 v[24:25], v[24:25], v[38:39]
	v_pk_fma_f32 v[24:25], v[24:25], v[32:33], v[42:43]
	v_cvt_pk_bf16_f32 v24, v28, v24
	v_cvt_pk_bf16_f32 v25, v29, v25
	global_store_dwordx2 v[60:61], v[24:25], off offset:1024
	v_mov_b32_e32 v24, v20
	v_mov_b32_e32 v25, v22
	v_pk_mul_f32 v[24:25], v[24:25], v[92:93] op_sel_hi:[1,0]
	v_mov_b32_e32 v22, v21
	v_pk_mul_f32 v[24:25], v[24:25], v[46:47]
	v_pk_mul_f32 v[20:21], v[22:23], v[92:93] op_sel_hi:[1,0]
	v_pk_fma_f32 v[24:25], v[24:25], v[44:45], v[48:49]
	v_pk_mul_f32 v[20:21], v[20:21], v[38:39]
	v_pk_fma_f32 v[20:21], v[20:21], v[32:33], v[42:43]
	v_cvt_pk_bf16_f32 v20, v24, v20
	v_cvt_pk_bf16_f32 v21, v25, v21
	global_store_dwordx2 v[56:57], v[20:21], off offset:1024
	v_mov_b32_e32 v20, v16
	v_mov_b32_e32 v21, v18
	v_pk_mul_f32 v[20:21], v[20:21], v[88:89] op_sel_hi:[1,0]
	v_mov_b32_e32 v18, v17
	v_pk_mul_f32 v[20:21], v[20:21], v[46:47]
	v_pk_mul_f32 v[16:17], v[18:19], v[88:89] op_sel_hi:[1,0]
	v_pk_fma_f32 v[20:21], v[20:21], v[44:45], v[48:49]
	v_pk_mul_f32 v[16:17], v[16:17], v[38:39]
	v_pk_fma_f32 v[16:17], v[16:17], v[32:33], v[42:43]
	v_cvt_pk_bf16_f32 v16, v20, v16
	v_cvt_pk_bf16_f32 v17, v21, v17
	global_store_dwordx2 v[52:53], v[16:17], off offset:1024
	v_lshl_add_u64 v[16:17], v[90:91], 0, v[86:87]
	s_nop 0
	s_waitcnt vmcnt(14)
	v_mov_b32_e32 v16, v236
	v_mov_b32_e32 v17, v237
	v_mov_b32_e32 v18, v238
	v_mov_b32_e32 v19, v239
	v_mov_b32_e32 v29, v18
	v_mov_b32_e32 v18, v17
	v_mov_b32_e32 v28, v16
	v_pk_add_f32 v[16:17], v[18:19], 1.0 op_sel_hi:[1,0]
	v_mov_b32_e32 v18, v12
	v_mov_b32_e32 v19, v14
	v_pk_mul_f32 v[18:19], v[18:19], v[100:101] op_sel_hi:[1,0]
	s_waitcnt vmcnt(13)
	v_mov_b32_e32 v20, v240
	v_mov_b32_e32 v21, v241
	v_mov_b32_e32 v22, v242
	v_mov_b32_e32 v23, v243
	v_mov_b32_e32 v30, v20
	v_mov_b32_e32 v31, v22
	v_mov_b32_e32 v14, v13
	v_pk_add_f32 v[28:29], v[28:29], 1.0 op_sel_hi:[1,0]
	v_pk_mul_f32 v[18:19], v[18:19], v[30:31]
	s_waitcnt vmcnt(12)
	v_mov_b32_e32 v24, v248
	v_mov_b32_e32 v25, v249
	v_mov_b32_e32 v26, v250
	v_mov_b32_e32 v27, v251
	v_mov_b32_e32 v32, v24
	v_mov_b32_e32 v33, v26
	v_pk_mul_f32 v[12:13], v[14:15], v[100:101] op_sel_hi:[1,0]
	v_mov_b32_e32 v22, v21
	v_pk_fma_f32 v[18:19], v[18:19], v[28:29], v[32:33]
	v_pk_mul_f32 v[12:13], v[12:13], v[22:23]
	v_mov_b32_e32 v26, v25
	v_pk_fma_f32 v[12:13], v[12:13], v[16:17], v[26:27]
	v_cvt_pk_bf16_f32 v12, v18, v12
	v_cvt_pk_bf16_f32 v13, v19, v13
	global_store_dwordx2 v[98:99], v[12:13], off offset:1536
	v_mov_b32_e32 v12, v8
	v_mov_b32_e32 v13, v10
	v_pk_mul_f32 v[12:13], v[12:13], v[96:97] op_sel_hi:[1,0]
	v_mov_b32_e32 v10, v9
	v_pk_mul_f32 v[12:13], v[12:13], v[30:31]
	v_pk_mul_f32 v[8:9], v[10:11], v[96:97] op_sel_hi:[1,0]
	v_pk_fma_f32 v[12:13], v[12:13], v[28:29], v[32:33]
	v_pk_mul_f32 v[8:9], v[8:9], v[22:23]
	v_pk_fma_f32 v[8:9], v[8:9], v[16:17], v[26:27]
	v_cvt_pk_bf16_f32 v8, v12, v8
	v_cvt_pk_bf16_f32 v9, v13, v9
	global_store_dwordx2 v[60:61], v[8:9], off offset:1536
	v_mov_b32_e32 v8, v4
	v_mov_b32_e32 v9, v6
	v_pk_mul_f32 v[8:9], v[8:9], v[92:93] op_sel_hi:[1,0]
	v_mov_b32_e32 v6, v5
	v_pk_mul_f32 v[8:9], v[8:9], v[30:31]
	v_pk_mul_f32 v[4:5], v[6:7], v[92:93] op_sel_hi:[1,0]
	v_pk_fma_f32 v[8:9], v[8:9], v[28:29], v[32:33]
	v_pk_mul_f32 v[4:5], v[4:5], v[22:23]
	v_pk_fma_f32 v[4:5], v[4:5], v[16:17], v[26:27]
	v_cvt_pk_bf16_f32 v4, v8, v4
	v_cvt_pk_bf16_f32 v5, v9, v5
	global_store_dwordx2 v[56:57], v[4:5], off offset:1536
	v_mov_b32_e32 v4, v0
	v_mov_b32_e32 v5, v2
	v_pk_mul_f32 v[4:5], v[4:5], v[88:89] op_sel_hi:[1,0]
	v_mov_b32_e32 v2, v1
	v_pk_mul_f32 v[4:5], v[4:5], v[30:31]
	v_pk_mul_f32 v[0:1], v[2:3], v[88:89] op_sel_hi:[1,0]
	v_pk_fma_f32 v[4:5], v[4:5], v[28:29], v[32:33]
	v_pk_mul_f32 v[0:1], v[0:1], v[22:23]
	v_pk_fma_f32 v[0:1], v[0:1], v[16:17], v[26:27]
	v_cvt_pk_bf16_f32 v0, v4, v0
	v_cvt_pk_bf16_f32 v1, v5, v1
	global_store_dwordx2 v[52:53], v[0:1], off offset:1536
	s_cbranch_scc1 .LBB0_1028

.LBB0_1030:
	s_or_b64 exec, exec, s[4:5]
	v_lshl_add_u64 v[0:1], v[0:1], 0, v[192:193]
	global_load_dwordx4 v[36:39], v[0:1], off nt
	global_load_dwordx4 v[8:11], v[0:1], off offset:1024 nt
	global_load_dwordx4 v[4:7], v[0:1], off offset:2048 nt
	s_nop 0
	global_load_dwordx4 v[0:3], v[0:1], off offset:3072 nt
	s_nop 0
	global_load_dwordx4 v[40:43], v[14:15], off
	v_min_i32_e32 v13, 0x4000, v28
	v_ashrrev_i32_e32 v13, 13, v13
	v_mul_hi_i32_i24_e32 v25, 0x6000, v13
	v_mul_i32_i24_e32 v24, 0x6000, v13
	v_lshl_add_u64 v[26:27], s[96:97], 0, v[24:25]
	s_mov_b64 s[4:5], 0x1000
	v_lshl_add_u64 v[24:25], v[26:27], 0, v[192:193]
	v_lshl_add_u64 v[26:27], v[26:27], 0, s[4:5]
	v_lshl_add_u64 v[48:49], v[26:27], 0, v[192:193]
	global_load_dwordx4 v[44:47], v[24:25], off
	s_mov_b32 s4, 0x800000
	global_load_dwordx4 v[48:51], v[48:49], off
	v_lshlrev_b64 v[28:29], 11, v[28:29]
	v_lshl_add_u64 v[28:29], v[16:17], 0, v[28:29]
	s_waitcnt vmcnt(6)
	v_mov_b32_e32 v54, v37
	s_waitcnt vmcnt(5)
	v_mov_b32_e32 v55, v9
	v_mov_b32_e32 v52, v36
	v_mov_b32_e32 v53, v8
	s_waitcnt vmcnt(4)
	v_mov_b32_e32 v62, v5
	s_waitcnt vmcnt(3)
	v_mov_b32_e32 v63, v1
	v_pk_mul_f32 v[54:55], v[54:55], v[54:55]
	v_mov_b32_e32 v56, v38
	v_mov_b32_e32 v57, v10
	v_mov_b32_e32 v60, v4
	v_mov_b32_e32 v61, v0
	v_pk_mul_f32 v[62:63], v[62:63], v[62:63]
	v_pk_fma_f32 v[52:53], v[52:53], v[52:53], v[54:55]
	v_mov_b32_e32 v58, v39
	v_mov_b32_e32 v59, v11
	v_mov_b32_e32 v64, v6
	v_mov_b32_e32 v65, v2
	v_pk_fma_f32 v[54:55], v[60:61], v[60:61], v[62:63]
	v_pk_fma_f32 v[52:53], v[56:57], v[56:57], v[52:53]
	v_mov_b32_e32 v66, v7
	v_mov_b32_e32 v67, v3
	v_pk_fma_f32 v[54:55], v[64:65], v[64:65], v[54:55]
	v_pk_fma_f32 v[52:53], v[58:59], v[58:59], v[52:53]
	v_pk_fma_f32 v[54:55], v[66:67], v[66:67], v[54:55]
	v_add_f32_e32 v13, v52, v53
	v_add_f32_e32 v13, v13, v54
	v_add_f32_e32 v13, v13, v55
	ds_bpermute_b32 v19, v30, v13
	s_waitcnt vmcnt(2)
	v_mov_b32_e32 v53, v42
	v_mov_b32_e32 v42, v41
	v_mov_b32_e32 v41, v38
	v_mov_b32_e32 v38, v37
	s_waitcnt lgkmcnt(0)
	v_add_f32_e32 v13, v13, v19
	ds_bpermute_b32 v19, v31, v13
	s_waitcnt vmcnt(1)
	v_mov_b32_e32 v37, v46
	v_mov_b32_e32 v46, v45
	s_waitcnt vmcnt(0)
	v_mov_b32_e32 v45, v50
	v_mov_b32_e32 v50, v49
	s_waitcnt lgkmcnt(0)
	v_add_f32_e32 v13, v13, v19
	ds_bpermute_b32 v21, v32, v13
	v_mov_b32_e32 v52, v40
	v_mov_b32_e32 v40, v36
	v_mov_b32_e32 v36, v44
	v_mov_b32_e32 v44, v48
	s_waitcnt lgkmcnt(0)
	v_add_f32_e32 v13, v13, v21
	ds_bpermute_b32 v21, v33, v13
	v_pk_add_f32 v[48:49], v[50:51], 1.0 op_sel_hi:[1,0]
	v_pk_add_f32 v[44:45], v[44:45], 1.0 op_sel_hi:[1,0]
	v_mov_b32_e32 v19, v193
	s_waitcnt lgkmcnt(0)
	v_add_f32_e32 v13, v13, v21
	ds_bpermute_b32 v21, v34, v13
	s_waitcnt lgkmcnt(0)
	v_add_f32_e32 v13, v13, v21
	ds_bpermute_b32 v21, v35, v13
	s_waitcnt lgkmcnt(0)
	v_add_f32_e32 v13, v13, v21
	v_fmamk_f32 v13, v13, 0x3a800000, v219
	v_mul_f32_e32 v21, 0x4b800000, v13
	v_cmp_gt_f32_e32 vcc, s4, v13
	v_readlane_b32 s4, v255, 11
	v_readlane_b32 s5, v255, 12
	v_cndmask_b32_e32 v13, v13, v21, vcc
	v_rsq_f32_e32 v13, v13
	v_add_u32_e32 v12, s4, v12
	s_movk_i32 s4, 0x1ff
	v_mul_f32_e32 v21, 0x45800000, v13
	v_cndmask_b32_e32 v50, v13, v21, vcc
	v_pk_mul_f32 v[40:41], v[40:41], v[50:51] op_sel_hi:[1,0]
	v_pk_mul_f32 v[38:39], v[38:39], v[50:51] op_sel_hi:[1,0]
	v_pk_mul_f32 v[40:41], v[52:53], v[40:41]
	v_pk_mul_f32 v[38:39], v[42:43], v[38:39]
	v_pk_fma_f32 v[36:37], v[44:45], v[40:41], v[36:37]
	v_pk_fma_f32 v[38:39], v[48:49], v[38:39], v[46:47]
	v_cvt_pk_bf16_f32 v36, v36, v38
	v_cvt_pk_bf16_f32 v37, v37, v39
	global_store_dwordx2 v[28:29], v[36:37], off
	global_load_dwordx4 v[36:39], v[14:15], off offset:1024
	v_lshl_add_u64 v[40:41], v[26:27], 0, v[18:19]
	global_load_dwordx4 v[40:43], v[40:41], off
	s_nop 0
	global_load_dwordx4 v[44:47], v[24:25], off offset:1024
	v_mov_b32_e32 v48, v8
	v_mov_b32_e32 v49, v10
	v_mov_b32_e32 v10, v9
	v_pk_mul_f32 v[8:9], v[48:49], v[50:51] op_sel_hi:[1,0]
	v_pk_mul_f32 v[10:11], v[10:11], v[50:51] op_sel_hi:[1,0]
	v_mov_b32_e32 v21, v193
	v_cmp_lt_i32_e32 vcc, s4, v12
	s_or_b64 s[2:3], vcc, s[2:3]
	s_waitcnt vmcnt(2)
	v_mov_b32_e32 v49, v38
	s_waitcnt vmcnt(1)
	v_mov_b32_e32 v53, v42
	v_mov_b32_e32 v38, v37
	v_mov_b32_e32 v42, v41
	v_mov_b32_e32 v48, v36
	v_mov_b32_e32 v52, v40
	s_waitcnt vmcnt(0)
	v_mov_b32_e32 v55, v46
	v_mov_b32_e32 v46, v45
	v_pk_mul_f32 v[10:11], v[10:11], v[38:39]
	v_pk_add_f32 v[38:39], v[42:43], 1.0 op_sel_hi:[1,0]
	v_mov_b32_e32 v54, v44
	v_pk_mul_f32 v[8:9], v[8:9], v[48:49]
	v_pk_add_f32 v[36:37], v[52:53], 1.0 op_sel_hi:[1,0]
	v_pk_fma_f32 v[10:11], v[10:11], v[38:39], v[46:47]
	v_pk_fma_f32 v[8:9], v[8:9], v[36:37], v[54:55]
	v_cvt_pk_bf16_f32 v9, v9, v11
	v_cvt_pk_bf16_f32 v8, v8, v10
	global_store_dwordx2 v[28:29], v[8:9], off offset:512
	global_load_dwordx4 v[8:11], v[14:15], off offset:2048
	v_lshl_add_u64 v[36:37], v[26:27], 0, v[20:21]
	global_load_dwordx4 v[36:39], v[36:37], off
	s_nop 0
	global_load_dwordx4 v[40:43], v[24:25], off offset:2048
	v_mov_b32_e32 v44, v4
	v_mov_b32_e32 v45, v6
	v_mov_b32_e32 v6, v5
	v_pk_mul_f32 v[4:5], v[44:45], v[50:51] op_sel_hi:[1,0]
	v_pk_mul_f32 v[6:7], v[6:7], v[50:51] op_sel_hi:[1,0]
	v_mov_b32_e32 v23, v193
	s_waitcnt vmcnt(2)
	v_mov_b32_e32 v45, v10
	s_waitcnt vmcnt(1)
	v_mov_b32_e32 v47, v38
	v_mov_b32_e32 v10, v9
	v_mov_b32_e32 v38, v37
	v_mov_b32_e32 v44, v8
	v_mov_b32_e32 v46, v36
	s_waitcnt vmcnt(0)
	v_mov_b32_e32 v49, v42
	v_mov_b32_e32 v42, v41
	v_pk_mul_f32 v[6:7], v[6:7], v[10:11]
	v_pk_add_f32 v[10:11], v[38:39], 1.0 op_sel_hi:[1,0]
	v_mov_b32_e32 v48, v40
	v_pk_mul_f32 v[4:5], v[4:5], v[44:45]
	v_pk_add_f32 v[8:9], v[46:47], 1.0 op_sel_hi:[1,0]
	v_pk_fma_f32 v[6:7], v[6:7], v[10:11], v[42:43]
	v_pk_fma_f32 v[4:5], v[4:5], v[8:9], v[48:49]
	v_cvt_pk_bf16_f32 v5, v5, v7
	v_cvt_pk_bf16_f32 v4, v4, v6
	global_store_dwordx2 v[28:29], v[4:5], off offset:1024
	global_load_dwordx4 v[4:7], v[14:15], off offset:3072
	v_lshl_add_u64 v[8:9], v[26:27], 0, v[22:23]
	global_load_dwordx4 v[8:11], v[8:9], off
	s_nop 0
	global_load_dwordx4 v[24:27], v[24:25], off offset:3072
	v_mov_b32_e32 v36, v0
	v_mov_b32_e32 v37, v2
	v_mov_b32_e32 v2, v1
	v_pk_mul_f32 v[0:1], v[36:37], v[50:51] op_sel_hi:[1,0]
	v_pk_mul_f32 v[2:3], v[2:3], v[50:51] op_sel_hi:[1,0]
	s_waitcnt vmcnt(2)
	v_mov_b32_e32 v37, v6
	s_waitcnt vmcnt(1)
	v_mov_b32_e32 v39, v10
	v_mov_b32_e32 v6, v5
	v_mov_b32_e32 v10, v9
	v_mov_b32_e32 v36, v4
	v_mov_b32_e32 v38, v8
	s_waitcnt vmcnt(0)
	v_mov_b32_e32 v41, v26
	v_mov_b32_e32 v26, v25
	v_pk_mul_f32 v[2:3], v[2:3], v[6:7]
	v_pk_add_f32 v[6:7], v[10:11], 1.0 op_sel_hi:[1,0]
	v_mov_b32_e32 v40, v24
	v_pk_mul_f32 v[0:1], v[0:1], v[36:37]
	v_pk_add_f32 v[4:5], v[38:39], 1.0 op_sel_hi:[1,0]
	v_pk_fma_f32 v[2:3], v[2:3], v[6:7], v[26:27]
	v_pk_fma_f32 v[0:1], v[0:1], v[4:5], v[40:41]
	v_cvt_pk_bf16_f32 v1, v1, v3
	v_cvt_pk_bf16_f32 v0, v0, v2
	global_store_dwordx2 v[28:29], v[0:1], off offset:1536
	s_andn2_b64 exec, exec, s[2:3]
	s_cbranch_execz .LBB0_1035
